# hand-written in-projection epilogue (section dispatch once per unit), SGPR-based LDS-DMA addressing in the G1 K-loop, no s_setprio flips in the GEMM K-loops
# speedup vs baseline: 1.0114x; 1.0070x over previous
; #define PG8_STAGE(bufoff, gbase, voff) do { _Pragma("unroll") for (int _i = 0; _i < 2; ++_i) \
;         __builtin_amdgcn_global_load_lds((const unsigned*)((const char*)(gbase) + (voff)[_i]), (LAS unsigned*)(lds + (bufoff) + ldsw + _i * 8192), 16, 0, 0); } while (0)
; #define PG8_WAIT_V(n) asm volatile("s_waitcnt vmcnt(" #n ")" ::: "memory")
; #define PG8_WAIT_L(n) asm volatile("s_waitcnt lgkmcnt(" #n ")" ::: "memory")
; #define PG8_BAR __builtin_amdgcn_s_barrier()
; template <class Epi>
; __device__ __forceinline__ void gemm_phase(LAS unsigned char* lds, const Gemm g, const StaticOrder& S, const Epi& E, unsigned long long& sw_acc) {
;     ...
; #pragma unroll
;     for (int a = 0; a < 2; ++a)
; #pragma unroll
;         for (int b = 0; b < 2; ++b)
; #pragma unroll
;             for (int m = 0; m < 4; ++m)
; #pragma unroll
;                 for (int n = 0; n < 2; ++n) acc[a][b][m][n] = (f32x4){0.f, 0.f, 0.f, 0.f};
;     ...
;     PG8_STAGE(PG8_SB(0, 0), cB, voffB); PG8_STAGE(PG8_SB(0, 1), cB + hstepB, voffB); PG8_STAGE(PG8_SA(0, 0), cA, voffA); PG8_STAGE(PG8_SA(0, 1), cA + hstep, voffA);
;     typename Epi::Pre pre; E.pre_load(pre, S);
;     if (wr == 1) PG8_BAR;
;     PG8_WAIT_V(2); PG8_BAR;
;     E.pre_finish(pre);
;     PG8_WAIT_L(0);
;     PG8_STAGE(PG8_SB(1, 0), cB + kstep, voffB); PG8_STAGE(PG8_SA(1, 0), cA + kstepA, voffA); PG8_STAGE(PG8_SB(1, 1), cB + hstepB + kstep, voffB);
;     PG8_WAIT_V(6); PG8_BAR;
.LBB0_118:
	s_or_b64 exec, exec, s[6:7]
	s_and_saveexec_b64 s[6:7], s[18:19]
	v_add_u32_e32 v12, 0, v12
	v_add_u32_e32 v12, 0x20000, v12
	ds_write_b32 v12, v13
	s_or_b64 exec, exec, s[6:7]
	v_and_b32_e32 v13, 15, v2
	v_bfe_u32 v2, v2, 4, 2
	v_lshlrev_b32_e32 v12, 3, v2
	v_lshlrev_b32_e32 v2, 4, v2
	v_lshl_or_b32 v187, s10, 6, v13
	v_lshl_or_b32 v14, v13, 6, v2
	v_lshlrev_b32_e32 v13, 2, v13
	s_and_b32 s1, s1, 3
	s_lshl_b32 s6, s10, 13
	v_and_b32_e32 v15, 32, v13
	s_waitcnt lgkmcnt(0)
	s_add_i32 m0, s31, 0x18000
	v_lshl_add_u64 v[8:9], v[8:9], 0, s[16:17]
	v_bitop3_b32 v16, v14, s6, v15 bitop3:0xde
	s_lshl_b32 s6, s1, 12
	global_load_lds_dwordx4 v[8:9], off
	v_lshl_add_u64 v[8:9], v[10:11], 0, s[16:17]
	s_add_i32 m0, s31, 0x1a000
	s_add_i32 s36, s31, 0x8000
	s_add_i32 s37, s31, 0xa000
	v_bitop3_b32 v218, v14, s6, v15 bitop3:0xde
	v_add_u32_e32 v254, 0x10000, v218
	v_add_u32_e32 v255, 0x18000, v218
	global_load_lds_dwordx4 v[8:9], off
	v_lshl_add_u64 v[6:7], v[6:7], 0, s[16:17]
	s_mov_b32 m0, s36
	s_add_u32 s6, s4, 0x10080
	global_load_lds_dwordx4 v[6:7], off
	v_lshl_add_u64 v[4:5], v[4:5], 0, s[16:17]
	s_mov_b32 m0, s37
	s_addc_u32 s7, s5, 0
	global_load_lds_dwordx4 v[4:5], off
	s_add_i32 m0, s31, 0x1c000
	v_lshl_add_u64 v[4:5], s[6:7], 0, v[196:197]
	global_load_lds_dwordx4 v[4:5], off
	v_lshl_add_u64 v[4:5], s[6:7], 0, v[192:193]
	s_add_i32 m0, s31, 0x1e000
	v_readlane_b32 s6, v250, 4
	global_load_lds_dwordx4 v[4:5], off
	v_readlane_b32 s7, v250, 5
	v_and_b32_e32 v4, 1, v24
	s_cmpk_lt_u32 s0, 0x100
	v_lshl_add_u64 v[200:201], s[6:7], 0, v[2:3]
	v_lshlrev_b32_e32 v2, 14, v24
	v_and_b32_e32 v2, 0xffff8000, v2
	v_lshl_add_u32 v2, v23, 11, v2
	v_lshl_or_b32 v2, v4, 6, v2
	s_cselect_b64 s[54:55], -1, 0
	s_lshl_b32 s0, s10, 8
	v_lshl_add_u32 v202, v25, 1, v2
	v_lshlrev_b32_e32 v2, 14, v20
	s_add_i32 s0, s0, 0
	v_and_b32_e32 v2, 0xffff8000, v2
	s_waitcnt vmcnt(6)
	s_add_i32 s0, s0, 0x20000
	v_lshl_add_u32 v2, v21, 11, v2
	v_and_b32_e32 v4, 1, v20
	v_add_u32_e32 v219, s0, v13
	v_lshl_or_b32 v220, s1, 6, v12
	v_lshl_or_b32 v2, v4, 6, v2
	v_mov_b32_e32 v4, 0
	v_readlane_b32 s0, v251, 27
	v_mov_b32_e32 v203, v3
	v_lshl_add_u32 v204, v22, 1, v2
	v_mov_b32_e32 v205, v3
	s_mov_b32 s70, 0
	v_add_u32_e32 v221, 0, v16
	v_lshlrev_b32_e32 v222, 2, v12
	s_mov_b32 s68, s0
	v_readlane_b32 s69, v251, 25
	v_mov_b32_e32 v5, v4
	v_mov_b32_e32 v6, v4
	v_mov_b32_e32 v7, v4
	v_mov_b32_e32 v8, v4
	v_mov_b32_e32 v9, v4
	v_mov_b32_e32 v10, v4
	v_mov_b32_e32 v11, v4
	v_mov_b32_e32 v12, v4
	v_mov_b32_e32 v13, v4
	v_mov_b32_e32 v14, v4
	v_mov_b32_e32 v15, v4
	v_mov_b32_e32 v16, v4
	v_mov_b32_e32 v17, v4
	v_mov_b32_e32 v18, v4
	v_mov_b32_e32 v19, v4
	v_mov_b32_e32 v20, v4
	v_mov_b32_e32 v21, v4
	v_mov_b32_e32 v22, v4
	v_mov_b32_e32 v23, v4
	v_mov_b32_e32 v24, v4
	v_mov_b32_e32 v25, v4
	v_mov_b32_e32 v26, v4
	v_mov_b32_e32 v27, v4
	v_mov_b32_e32 v28, v4
	v_mov_b32_e32 v29, v4
	v_mov_b32_e32 v30, v4
	v_mov_b32_e32 v31, v4
	v_mov_b32_e32 v32, v4
	v_mov_b32_e32 v33, v4
	v_mov_b32_e32 v34, v4
	v_mov_b32_e32 v35, v4
	v_mov_b32_e32 v36, v4
	v_mov_b32_e32 v37, v4
	v_mov_b32_e32 v38, v4
	v_mov_b32_e32 v39, v4
	v_mov_b32_e32 v40, v4
	v_mov_b32_e32 v41, v4
	v_mov_b32_e32 v42, v4
	v_mov_b32_e32 v43, v4
	v_mov_b32_e32 v44, v4
	v_mov_b32_e32 v45, v4
	v_mov_b32_e32 v46, v4
	v_mov_b32_e32 v47, v4
	v_mov_b32_e32 v48, v4
	v_mov_b32_e32 v49, v4
	v_mov_b32_e32 v50, v4
	v_mov_b32_e32 v51, v4
	v_mov_b32_e32 v52, v4
	v_mov_b32_e32 v53, v4
	v_mov_b32_e32 v54, v4
	v_mov_b32_e32 v55, v4
	v_mov_b32_e32 v56, v4
	v_mov_b32_e32 v57, v4
	v_mov_b32_e32 v58, v4
	v_mov_b32_e32 v59, v4
	v_mov_b32_e32 v60, v4
	v_mov_b32_e32 v61, v4
	v_mov_b32_e32 v62, v4
	v_mov_b32_e32 v63, v4
	v_mov_b32_e32 v64, v4
	v_mov_b32_e32 v65, v4
	v_mov_b32_e32 v66, v4
	v_mov_b32_e32 v67, v4
	v_mov_b32_e32 v68, v4
	v_mov_b32_e32 v69, v4
	v_mov_b32_e32 v70, v4
	v_mov_b32_e32 v71, v4
	v_mov_b32_e32 v72, v4
	v_mov_b32_e32 v73, v4
	v_mov_b32_e32 v74, v4
	v_mov_b32_e32 v75, v4
	v_mov_b32_e32 v76, v4
	v_mov_b32_e32 v77, v4
	v_mov_b32_e32 v78, v4
	v_mov_b32_e32 v79, v4
	v_mov_b32_e32 v80, v4
	v_mov_b32_e32 v81, v4
	v_mov_b32_e32 v82, v4
	v_mov_b32_e32 v83, v4
	v_mov_b32_e32 v84, v4
	v_mov_b32_e32 v85, v4
	v_mov_b32_e32 v86, v4
	v_mov_b32_e32 v87, v4
	v_mov_b32_e32 v88, v4
	v_mov_b32_e32 v89, v4
	v_mov_b32_e32 v90, v4
	v_mov_b32_e32 v91, v4
	v_mov_b32_e32 v92, v4
	v_mov_b32_e32 v93, v4
	v_mov_b32_e32 v94, v4
	v_mov_b32_e32 v95, v4
	v_mov_b32_e32 v96, v4
	v_mov_b32_e32 v97, v4
	v_mov_b32_e32 v98, v4
	v_mov_b32_e32 v99, v4
	v_mov_b32_e32 v100, v4
	v_mov_b32_e32 v101, v4
	v_mov_b32_e32 v102, v4
	v_mov_b32_e32 v103, v4
	v_mov_b32_e32 v104, v4
	v_mov_b32_e32 v105, v4
	v_mov_b32_e32 v106, v4
	v_mov_b32_e32 v107, v4
	v_mov_b32_e32 v108, v4
	v_mov_b32_e32 v109, v4
	v_mov_b32_e32 v110, v4
	v_mov_b32_e32 v111, v4
	v_mov_b32_e32 v112, v4
	v_mov_b32_e32 v113, v4
	v_mov_b32_e32 v114, v4
	v_mov_b32_e32 v115, v4
	v_mov_b32_e32 v116, v4
	v_mov_b32_e32 v117, v4
	v_mov_b32_e32 v118, v4
	v_mov_b32_e32 v119, v4
	v_mov_b32_e32 v120, v4
	v_mov_b32_e32 v121, v4
	v_mov_b32_e32 v122, v4
	v_mov_b32_e32 v123, v4
	v_mov_b32_e32 v124, v4
	v_mov_b32_e32 v125, v4
	v_mov_b32_e32 v126, v4
	v_mov_b32_e32 v127, v4
	v_mov_b32_e32 v128, v4
	v_mov_b32_e32 v129, v4
	v_mov_b32_e32 v130, v4
	v_mov_b32_e32 v131, v4
	s_barrier
	v_readlane_b32 s1, v251, 28
	s_branch .LBB0_122

; #define PG8_STAGE(bufoff, gbase, voff) do { _Pragma("unroll") for (int _i = 0; _i < 2; ++_i) \
;         __builtin_amdgcn_global_load_lds((const unsigned*)((const char*)(gbase) + (voff)[_i]), (LAS unsigned*)(lds + (bufoff) + ldsw + _i * 8192), 16, 0, 0); } while (0)
; #define PG8_LDA(dst, b, h) do { _Pragma("unroll") for (int m = 0; m < 4; ++m) _Pragma("unroll") for (int k = 0; k < 2; ++k) dst[m][k] = *(const LAS h8*)(lds + PG8_SA(b, h) + aoff + m * 2048 + k * 1024); } while (0)
; #define PG8_LDB(dst, b, h) do { _Pragma("unroll") for (int n = 0; n < 2; ++n) _Pragma("unroll") for (int k = 0; k < 2; ++k) dst[n][k] = *(const LAS h8*)(lds + PG8_SB(b, h) + boff + n * 2048 + k * 1024); } while (0)
; #define PG8_MMA(ai, bj, At, Bt) do { __builtin_amdgcn_s_setprio(1); _Pragma("unroll") for (int m = 0; m < 4; ++m) _Pragma("unroll") for (int n = 0; n < 2; ++n) _Pragma("unroll") for (int k = 0; k < 2; ++k) \
;         acc[ai][bj][m][n] = __builtin_amdgcn_mfma_f32_16x16x32_f16(Bt[n][k], At[m][k], acc[ai][bj][m][n], 0, 0, 0); __builtin_amdgcn_s_setprio(0); } while (0)
; #define PG8_WAIT_V(n) asm volatile("s_waitcnt vmcnt(" #n ")" ::: "memory")
; #define PG8_WAIT_L(n) asm volatile("s_waitcnt lgkmcnt(" #n ")" ::: "memory")
; #define PG8_BAR __builtin_amdgcn_s_barrier()
; #define PG8_SCHED __builtin_amdgcn_sched_barrier(0)
; template <class Epi>
; __device__ __forceinline__ void gemm_phase(LAS unsigned char* lds, const Gemm g, const StaticOrder& S, const Epi& E, unsigned long long& sw_acc) {
;     ...
;             PG8_LDB(B0, 0, 0); PG8_LDB(B1, 0, 1); PG8_SCHED; PG8_LDA(At, 0, 0); PG8_STAGE(PG8_SA(1, 1), a1 + hstep, voffA);
;             PG8_WAIT_V(8); PG8_WAIT_L(0); PG8_BAR; PG8_MMA(0, 0, At, B0); PG8_MMA(0, 1, At, B1); PG8_BAR; PG8_SCHED;
;             PG8_LDA(At, 0, 1); PG8_STAGE(PG8_SB(0, 0), b2, voffB); PG8_STAGE(PG8_SB(0, 1), b2 + hstepB, voffB); PG8_STAGE(PG8_SA(0, 0), a2, voffA);
;             PG8_WAIT_V(8); PG8_WAIT_L(0); PG8_BAR; PG8_MMA(1, 0, At, B0); PG8_MMA(1, 1, At, B1); PG8_BAR; PG8_SCHED;
.LBB0_134:
	s_add_u32 s6, s52, s4
	s_addc_u32 s7, s53, s5
	s_add_u32 s28, s6, 0x40080
	s_addc_u32 s29, s7, 0
	s_add_u32 s6, s6, 0x100
	s_addc_u32 s7, s7, 0
	s_add_u32 s15, s72, s4
	s_addc_u32 s20, s73, s5
	s_add_i32 s21, 0, 0x10000
	s_cmpk_eq_i32 s4, 0x700
	s_cselect_b32 s19, s0, s7
	s_cselect_b32 s18, s1, s6
	s_cselect_b32 s7, s10, s20
	s_cselect_b32 s6, s11, s15
	s_add_i32 s15, 0, 0x14000
	ds_read_b128 v[136:139], v254
	ds_read_b128 v[140:143], v254 offset:1024
	ds_read_b128 v[144:147], v254 offset:2048
	ds_read_b128 v[148:151], v254 offset:3072
	ds_read_b128 v[152:155], v254 offset:16384
	ds_read_b128 v[156:159], v254 offset:17408
	ds_read_b128 v[160:163], v254 offset:18432
	ds_read_b128 v[164:167], v254 offset:19456
	s_add_i32 m0, s31, 0xc000
	ds_read_b128 v[168:171], v221
	ds_read_b128 v[172:175], v221 offset:1024
	ds_read_b128 v[176:179], v221 offset:2048
	ds_read_b128 v[206:209], v221 offset:3072
	ds_read_b128 v[224:227], v221 offset:4096
	ds_read_b128 v[228:231], v221 offset:5120
	ds_read_b128 v[232:235], v221 offset:6144
	ds_read_b128 v[236:239], v221 offset:7168
	global_load_lds_dwordx4 v202, s[28:29]
	s_add_i32 m0, s31, 0xe000
	s_nop 0
	global_load_lds_dwordx4 v204, s[28:29]
	s_waitcnt vmcnt(8)
	s_waitcnt lgkmcnt(0)
	s_barrier
	s_waitcnt lgkmcnt(0)
	v_mfma_f32_16x16x32_f16 v[128:131], v[136:139], v[168:171], v[128:131]
	v_mfma_f32_16x16x32_f16 v[124:127], v[144:147], v[168:171], v[124:127]
	v_mfma_f32_16x16x32_f16 v[120:123], v[136:139], v[176:179], v[120:123]
	v_mfma_f32_16x16x32_f16 v[116:119], v[144:147], v[176:179], v[116:119]
	v_mfma_f32_16x16x32_f16 v[112:115], v[136:139], v[224:227], v[112:115]
	v_mfma_f32_16x16x32_f16 v[108:111], v[144:147], v[224:227], v[108:111]
	v_mfma_f32_16x16x32_f16 v[104:107], v[136:139], v[232:235], v[104:107]
	v_mfma_f32_16x16x32_f16 v[100:103], v[144:147], v[232:235], v[100:103]
	v_mfma_f32_16x16x32_f16 v[128:131], v[140:143], v[172:175], v[128:131]
	v_mfma_f32_16x16x32_f16 v[124:127], v[148:151], v[172:175], v[124:127]
	v_mfma_f32_16x16x32_f16 v[120:123], v[140:143], v[206:209], v[120:123]
	v_mfma_f32_16x16x32_f16 v[116:119], v[148:151], v[206:209], v[116:119]
	v_mfma_f32_16x16x32_f16 v[112:115], v[140:143], v[228:231], v[112:115]
	v_mfma_f32_16x16x32_f16 v[108:111], v[148:151], v[228:231], v[108:111]
	v_mfma_f32_16x16x32_f16 v[104:107], v[140:143], v[236:239], v[104:107]
	v_mfma_f32_16x16x32_f16 v[100:103], v[148:151], v[236:239], v[100:103]
	v_mfma_f32_16x16x32_f16 v[96:99], v[152:155], v[168:171], v[96:99]
	v_mfma_f32_16x16x32_f16 v[92:95], v[160:163], v[168:171], v[92:95]
	v_mfma_f32_16x16x32_f16 v[88:91], v[152:155], v[176:179], v[88:91]
	v_mfma_f32_16x16x32_f16 v[84:87], v[160:163], v[176:179], v[84:87]
	v_mfma_f32_16x16x32_f16 v[80:83], v[152:155], v[224:227], v[80:83]
	v_mfma_f32_16x16x32_f16 v[76:79], v[160:163], v[224:227], v[76:79]
	v_mfma_f32_16x16x32_f16 v[72:75], v[152:155], v[232:235], v[72:75]
	v_mfma_f32_16x16x32_f16 v[68:71], v[160:163], v[232:235], v[68:71]
	v_mfma_f32_16x16x32_f16 v[96:99], v[156:159], v[172:175], v[96:99]
	v_mfma_f32_16x16x32_f16 v[92:95], v[164:167], v[172:175], v[92:95]
	v_mfma_f32_16x16x32_f16 v[88:91], v[156:159], v[206:209], v[88:91]
	v_mfma_f32_16x16x32_f16 v[84:87], v[164:167], v[206:209], v[84:87]
	v_mfma_f32_16x16x32_f16 v[80:83], v[156:159], v[228:231], v[80:83]
	v_mfma_f32_16x16x32_f16 v[76:79], v[164:167], v[228:231], v[76:79]
	v_mfma_f32_16x16x32_f16 v[72:75], v[156:159], v[236:239], v[72:75]
	v_mfma_f32_16x16x32_f16 v[68:71], v[164:167], v[236:239], v[68:71]
	s_barrier
	s_add_i32 s20, s21, s26
	s_mov_b32 m0, s20
	ds_read_b128 v[168:171], v221 offset:16384
	ds_read_b128 v[172:175], v221 offset:17408
	ds_read_b128 v[176:179], v221 offset:18432
	ds_read_b128 v[206:209], v221 offset:19456
	ds_read_b128 v[224:227], v221 offset:20480
	ds_read_b128 v[228:231], v221 offset:21504
	ds_read_b128 v[232:235], v221 offset:22528
	ds_read_b128 v[236:239], v221 offset:23552
	global_load_lds_dwordx4 v196, s[6:7]
	s_add_i32 m0, s20, 0x2000
	s_add_u32 s20, s6, 0x10000
	s_addc_u32 s21, s7, 0
	s_add_i32 s15, s15, s26
	global_load_lds_dwordx4 v192, s[6:7]
	s_mov_b32 m0, s15
	s_nop 0
	global_load_lds_dwordx4 v196, s[20:21]
	s_add_i32 m0, s15, 0x2000
	s_nop 0
	global_load_lds_dwordx4 v192, s[20:21]
	s_mov_b32 m0, s31
	s_nop 0
	global_load_lds_dwordx4 v198, s[18:19]
	s_mov_b32 m0, s33
	s_nop 0
	global_load_lds_dwordx4 v194, s[18:19]
	s_waitcnt vmcnt(8)
	s_waitcnt lgkmcnt(0)
	s_barrier
	s_waitcnt lgkmcnt(0)
	v_mfma_f32_16x16x32_f16 v[64:67], v[136:139], v[168:171], v[64:67]
	v_mfma_f32_16x16x32_f16 v[60:63], v[144:147], v[168:171], v[60:63]
	v_mfma_f32_16x16x32_f16 v[56:59], v[136:139], v[176:179], v[56:59]
	v_mfma_f32_16x16x32_f16 v[52:55], v[144:147], v[176:179], v[52:55]
	v_mfma_f32_16x16x32_f16 v[48:51], v[136:139], v[224:227], v[48:51]
	v_mfma_f32_16x16x32_f16 v[44:47], v[144:147], v[224:227], v[44:47]
	v_mfma_f32_16x16x32_f16 v[40:43], v[136:139], v[232:235], v[40:43]
	v_mfma_f32_16x16x32_f16 v[36:39], v[144:147], v[232:235], v[36:39]
	v_mfma_f32_16x16x32_f16 v[64:67], v[140:143], v[172:175], v[64:67]
	v_mfma_f32_16x16x32_f16 v[60:63], v[148:151], v[172:175], v[60:63]
	v_mfma_f32_16x16x32_f16 v[56:59], v[140:143], v[206:209], v[56:59]
	v_mfma_f32_16x16x32_f16 v[52:55], v[148:151], v[206:209], v[52:55]
	v_mfma_f32_16x16x32_f16 v[48:51], v[140:143], v[228:231], v[48:51]
	v_mfma_f32_16x16x32_f16 v[44:47], v[148:151], v[228:231], v[44:47]
	v_mfma_f32_16x16x32_f16 v[40:43], v[140:143], v[236:239], v[40:43]
	v_mfma_f32_16x16x32_f16 v[36:39], v[148:151], v[236:239], v[36:39]
	v_mfma_f32_16x16x32_f16 v[32:35], v[152:155], v[168:171], v[32:35]
	v_mfma_f32_16x16x32_f16 v[28:31], v[160:163], v[168:171], v[28:31]
	v_mfma_f32_16x16x32_f16 v[24:27], v[152:155], v[176:179], v[24:27]
	v_mfma_f32_16x16x32_f16 v[20:23], v[160:163], v[176:179], v[20:23]
	v_mfma_f32_16x16x32_f16 v[16:19], v[152:155], v[224:227], v[16:19]
	v_mfma_f32_16x16x32_f16 v[12:15], v[160:163], v[224:227], v[12:15]
	v_mfma_f32_16x16x32_f16 v[8:11], v[152:155], v[232:235], v[8:11]
	v_mfma_f32_16x16x32_f16 v[4:7], v[160:163], v[232:235], v[4:7]
	v_mfma_f32_16x16x32_f16 v[32:35], v[156:159], v[172:175], v[32:35]
	v_mfma_f32_16x16x32_f16 v[28:31], v[164:167], v[172:175], v[28:31]
	v_mfma_f32_16x16x32_f16 v[24:27], v[156:159], v[206:209], v[24:27]
	v_mfma_f32_16x16x32_f16 v[20:23], v[164:167], v[206:209], v[20:23]
	v_mfma_f32_16x16x32_f16 v[16:19], v[156:159], v[228:231], v[16:19]
	v_mfma_f32_16x16x32_f16 v[12:15], v[164:167], v[228:231], v[12:15]
	v_mfma_f32_16x16x32_f16 v[8:11], v[156:159], v[236:239], v[8:11]
	v_mfma_f32_16x16x32_f16 v[4:7], v[164:167], v[236:239], v[4:7]
	s_barrier
; #define PG8_STAGE(bufoff, gbase, voff) do { _Pragma("unroll") for (int _i = 0; _i < 2; ++_i) \
;         __builtin_amdgcn_global_load_lds((const unsigned*)((const char*)(gbase) + (voff)[_i]), (LAS unsigned*)(lds + (bufoff) + ldsw + _i * 8192), 16, 0, 0); } while (0)
; #define PG8_LDA(dst, b, h) do { _Pragma("unroll") for (int m = 0; m < 4; ++m) _Pragma("unroll") for (int k = 0; k < 2; ++k) dst[m][k] = *(const LAS h8*)(lds + PG8_SA(b, h) + aoff + m * 2048 + k * 1024); } while (0)
; #define PG8_LDB(dst, b, h) do { _Pragma("unroll") for (int n = 0; n < 2; ++n) _Pragma("unroll") for (int k = 0; k < 2; ++k) dst[n][k] = *(const LAS h8*)(lds + PG8_SB(b, h) + boff + n * 2048 + k * 1024); } while (0)
; #define PG8_MMA(ai, bj, At, Bt) do { __builtin_amdgcn_s_setprio(1); _Pragma("unroll") for (int m = 0; m < 4; ++m) _Pragma("unroll") for (int n = 0; n < 2; ++n) _Pragma("unroll") for (int k = 0; k < 2; ++k) \
;         acc[ai][bj][m][n] = __builtin_amdgcn_mfma_f32_16x16x32_f16(Bt[n][k], At[m][k], acc[ai][bj][m][n], 0, 0, 0); __builtin_amdgcn_s_setprio(0); } while (0)
; #define PG8_WAIT_V(n) asm volatile("s_waitcnt vmcnt(" #n ")" ::: "memory")
; #define PG8_WAIT_L(n) asm volatile("s_waitcnt lgkmcnt(" #n ")" ::: "memory")
; #define PG8_BAR __builtin_amdgcn_s_barrier()
; #define PG8_SCHED __builtin_amdgcn_sched_barrier(0)
; template <class Epi>
; __device__ __forceinline__ void gemm_phase(LAS unsigned char* lds, const Gemm g, const StaticOrder& S, const Epi& E, unsigned long long& sw_acc) {
;     ...
;             PG8_LDB(B0, 1, 0); PG8_LDB(B1, 1, 1); PG8_SCHED; PG8_LDA(At, 1, 0); PG8_STAGE(PG8_SA(0, 1), a2 + hstep, voffA);
;             PG8_WAIT_V(8); PG8_WAIT_L(0); PG8_BAR; PG8_MMA(0, 0, At, B0); PG8_MMA(0, 1, At, B1); PG8_BAR; PG8_SCHED;
;             PG8_LDA(At, 1, 1); PG8_STAGE(PG8_SB(1, 0), b3, voffB); PG8_STAGE(PG8_SB(1, 1), b3 + hstepB, voffB); PG8_STAGE(PG8_SA(1, 0), a3, voffA);
;             PG8_WAIT_V(8); PG8_WAIT_L(0); PG8_BAR; PG8_MMA(1, 0, At, B0); PG8_MMA(1, 1, At, B1); PG8_BAR; PG8_SCHED;
;         }
	s_add_i32 s15, 0, 0x18000
	s_add_i32 s20, 0, 0x1c000
	ds_read_b128 v[136:139], v255
	ds_read_b128 v[140:143], v255 offset:1024
	ds_read_b128 v[144:147], v255 offset:2048
	ds_read_b128 v[148:151], v255 offset:3072
	ds_read_b128 v[152:155], v255 offset:16384
	ds_read_b128 v[156:159], v255 offset:17408
	ds_read_b128 v[160:163], v255 offset:18432
	ds_read_b128 v[164:167], v255 offset:19456
	s_add_u32 s18, s18, 0x40000
	s_addc_u32 s19, s19, 0
	s_mov_b32 m0, s34
	ds_read_b128 v[168:171], v221 offset:32768
	ds_read_b128 v[172:175], v221 offset:33792
	ds_read_b128 v[176:179], v221 offset:34816
	ds_read_b128 v[206:209], v221 offset:35840
	ds_read_b128 v[224:227], v221 offset:36864
	ds_read_b128 v[228:231], v221 offset:37888
	ds_read_b128 v[232:235], v221 offset:38912
	ds_read_b128 v[236:239], v221 offset:39936
	global_load_lds_dwordx4 v198, s[18:19]
	s_mov_b32 m0, s35
	s_nop 0
	global_load_lds_dwordx4 v194, s[18:19]
	s_waitcnt vmcnt(8)
	s_waitcnt lgkmcnt(0)
	s_barrier
	s_waitcnt lgkmcnt(0)
	v_mfma_f32_16x16x32_f16 v[128:131], v[136:139], v[168:171], v[128:131]
	v_mfma_f32_16x16x32_f16 v[124:127], v[144:147], v[168:171], v[124:127]
	v_mfma_f32_16x16x32_f16 v[120:123], v[136:139], v[176:179], v[120:123]
	v_mfma_f32_16x16x32_f16 v[116:119], v[144:147], v[176:179], v[116:119]
	v_mfma_f32_16x16x32_f16 v[112:115], v[136:139], v[224:227], v[112:115]
	v_mfma_f32_16x16x32_f16 v[108:111], v[144:147], v[224:227], v[108:111]
	v_mfma_f32_16x16x32_f16 v[104:107], v[136:139], v[232:235], v[104:107]
	v_mfma_f32_16x16x32_f16 v[100:103], v[144:147], v[232:235], v[100:103]
	v_mfma_f32_16x16x32_f16 v[128:131], v[140:143], v[172:175], v[128:131]
	v_mfma_f32_16x16x32_f16 v[124:127], v[148:151], v[172:175], v[124:127]
	v_mfma_f32_16x16x32_f16 v[120:123], v[140:143], v[206:209], v[120:123]
	v_mfma_f32_16x16x32_f16 v[116:119], v[148:151], v[206:209], v[116:119]
	v_mfma_f32_16x16x32_f16 v[112:115], v[140:143], v[228:231], v[112:115]
	v_mfma_f32_16x16x32_f16 v[108:111], v[148:151], v[228:231], v[108:111]
	v_mfma_f32_16x16x32_f16 v[104:107], v[140:143], v[236:239], v[104:107]
	v_mfma_f32_16x16x32_f16 v[100:103], v[148:151], v[236:239], v[100:103]
	v_mfma_f32_16x16x32_f16 v[96:99], v[152:155], v[168:171], v[96:99]
	v_mfma_f32_16x16x32_f16 v[92:95], v[160:163], v[168:171], v[92:95]
	v_mfma_f32_16x16x32_f16 v[88:91], v[152:155], v[176:179], v[88:91]
	v_mfma_f32_16x16x32_f16 v[84:87], v[160:163], v[176:179], v[84:87]
	v_mfma_f32_16x16x32_f16 v[80:83], v[152:155], v[224:227], v[80:83]
	v_mfma_f32_16x16x32_f16 v[76:79], v[160:163], v[224:227], v[76:79]
	v_mfma_f32_16x16x32_f16 v[72:75], v[152:155], v[232:235], v[72:75]
	v_mfma_f32_16x16x32_f16 v[68:71], v[160:163], v[232:235], v[68:71]
	v_mfma_f32_16x16x32_f16 v[96:99], v[156:159], v[172:175], v[96:99]
	v_mfma_f32_16x16x32_f16 v[92:95], v[164:167], v[172:175], v[92:95]
	v_mfma_f32_16x16x32_f16 v[88:91], v[156:159], v[206:209], v[88:91]
	v_mfma_f32_16x16x32_f16 v[84:87], v[164:167], v[206:209], v[84:87]
	v_mfma_f32_16x16x32_f16 v[80:83], v[156:159], v[228:231], v[80:83]
	v_mfma_f32_16x16x32_f16 v[76:79], v[164:167], v[228:231], v[76:79]
	v_mfma_f32_16x16x32_f16 v[72:75], v[156:159], v[236:239], v[72:75]
	v_mfma_f32_16x16x32_f16 v[68:71], v[164:167], v[236:239], v[68:71]
	s_barrier
	s_add_i32 s15, s15, s26
	s_add_u32 s28, s6, 0x80
	s_addc_u32 s29, s7, 0
	s_mov_b32 m0, s15
	ds_read_b128 v[168:171], v221 offset:49152
	ds_read_b128 v[172:175], v221 offset:50176
	ds_read_b128 v[176:179], v221 offset:51200
	ds_read_b128 v[206:209], v221 offset:52224
	ds_read_b128 v[224:227], v221 offset:53248
	ds_read_b128 v[228:231], v221 offset:54272
	ds_read_b128 v[232:235], v221 offset:55296
	ds_read_b128 v[236:239], v221 offset:56320
	global_load_lds_dwordx4 v196, s[28:29]
	s_add_i32 m0, s15, 0x2000
	s_add_u32 s6, s6, 0x10080
	s_addc_u32 s7, s7, 0
	s_add_i32 s15, s20, s26
	global_load_lds_dwordx4 v192, s[28:29]
	s_mov_b32 m0, s15
	s_sub_u32 s18, s18, 0x3ff80
	s_subb_u32 s19, s19, 0
	global_load_lds_dwordx4 v196, s[6:7]
	s_add_i32 m0, s15, 0x2000
	s_nop 0
	global_load_lds_dwordx4 v192, s[6:7]
	s_mov_b32 m0, s36
	s_nop 0
	global_load_lds_dwordx4 v198, s[18:19]
	s_mov_b32 m0, s37
	s_nop 0
	global_load_lds_dwordx4 v194, s[18:19]
	s_waitcnt vmcnt(8)
	s_waitcnt lgkmcnt(0)
	s_barrier
	s_waitcnt lgkmcnt(0)
	v_mfma_f32_16x16x32_f16 v[64:67], v[136:139], v[168:171], v[64:67]
	v_mfma_f32_16x16x32_f16 v[60:63], v[144:147], v[168:171], v[60:63]
	v_mfma_f32_16x16x32_f16 v[56:59], v[136:139], v[176:179], v[56:59]
	v_mfma_f32_16x16x32_f16 v[52:55], v[144:147], v[176:179], v[52:55]
	v_mfma_f32_16x16x32_f16 v[48:51], v[136:139], v[224:227], v[48:51]
	v_mfma_f32_16x16x32_f16 v[44:47], v[144:147], v[224:227], v[44:47]
	v_mfma_f32_16x16x32_f16 v[40:43], v[136:139], v[232:235], v[40:43]
	v_mfma_f32_16x16x32_f16 v[36:39], v[144:147], v[232:235], v[36:39]
	v_mfma_f32_16x16x32_f16 v[64:67], v[140:143], v[172:175], v[64:67]
	v_mfma_f32_16x16x32_f16 v[60:63], v[148:151], v[172:175], v[60:63]
	v_mfma_f32_16x16x32_f16 v[56:59], v[140:143], v[206:209], v[56:59]
	v_mfma_f32_16x16x32_f16 v[52:55], v[148:151], v[206:209], v[52:55]
	v_mfma_f32_16x16x32_f16 v[48:51], v[140:143], v[228:231], v[48:51]
	v_mfma_f32_16x16x32_f16 v[44:47], v[148:151], v[228:231], v[44:47]
	v_mfma_f32_16x16x32_f16 v[40:43], v[140:143], v[236:239], v[40:43]
	v_mfma_f32_16x16x32_f16 v[36:39], v[148:151], v[236:239], v[36:39]
	v_mfma_f32_16x16x32_f16 v[32:35], v[152:155], v[168:171], v[32:35]
	v_mfma_f32_16x16x32_f16 v[28:31], v[160:163], v[168:171], v[28:31]
	v_mfma_f32_16x16x32_f16 v[24:27], v[152:155], v[176:179], v[24:27]
	v_mfma_f32_16x16x32_f16 v[20:23], v[160:163], v[176:179], v[20:23]
	v_mfma_f32_16x16x32_f16 v[16:19], v[152:155], v[224:227], v[16:19]
	v_mfma_f32_16x16x32_f16 v[12:15], v[160:163], v[224:227], v[12:15]
	v_mfma_f32_16x16x32_f16 v[8:11], v[152:155], v[232:235], v[8:11]
	v_mfma_f32_16x16x32_f16 v[4:7], v[160:163], v[232:235], v[4:7]
	v_mfma_f32_16x16x32_f16 v[32:35], v[156:159], v[172:175], v[32:35]
	v_mfma_f32_16x16x32_f16 v[28:31], v[164:167], v[172:175], v[28:31]
	v_mfma_f32_16x16x32_f16 v[24:27], v[156:159], v[206:209], v[24:27]
	v_mfma_f32_16x16x32_f16 v[20:23], v[164:167], v[206:209], v[20:23]
	v_mfma_f32_16x16x32_f16 v[16:19], v[156:159], v[228:231], v[16:19]
	v_mfma_f32_16x16x32_f16 v[12:15], v[164:167], v[228:231], v[12:15]
	v_mfma_f32_16x16x32_f16 v[8:11], v[156:159], v[236:239], v[8:11]
	v_mfma_f32_16x16x32_f16 v[4:7], v[164:167], v[236:239], v[4:7]
	s_barrier
	s_add_i32 s14, s14, 2
	s_add_u32 s4, s4, 0x100
	s_addc_u32 s5, s5, 0
	s_cmp_gt_u32 s14, 13
	s_cbranch_scc0 .LBB0_134
	s_and_b64 vcc, exec, s[54:55]
	s_cbranch_vccz .LBB0_137
	s_barrier
; #define LAS __attribute__((address_space(3)))
; #define GAS __attribute__((address_space(1)))
;     __device__ __forceinline__ void operator()(const f32x4 (&acc)[2][2][4][2], const Unit& u, int wr, int wc, int fr, int fq) const {
;         const int sec = u.pn >> 1;
;         const int row0 = u.pm * BM + wr * 64 + fr;
;         const int cs = (u.pn & 1) * BM + wc * 64 + 8 * fq;
;         const bool isqg = (sec == 0) || (sec == 3) || (sec == 4) || (sec == 7);
;         const int dsec = isqg ? ((sec == 0) ? S_SBQ : (sec == 3) ? S_SBG : (sec == 4) ? S_DAQ : S_DAG) : ((sec == 1) ? 0 : (sec == 2) ? 1 : (sec == 5) ? 2 : 3);
;         const int bjstep = isqg ? 1024 : 32;
;         f32x4 gain[2][2];
;         if (sec == 4 || sec == 5) {
;             const GAS float* g = (sec == 4) ? gq : gk;
; #pragma unroll
;             for (int bj = 0; bj < 2; ++bj)
; #pragma unroll
;                 for (int n = 0; n < 2; ++n) gain[bj][n] = *(const GAS f32x4*)(g + 32 * bj + 8 * fq + 4 * n);
;         }
;         const LAS int* tags = (const LAS int*)(rsc + 2048);
;         const int slot = (tags[0] == u.pm) ? 0 : (tags[1] == u.pm) ? 1 : -1;
;         const LAS float* rtab = (const LAS float*)rsc + (slot > 0 ? 256 : 0) + wr * 64 + fr;
.LBB0_137:
	s_and_b64 vcc, exec, s[84:85]
	s_cbranch_vccz .Lepi_orig_g1
	s_lshr_b32 s57, s69, 1
	s_cmp_eq_u32 s57, 0
	s_cbranch_scc1 .Lepi_qs
	s_cmp_eq_u32 s57, 1
	s_cbranch_scc1 .Lepi_kvp
	s_cmp_eq_u32 s57, 2
	s_cbranch_scc1 .Lepi_kvp
	s_cmp_eq_u32 s57, 3
	s_cbranch_scc1 .Lepi_silu
	s_cmp_eq_u32 s57, 4
	s_cbranch_scc1 .Lepi_qn
	s_cmp_eq_u32 s57, 5
	s_cbranch_scc1 .Lepi_kn
	s_cmp_eq_u32 s57, 6
	s_cbranch_scc1 .Lepi_kvp
	s_cmp_eq_u32 s57, 7
	s_cbranch_scc1 .Lepi_silu

; #define LAS __attribute__((address_space(3)))
; #define GAS __attribute__((address_space(1)))
; __host__ __device__ __forceinline__ size_t bl512(size_t row, int col) { return ((row >> 5) * 64 + (size_t)(col >> 3)) * 256 + (row & 31) * 8 + (col & 7); }
;     __device__ __forceinline__ void operator()(const f32x4 (&acc)[2][2][4][2], const Unit& u, int wr, int wc, int fr, int fq) const {
;     ...
;         const LAS float* rtab = (const LAS float*)rsc + (slot > 0 ? 256 : 0) + wr * 64 + fr;
; #pragma unroll
;         for (int ai = 0; ai < 2; ++ai)
; #pragma unroll
;             for (int m = 0; m < 4; ++m) {
;                 const int row = row0 + ai * HALF + m * 16;
;                 float rs;
;                 if (slot >= 0) rs = rtab[ai * HALF + m * 16];
;                 else {
;                     const f32x4 pv = *(const GAS f32x4*)(part + (size_t)row * 16 + fq * 4);
;                     float s = (pv[0] + pv[1]) + (pv[2] + pv[3]);
;                     s = row4_sum(s);
;                     rs = __builtin_amdgcn_rsqf(s * (1.0f / DM) + RMS_EPS);
;                 }
;                 f32x4 v[2][2];
; #pragma unroll
;                 for (int bj = 0; bj < 2; ++bj)
; #pragma unroll
;                     for (int n = 0; n < 2; ++n) v[bj][n] = acc[ai][bj][m][n] * rs;
;     ...
;                 GAS f16* rowp = isqg ? QG + (size_t)dsec * QG_SEC + bl512((size_t)row, cs) : KV + (size_t)row * KVW + dsec * 512 + cs;
; #pragma unroll
;                 for (int bj = 0; bj < 2; ++bj) {
;                     u32x4 w; w.x = pkh(v[bj][0][0], v[bj][0][1]); w.y = pkh(v[bj][0][2], v[bj][0][3]); w.z = pkh(v[bj][1][0], v[bj][1][1]); w.w = pkh(v[bj][1][2], v[bj][1][3]);
;                     *(GAS u32x4*)(rowp + bjstep * bj) = w;
;                 }
.Lepi_tail_g1:
	s_andn2_b64 vcc, exec, s[50:51]
	s_cbranch_vccnz .LBB0_121
	s_barrier
	s_branch .LBB0_121
.Lepi_kvp:
	s_and_b32 s0, s70, 1
	s_lshl_b32 s0, s0, 10
	v_add_u32_e32 v132, s0, v219
	ds_read_b32 v134, v132
	ds_read_b32 v136, v132 offset:64
	ds_read_b32 v138, v132 offset:128
	ds_read_b32 v140, v132 offset:192
	ds_read_b32 v142, v132 offset:512
	ds_read_b32 v144, v132 offset:576
	ds_read_b32 v146, v132 offset:640
	ds_read_b32 v148, v132 offset:704
	s_lshr_b32 s0, s69, 2
	s_and_b32 s1, s69, 1
	v_lshl_add_u32 v133, s68, 8, v187
	v_lshlrev_b32_e32 v133, 12, v133
	v_lshl_add_u32 v133, v220, 1, v133
	s_lshl_b32 s0, s0, 10
	s_lshl_b32 s1, s1, 9
	s_add_u32 s0, s0, s1
	s_add_u32 s4, s8, s0
	s_addc_u32 s5, s9, 0
	s_waitcnt lgkmcnt(0)
	s_mov_b32 s6, s4
	s_mov_b32 s7, s5
	v_pk_mul_f32 v[128:129], v[128:129], v[134:135] op_sel_hi:[1,0]
	v_pk_mul_f32 v[130:131], v[130:131], v[134:135] op_sel_hi:[1,0]
	v_pk_mul_f32 v[124:125], v[124:125], v[134:135] op_sel_hi:[1,0]
	v_pk_mul_f32 v[126:127], v[126:127], v[134:135] op_sel_hi:[1,0]
	v_pk_mul_f32 v[96:97], v[96:97], v[134:135] op_sel_hi:[1,0]
	v_pk_mul_f32 v[98:99], v[98:99], v[134:135] op_sel_hi:[1,0]
	v_pk_mul_f32 v[92:93], v[92:93], v[134:135] op_sel_hi:[1,0]
	v_pk_mul_f32 v[94:95], v[94:95], v[134:135] op_sel_hi:[1,0]
	v_cvt_pk_f16_f32 v152, v128, v129
	v_cvt_pk_f16_f32 v153, v130, v131
	v_cvt_pk_f16_f32 v154, v124, v125
	v_cvt_pk_f16_f32 v155, v126, v127
	global_store_dwordx4 v133, v[152:155], s[6:7]
	v_cvt_pk_f16_f32 v156, v96, v97
	v_cvt_pk_f16_f32 v157, v98, v99
	v_cvt_pk_f16_f32 v158, v92, v93
	v_cvt_pk_f16_f32 v159, v94, v95
	global_store_dwordx4 v133, v[156:159], s[6:7] offset:64
	s_add_u32 s6, s4, 0x10000
	s_addc_u32 s7, s5, 0
	v_pk_mul_f32 v[120:121], v[120:121], v[136:137] op_sel_hi:[1,0]
	v_pk_mul_f32 v[122:123], v[122:123], v[136:137] op_sel_hi:[1,0]
	v_pk_mul_f32 v[116:117], v[116:117], v[136:137] op_sel_hi:[1,0]
	v_pk_mul_f32 v[118:119], v[118:119], v[136:137] op_sel_hi:[1,0]
	v_pk_mul_f32 v[88:89], v[88:89], v[136:137] op_sel_hi:[1,0]
	v_pk_mul_f32 v[90:91], v[90:91], v[136:137] op_sel_hi:[1,0]
	v_pk_mul_f32 v[84:85], v[84:85], v[136:137] op_sel_hi:[1,0]
	v_pk_mul_f32 v[86:87], v[86:87], v[136:137] op_sel_hi:[1,0]
	v_cvt_pk_f16_f32 v160, v120, v121
	v_cvt_pk_f16_f32 v161, v122, v123
	v_cvt_pk_f16_f32 v162, v116, v117
	v_cvt_pk_f16_f32 v163, v118, v119
	global_store_dwordx4 v133, v[160:163], s[6:7]
	v_cvt_pk_f16_f32 v164, v88, v89
	v_cvt_pk_f16_f32 v165, v90, v91
	v_cvt_pk_f16_f32 v166, v84, v85
	v_cvt_pk_f16_f32 v167, v86, v87
	global_store_dwordx4 v133, v[164:167], s[6:7] offset:64
	s_add_u32 s6, s4, 0x20000
	s_addc_u32 s7, s5, 0
	v_pk_mul_f32 v[112:113], v[112:113], v[138:139] op_sel_hi:[1,0]
	v_pk_mul_f32 v[114:115], v[114:115], v[138:139] op_sel_hi:[1,0]
	v_pk_mul_f32 v[108:109], v[108:109], v[138:139] op_sel_hi:[1,0]
	v_pk_mul_f32 v[110:111], v[110:111], v[138:139] op_sel_hi:[1,0]
	v_pk_mul_f32 v[80:81], v[80:81], v[138:139] op_sel_hi:[1,0]
	v_pk_mul_f32 v[82:83], v[82:83], v[138:139] op_sel_hi:[1,0]
	v_pk_mul_f32 v[76:77], v[76:77], v[138:139] op_sel_hi:[1,0]
	v_pk_mul_f32 v[78:79], v[78:79], v[138:139] op_sel_hi:[1,0]
	v_cvt_pk_f16_f32 v152, v112, v113
	v_cvt_pk_f16_f32 v153, v114, v115
	v_cvt_pk_f16_f32 v154, v108, v109
	v_cvt_pk_f16_f32 v155, v110, v111
	global_store_dwordx4 v133, v[152:155], s[6:7]
	v_cvt_pk_f16_f32 v156, v80, v81
	v_cvt_pk_f16_f32 v157, v82, v83
	v_cvt_pk_f16_f32 v158, v76, v77
	v_cvt_pk_f16_f32 v159, v78, v79
	global_store_dwordx4 v133, v[156:159], s[6:7] offset:64
	s_add_u32 s6, s4, 0x30000
	s_addc_u32 s7, s5, 0
	v_pk_mul_f32 v[104:105], v[104:105], v[140:141] op_sel_hi:[1,0]
	v_pk_mul_f32 v[106:107], v[106:107], v[140:141] op_sel_hi:[1,0]
	v_pk_mul_f32 v[100:101], v[100:101], v[140:141] op_sel_hi:[1,0]
	v_pk_mul_f32 v[102:103], v[102:103], v[140:141] op_sel_hi:[1,0]
	v_pk_mul_f32 v[72:73], v[72:73], v[140:141] op_sel_hi:[1,0]
	v_pk_mul_f32 v[74:75], v[74:75], v[140:141] op_sel_hi:[1,0]
	v_pk_mul_f32 v[68:69], v[68:69], v[140:141] op_sel_hi:[1,0]
	v_pk_mul_f32 v[70:71], v[70:71], v[140:141] op_sel_hi:[1,0]
	v_cvt_pk_f16_f32 v160, v104, v105
	v_cvt_pk_f16_f32 v161, v106, v107
	v_cvt_pk_f16_f32 v162, v100, v101
	v_cvt_pk_f16_f32 v163, v102, v103
	global_store_dwordx4 v133, v[160:163], s[6:7]
	v_cvt_pk_f16_f32 v164, v72, v73
	v_cvt_pk_f16_f32 v165, v74, v75
	v_cvt_pk_f16_f32 v166, v68, v69
	v_cvt_pk_f16_f32 v167, v70, v71
	global_store_dwordx4 v133, v[164:167], s[6:7] offset:64
	s_add_u32 s6, s4, 0x80000
	s_addc_u32 s7, s5, 0
	v_pk_mul_f32 v[64:65], v[64:65], v[142:143] op_sel_hi:[1,0]
	v_pk_mul_f32 v[66:67], v[66:67], v[142:143] op_sel_hi:[1,0]
	v_pk_mul_f32 v[60:61], v[60:61], v[142:143] op_sel_hi:[1,0]
	v_pk_mul_f32 v[62:63], v[62:63], v[142:143] op_sel_hi:[1,0]
	v_pk_mul_f32 v[32:33], v[32:33], v[142:143] op_sel_hi:[1,0]
	v_pk_mul_f32 v[34:35], v[34:35], v[142:143] op_sel_hi:[1,0]
	v_pk_mul_f32 v[28:29], v[28:29], v[142:143] op_sel_hi:[1,0]
	v_pk_mul_f32 v[30:31], v[30:31], v[142:143] op_sel_hi:[1,0]
	v_cvt_pk_f16_f32 v152, v64, v65
	v_cvt_pk_f16_f32 v153, v66, v67
	v_cvt_pk_f16_f32 v154, v60, v61
	v_cvt_pk_f16_f32 v155, v62, v63
	global_store_dwordx4 v133, v[152:155], s[6:7]
	v_cvt_pk_f16_f32 v156, v32, v33
	v_cvt_pk_f16_f32 v157, v34, v35
	v_cvt_pk_f16_f32 v158, v28, v29
	v_cvt_pk_f16_f32 v159, v30, v31
	global_store_dwordx4 v133, v[156:159], s[6:7] offset:64
	s_add_u32 s6, s4, 0x90000
	s_addc_u32 s7, s5, 0
	v_pk_mul_f32 v[56:57], v[56:57], v[144:145] op_sel_hi:[1,0]
	v_pk_mul_f32 v[58:59], v[58:59], v[144:145] op_sel_hi:[1,0]
	v_pk_mul_f32 v[52:53], v[52:53], v[144:145] op_sel_hi:[1,0]
	v_pk_mul_f32 v[54:55], v[54:55], v[144:145] op_sel_hi:[1,0]
; #define GAS __attribute__((address_space(1)))
;     __device__ __forceinline__ void operator()(const f32x4 (&acc)[2][2][4][2], const Unit& u, int wr, int wc, int fr, int fq) const {
;     ...
;                 const int row = row0 + ai * HALF + m * 16;
;                 float rs;
;                 if (slot >= 0) rs = rtab[ai * HALF + m * 16];
;                 else {
;                     const f32x4 pv = *(const GAS f32x4*)(part + (size_t)row * 16 + fq * 4);
;                     float s = (pv[0] + pv[1]) + (pv[2] + pv[3]);
;                     s = row4_sum(s);
;                     rs = __builtin_amdgcn_rsqf(s * (1.0f / DM) + RMS_EPS);
;                 }
;                 f32x4 v[2][2];
; #pragma unroll
;                 for (int bj = 0; bj < 2; ++bj)
; #pragma unroll
;                     for (int n = 0; n < 2; ++n) v[bj][n] = acc[ai][bj][m][n] * rs;
;     ...
;                 } else if (sec == 0) {
; #pragma unroll
;                     for (int bj = 0; bj < 2; ++bj)
; #pragma unroll
;                         for (int n = 0; n < 2; ++n) v[bj][n] = v[bj][n] * QS;
	v_pk_mul_f32 v[24:25], v[24:25], v[144:145] op_sel_hi:[1,0]
	v_pk_mul_f32 v[26:27], v[26:27], v[144:145] op_sel_hi:[1,0]
	v_pk_mul_f32 v[20:21], v[20:21], v[144:145] op_sel_hi:[1,0]
	v_pk_mul_f32 v[22:23], v[22:23], v[144:145] op_sel_hi:[1,0]
	v_cvt_pk_f16_f32 v160, v56, v57
	v_cvt_pk_f16_f32 v161, v58, v59
	v_cvt_pk_f16_f32 v162, v52, v53
	v_cvt_pk_f16_f32 v163, v54, v55
	global_store_dwordx4 v133, v[160:163], s[6:7]
	v_cvt_pk_f16_f32 v164, v24, v25
	v_cvt_pk_f16_f32 v165, v26, v27
	v_cvt_pk_f16_f32 v166, v20, v21
	v_cvt_pk_f16_f32 v167, v22, v23
	global_store_dwordx4 v133, v[164:167], s[6:7] offset:64
	s_add_u32 s6, s4, 0xa0000
	s_addc_u32 s7, s5, 0
	v_pk_mul_f32 v[48:49], v[48:49], v[146:147] op_sel_hi:[1,0]
	v_pk_mul_f32 v[50:51], v[50:51], v[146:147] op_sel_hi:[1,0]
	v_pk_mul_f32 v[44:45], v[44:45], v[146:147] op_sel_hi:[1,0]
	v_pk_mul_f32 v[46:47], v[46:47], v[146:147] op_sel_hi:[1,0]
	v_pk_mul_f32 v[16:17], v[16:17], v[146:147] op_sel_hi:[1,0]
	v_pk_mul_f32 v[18:19], v[18:19], v[146:147] op_sel_hi:[1,0]
	v_pk_mul_f32 v[12:13], v[12:13], v[146:147] op_sel_hi:[1,0]
	v_pk_mul_f32 v[14:15], v[14:15], v[146:147] op_sel_hi:[1,0]
	v_cvt_pk_f16_f32 v152, v48, v49
	v_cvt_pk_f16_f32 v153, v50, v51
	v_cvt_pk_f16_f32 v154, v44, v45
	v_cvt_pk_f16_f32 v155, v46, v47
	global_store_dwordx4 v133, v[152:155], s[6:7]
	v_cvt_pk_f16_f32 v156, v16, v17
	v_cvt_pk_f16_f32 v157, v18, v19
	v_cvt_pk_f16_f32 v158, v12, v13
	v_cvt_pk_f16_f32 v159, v14, v15
	global_store_dwordx4 v133, v[156:159], s[6:7] offset:64
	s_add_u32 s6, s4, 0xb0000
	s_addc_u32 s7, s5, 0
	v_pk_mul_f32 v[40:41], v[40:41], v[148:149] op_sel_hi:[1,0]
	v_pk_mul_f32 v[42:43], v[42:43], v[148:149] op_sel_hi:[1,0]
	v_pk_mul_f32 v[36:37], v[36:37], v[148:149] op_sel_hi:[1,0]
	v_pk_mul_f32 v[38:39], v[38:39], v[148:149] op_sel_hi:[1,0]
	v_pk_mul_f32 v[8:9], v[8:9], v[148:149] op_sel_hi:[1,0]
	v_pk_mul_f32 v[10:11], v[10:11], v[148:149] op_sel_hi:[1,0]
	v_pk_mul_f32 v[4:5], v[4:5], v[148:149] op_sel_hi:[1,0]
	v_pk_mul_f32 v[6:7], v[6:7], v[148:149] op_sel_hi:[1,0]
	v_cvt_pk_f16_f32 v160, v40, v41
	v_cvt_pk_f16_f32 v161, v42, v43
	v_cvt_pk_f16_f32 v162, v36, v37
	v_cvt_pk_f16_f32 v163, v38, v39
	global_store_dwordx4 v133, v[160:163], s[6:7]
	v_cvt_pk_f16_f32 v164, v8, v9
	v_cvt_pk_f16_f32 v165, v10, v11
	v_cvt_pk_f16_f32 v166, v4, v5
	v_cvt_pk_f16_f32 v167, v6, v7
	global_store_dwordx4 v133, v[164:167], s[6:7] offset:64
	s_branch .Lepi_done_g1
.Lepi_qs:
	s_and_b32 s0, s70, 1
	s_lshl_b32 s0, s0, 10
	v_add_u32_e32 v132, s0, v219
	ds_read_b32 v134, v132
	ds_read_b32 v136, v132 offset:64
	ds_read_b32 v138, v132 offset:128
	ds_read_b32 v140, v132 offset:192
	ds_read_b32 v142, v132 offset:512
	ds_read_b32 v144, v132 offset:576
	ds_read_b32 v146, v132 offset:640
	ds_read_b32 v148, v132 offset:704
	s_lshr_b32 s0, s69, 2
	s_and_b32 s1, s69, 1
	v_lshrrev_b32_e32 v2, 6, v187
	v_lshrrev_b32_e32 v133, 3, v220
	v_lshl_add_u32 v133, v2, 7, v133
	v_and_b32_e32 v2, 15, v187
	v_lshlrev_b32_e32 v133, 8, v133
	v_lshl_add_u32 v133, v2, 3, v133
	v_lshlrev_b32_e32 v133, 1, v133
	s_lshl_b32 s0, s0, 25
	s_lshl_b32 s1, s1, 14
	s_add_u32 s0, s0, s1
	s_lshl_b32 s1, s68, 18
	s_add_u32 s0, s0, s1
	s_add_u32 s4, s82, s0
	s_addc_u32 s5, s83, 0
	s_waitcnt lgkmcnt(0)
	s_mov_b32 s6, s4
	s_mov_b32 s7, s5
	v_pk_mul_f32 v[128:129], v[128:129], v[134:135] op_sel_hi:[1,0]
	v_pk_mul_f32 v[130:131], v[130:131], v[134:135] op_sel_hi:[1,0]
	v_pk_mul_f32 v[124:125], v[124:125], v[134:135] op_sel_hi:[1,0]
	v_pk_mul_f32 v[126:127], v[126:127], v[134:135] op_sel_hi:[1,0]
	v_pk_mul_f32 v[96:97], v[96:97], v[134:135] op_sel_hi:[1,0]
	v_pk_mul_f32 v[98:99], v[98:99], v[134:135] op_sel_hi:[1,0]
	v_pk_mul_f32 v[92:93], v[92:93], v[134:135] op_sel_hi:[1,0]
	v_pk_mul_f32 v[94:95], v[94:95], v[134:135] op_sel_hi:[1,0]
	v_pk_mul_f32 v[128:129], v[128:129], s[78:79] op_sel_hi:[1,0]
	v_pk_mul_f32 v[130:131], v[130:131], s[78:79] op_sel_hi:[1,0]
	v_pk_mul_f32 v[124:125], v[124:125], s[78:79] op_sel_hi:[1,0]
	v_pk_mul_f32 v[126:127], v[126:127], s[78:79] op_sel_hi:[1,0]
	v_pk_mul_f32 v[96:97], v[96:97], s[78:79] op_sel_hi:[1,0]
	v_pk_mul_f32 v[98:99], v[98:99], s[78:79] op_sel_hi:[1,0]
	v_pk_mul_f32 v[92:93], v[92:93], s[78:79] op_sel_hi:[1,0]
	v_pk_mul_f32 v[94:95], v[94:95], s[78:79] op_sel_hi:[1,0]
	v_cvt_pk_f16_f32 v152, v128, v129
	v_cvt_pk_f16_f32 v153, v130, v131
	v_cvt_pk_f16_f32 v154, v124, v125
	v_cvt_pk_f16_f32 v155, v126, v127
	global_store_dwordx4 v133, v[152:155], s[6:7]
	v_cvt_pk_f16_f32 v156, v96, v97
	v_cvt_pk_f16_f32 v157, v98, v99
	v_cvt_pk_f16_f32 v158, v92, v93
	v_cvt_pk_f16_f32 v159, v94, v95
	global_store_dwordx4 v133, v[156:159], s[6:7] offset:2048
	s_add_u32 s6, s4, 0x100
	s_addc_u32 s7, s5, 0
	v_pk_mul_f32 v[120:121], v[120:121], v[136:137] op_sel_hi:[1,0]
	v_pk_mul_f32 v[122:123], v[122:123], v[136:137] op_sel_hi:[1,0]
	v_pk_mul_f32 v[116:117], v[116:117], v[136:137] op_sel_hi:[1,0]
	v_pk_mul_f32 v[118:119], v[118:119], v[136:137] op_sel_hi:[1,0]
	v_pk_mul_f32 v[88:89], v[88:89], v[136:137] op_sel_hi:[1,0]
	v_pk_mul_f32 v[90:91], v[90:91], v[136:137] op_sel_hi:[1,0]
	v_pk_mul_f32 v[84:85], v[84:85], v[136:137] op_sel_hi:[1,0]
	v_pk_mul_f32 v[86:87], v[86:87], v[136:137] op_sel_hi:[1,0]
	v_pk_mul_f32 v[120:121], v[120:121], s[78:79] op_sel_hi:[1,0]
	v_pk_mul_f32 v[122:123], v[122:123], s[78:79] op_sel_hi:[1,0]
	v_pk_mul_f32 v[116:117], v[116:117], s[78:79] op_sel_hi:[1,0]
	v_pk_mul_f32 v[118:119], v[118:119], s[78:79] op_sel_hi:[1,0]
	v_pk_mul_f32 v[88:89], v[88:89], s[78:79] op_sel_hi:[1,0]
	v_pk_mul_f32 v[90:91], v[90:91], s[78:79] op_sel_hi:[1,0]
	v_pk_mul_f32 v[84:85], v[84:85], s[78:79] op_sel_hi:[1,0]
; #define GAS __attribute__((address_space(1)))
; __host__ __device__ __forceinline__ size_t bl512(size_t row, int col) { return ((row >> 5) * 64 + (size_t)(col >> 3)) * 256 + (row & 31) * 8 + (col & 7); }
;     __device__ __forceinline__ void operator()(const f32x4 (&acc)[2][2][4][2], const Unit& u, int wr, int wc, int fr, int fq) const {
;     ...
;                 } else if (sec == 0) {
; #pragma unroll
;                     for (int bj = 0; bj < 2; ++bj)
; #pragma unroll
;                         for (int n = 0; n < 2; ++n) v[bj][n] = v[bj][n] * QS;
;     ...
;                 GAS f16* rowp = isqg ? QG + (size_t)dsec * QG_SEC + bl512((size_t)row, cs) : KV + (size_t)row * KVW + dsec * 512 + cs;
; #pragma unroll
;                 for (int bj = 0; bj < 2; ++bj) {
;                     u32x4 w; w.x = pkh(v[bj][0][0], v[bj][0][1]); w.y = pkh(v[bj][0][2], v[bj][0][3]); w.z = pkh(v[bj][1][0], v[bj][1][1]); w.w = pkh(v[bj][1][2], v[bj][1][3]);
;                     *(GAS u32x4*)(rowp + bjstep * bj) = w;
;                 }
	v_pk_mul_f32 v[86:87], v[86:87], s[78:79] op_sel_hi:[1,0]
	v_cvt_pk_f16_f32 v160, v120, v121
	v_cvt_pk_f16_f32 v161, v122, v123
	v_cvt_pk_f16_f32 v162, v116, v117
	v_cvt_pk_f16_f32 v163, v118, v119
	global_store_dwordx4 v133, v[160:163], s[6:7]
	v_cvt_pk_f16_f32 v164, v88, v89
	v_cvt_pk_f16_f32 v165, v90, v91
	v_cvt_pk_f16_f32 v166, v84, v85
	v_cvt_pk_f16_f32 v167, v86, v87
	global_store_dwordx4 v133, v[164:167], s[6:7] offset:2048
	s_add_u32 s6, s4, 0x8000
	s_addc_u32 s7, s5, 0
	v_pk_mul_f32 v[112:113], v[112:113], v[138:139] op_sel_hi:[1,0]
	v_pk_mul_f32 v[114:115], v[114:115], v[138:139] op_sel_hi:[1,0]
	v_pk_mul_f32 v[108:109], v[108:109], v[138:139] op_sel_hi:[1,0]
	v_pk_mul_f32 v[110:111], v[110:111], v[138:139] op_sel_hi:[1,0]
	v_pk_mul_f32 v[80:81], v[80:81], v[138:139] op_sel_hi:[1,0]
	v_pk_mul_f32 v[82:83], v[82:83], v[138:139] op_sel_hi:[1,0]
	v_pk_mul_f32 v[76:77], v[76:77], v[138:139] op_sel_hi:[1,0]
	v_pk_mul_f32 v[78:79], v[78:79], v[138:139] op_sel_hi:[1,0]
	v_pk_mul_f32 v[112:113], v[112:113], s[78:79] op_sel_hi:[1,0]
	v_pk_mul_f32 v[114:115], v[114:115], s[78:79] op_sel_hi:[1,0]
	v_pk_mul_f32 v[108:109], v[108:109], s[78:79] op_sel_hi:[1,0]
	v_pk_mul_f32 v[110:111], v[110:111], s[78:79] op_sel_hi:[1,0]
	v_pk_mul_f32 v[80:81], v[80:81], s[78:79] op_sel_hi:[1,0]
	v_pk_mul_f32 v[82:83], v[82:83], s[78:79] op_sel_hi:[1,0]
	v_pk_mul_f32 v[76:77], v[76:77], s[78:79] op_sel_hi:[1,0]
	v_pk_mul_f32 v[78:79], v[78:79], s[78:79] op_sel_hi:[1,0]
	v_cvt_pk_f16_f32 v152, v112, v113
	v_cvt_pk_f16_f32 v153, v114, v115
	v_cvt_pk_f16_f32 v154, v108, v109
	v_cvt_pk_f16_f32 v155, v110, v111
	global_store_dwordx4 v133, v[152:155], s[6:7]
	v_cvt_pk_f16_f32 v156, v80, v81
	v_cvt_pk_f16_f32 v157, v82, v83
	v_cvt_pk_f16_f32 v158, v76, v77
	v_cvt_pk_f16_f32 v159, v78, v79
	global_store_dwordx4 v133, v[156:159], s[6:7] offset:2048
	s_add_u32 s6, s4, 0x8100
	s_addc_u32 s7, s5, 0
	v_pk_mul_f32 v[104:105], v[104:105], v[140:141] op_sel_hi:[1,0]
	v_pk_mul_f32 v[106:107], v[106:107], v[140:141] op_sel_hi:[1,0]
	v_pk_mul_f32 v[100:101], v[100:101], v[140:141] op_sel_hi:[1,0]
	v_pk_mul_f32 v[102:103], v[102:103], v[140:141] op_sel_hi:[1,0]
	v_pk_mul_f32 v[72:73], v[72:73], v[140:141] op_sel_hi:[1,0]
	v_pk_mul_f32 v[74:75], v[74:75], v[140:141] op_sel_hi:[1,0]
	v_pk_mul_f32 v[68:69], v[68:69], v[140:141] op_sel_hi:[1,0]
	v_pk_mul_f32 v[70:71], v[70:71], v[140:141] op_sel_hi:[1,0]
	v_pk_mul_f32 v[104:105], v[104:105], s[78:79] op_sel_hi:[1,0]
	v_pk_mul_f32 v[106:107], v[106:107], s[78:79] op_sel_hi:[1,0]
	v_pk_mul_f32 v[100:101], v[100:101], s[78:79] op_sel_hi:[1,0]
	v_pk_mul_f32 v[102:103], v[102:103], s[78:79] op_sel_hi:[1,0]
	v_pk_mul_f32 v[72:73], v[72:73], s[78:79] op_sel_hi:[1,0]
	v_pk_mul_f32 v[74:75], v[74:75], s[78:79] op_sel_hi:[1,0]
	v_pk_mul_f32 v[68:69], v[68:69], s[78:79] op_sel_hi:[1,0]
	v_pk_mul_f32 v[70:71], v[70:71], s[78:79] op_sel_hi:[1,0]
	v_cvt_pk_f16_f32 v160, v104, v105
	v_cvt_pk_f16_f32 v161, v106, v107
	v_cvt_pk_f16_f32 v162, v100, v101
	v_cvt_pk_f16_f32 v163, v102, v103
	global_store_dwordx4 v133, v[160:163], s[6:7]
	v_cvt_pk_f16_f32 v164, v72, v73
	v_cvt_pk_f16_f32 v165, v74, v75
	v_cvt_pk_f16_f32 v166, v68, v69
	v_cvt_pk_f16_f32 v167, v70, v71
	global_store_dwordx4 v133, v[164:167], s[6:7] offset:2048
	s_add_u32 s6, s4, 0x20000
	s_addc_u32 s7, s5, 0
	v_pk_mul_f32 v[64:65], v[64:65], v[142:143] op_sel_hi:[1,0]
	v_pk_mul_f32 v[66:67], v[66:67], v[142:143] op_sel_hi:[1,0]
	v_pk_mul_f32 v[60:61], v[60:61], v[142:143] op_sel_hi:[1,0]
	v_pk_mul_f32 v[62:63], v[62:63], v[142:143] op_sel_hi:[1,0]
	v_pk_mul_f32 v[32:33], v[32:33], v[142:143] op_sel_hi:[1,0]
	v_pk_mul_f32 v[34:35], v[34:35], v[142:143] op_sel_hi:[1,0]
	v_pk_mul_f32 v[28:29], v[28:29], v[142:143] op_sel_hi:[1,0]
	v_pk_mul_f32 v[30:31], v[30:31], v[142:143] op_sel_hi:[1,0]
	v_pk_mul_f32 v[64:65], v[64:65], s[78:79] op_sel_hi:[1,0]
	v_pk_mul_f32 v[66:67], v[66:67], s[78:79] op_sel_hi:[1,0]
	v_pk_mul_f32 v[60:61], v[60:61], s[78:79] op_sel_hi:[1,0]
	v_pk_mul_f32 v[62:63], v[62:63], s[78:79] op_sel_hi:[1,0]
	v_pk_mul_f32 v[32:33], v[32:33], s[78:79] op_sel_hi:[1,0]
	v_pk_mul_f32 v[34:35], v[34:35], s[78:79] op_sel_hi:[1,0]
	v_pk_mul_f32 v[28:29], v[28:29], s[78:79] op_sel_hi:[1,0]
	v_pk_mul_f32 v[30:31], v[30:31], s[78:79] op_sel_hi:[1,0]
	v_cvt_pk_f16_f32 v152, v64, v65
	v_cvt_pk_f16_f32 v153, v66, v67
	v_cvt_pk_f16_f32 v154, v60, v61
	v_cvt_pk_f16_f32 v155, v62, v63
	global_store_dwordx4 v133, v[152:155], s[6:7]
	v_cvt_pk_f16_f32 v156, v32, v33
	v_cvt_pk_f16_f32 v157, v34, v35
	v_cvt_pk_f16_f32 v158, v28, v29
	v_cvt_pk_f16_f32 v159, v30, v31
	global_store_dwordx4 v133, v[156:159], s[6:7] offset:2048
	s_add_u32 s6, s4, 0x20100
	s_addc_u32 s7, s5, 0
	v_pk_mul_f32 v[56:57], v[56:57], v[144:145] op_sel_hi:[1,0]
	v_pk_mul_f32 v[58:59], v[58:59], v[144:145] op_sel_hi:[1,0]
	v_pk_mul_f32 v[52:53], v[52:53], v[144:145] op_sel_hi:[1,0]
	v_pk_mul_f32 v[54:55], v[54:55], v[144:145] op_sel_hi:[1,0]
	v_pk_mul_f32 v[24:25], v[24:25], v[144:145] op_sel_hi:[1,0]
	v_pk_mul_f32 v[26:27], v[26:27], v[144:145] op_sel_hi:[1,0]
	v_pk_mul_f32 v[20:21], v[20:21], v[144:145] op_sel_hi:[1,0]
	v_pk_mul_f32 v[22:23], v[22:23], v[144:145] op_sel_hi:[1,0]
	v_pk_mul_f32 v[56:57], v[56:57], s[78:79] op_sel_hi:[1,0]
	v_pk_mul_f32 v[58:59], v[58:59], s[78:79] op_sel_hi:[1,0]
	v_pk_mul_f32 v[52:53], v[52:53], s[78:79] op_sel_hi:[1,0]
	v_pk_mul_f32 v[54:55], v[54:55], s[78:79] op_sel_hi:[1,0]
	v_pk_mul_f32 v[24:25], v[24:25], s[78:79] op_sel_hi:[1,0]
	v_pk_mul_f32 v[26:27], v[26:27], s[78:79] op_sel_hi:[1,0]
	v_pk_mul_f32 v[20:21], v[20:21], s[78:79] op_sel_hi:[1,0]
	v_pk_mul_f32 v[22:23], v[22:23], s[78:79] op_sel_hi:[1,0]
; #define GAS __attribute__((address_space(1)))
; __host__ __device__ __forceinline__ size_t bl512(size_t row, int col) { return ((row >> 5) * 64 + (size_t)(col >> 3)) * 256 + (row & 31) * 8 + (col & 7); }
; __device__ __forceinline__ float silu_f(float v) { return v * __builtin_amdgcn_rcpf(1.0f + __builtin_amdgcn_exp2f(-v * LOG2E)); }
;     __device__ __forceinline__ void operator()(const f32x4 (&acc)[2][2][4][2], const Unit& u, int wr, int wc, int fr, int fq) const {
;     ...
;                 } else if (sec == 0) {
; #pragma unroll
;                     for (int bj = 0; bj < 2; ++bj)
; #pragma unroll
;                         for (int n = 0; n < 2; ++n) v[bj][n] = v[bj][n] * QS;
;                 } else if (sec == 3 || sec == 7) {
; #pragma unroll
;                     for (int bj = 0; bj < 2; ++bj)
; #pragma unroll
;                         for (int n = 0; n < 2; ++n)
; #pragma unroll
;                             for (int e = 0; e < 4; ++e) v[bj][n][e] = silu_f(v[bj][n][e]);
;                 }
;                 GAS f16* rowp = isqg ? QG + (size_t)dsec * QG_SEC + bl512((size_t)row, cs) : KV + (size_t)row * KVW + dsec * 512 + cs;
; #pragma unroll
;                 for (int bj = 0; bj < 2; ++bj) {
;                     u32x4 w; w.x = pkh(v[bj][0][0], v[bj][0][1]); w.y = pkh(v[bj][0][2], v[bj][0][3]); w.z = pkh(v[bj][1][0], v[bj][1][1]); w.w = pkh(v[bj][1][2], v[bj][1][3]);
;                     *(GAS u32x4*)(rowp + bjstep * bj) = w;
;                 }
	v_cvt_pk_f16_f32 v160, v56, v57
	v_cvt_pk_f16_f32 v161, v58, v59
	v_cvt_pk_f16_f32 v162, v52, v53
	v_cvt_pk_f16_f32 v163, v54, v55
	global_store_dwordx4 v133, v[160:163], s[6:7]
	v_cvt_pk_f16_f32 v164, v24, v25
	v_cvt_pk_f16_f32 v165, v26, v27
	v_cvt_pk_f16_f32 v166, v20, v21
	v_cvt_pk_f16_f32 v167, v22, v23
	global_store_dwordx4 v133, v[164:167], s[6:7] offset:2048
	s_add_u32 s6, s4, 0x28000
	s_addc_u32 s7, s5, 0
	v_pk_mul_f32 v[48:49], v[48:49], v[146:147] op_sel_hi:[1,0]
	v_pk_mul_f32 v[50:51], v[50:51], v[146:147] op_sel_hi:[1,0]
	v_pk_mul_f32 v[44:45], v[44:45], v[146:147] op_sel_hi:[1,0]
	v_pk_mul_f32 v[46:47], v[46:47], v[146:147] op_sel_hi:[1,0]
	v_pk_mul_f32 v[16:17], v[16:17], v[146:147] op_sel_hi:[1,0]
	v_pk_mul_f32 v[18:19], v[18:19], v[146:147] op_sel_hi:[1,0]
	v_pk_mul_f32 v[12:13], v[12:13], v[146:147] op_sel_hi:[1,0]
	v_pk_mul_f32 v[14:15], v[14:15], v[146:147] op_sel_hi:[1,0]
	v_pk_mul_f32 v[48:49], v[48:49], s[78:79] op_sel_hi:[1,0]
	v_pk_mul_f32 v[50:51], v[50:51], s[78:79] op_sel_hi:[1,0]
	v_pk_mul_f32 v[44:45], v[44:45], s[78:79] op_sel_hi:[1,0]
	v_pk_mul_f32 v[46:47], v[46:47], s[78:79] op_sel_hi:[1,0]
	v_pk_mul_f32 v[16:17], v[16:17], s[78:79] op_sel_hi:[1,0]
	v_pk_mul_f32 v[18:19], v[18:19], s[78:79] op_sel_hi:[1,0]
	v_pk_mul_f32 v[12:13], v[12:13], s[78:79] op_sel_hi:[1,0]
	v_pk_mul_f32 v[14:15], v[14:15], s[78:79] op_sel_hi:[1,0]
	v_cvt_pk_f16_f32 v152, v48, v49
	v_cvt_pk_f16_f32 v153, v50, v51
	v_cvt_pk_f16_f32 v154, v44, v45
	v_cvt_pk_f16_f32 v155, v46, v47
	global_store_dwordx4 v133, v[152:155], s[6:7]
	v_cvt_pk_f16_f32 v156, v16, v17
	v_cvt_pk_f16_f32 v157, v18, v19
	v_cvt_pk_f16_f32 v158, v12, v13
	v_cvt_pk_f16_f32 v159, v14, v15
	global_store_dwordx4 v133, v[156:159], s[6:7] offset:2048
	s_add_u32 s6, s4, 0x28100
	s_addc_u32 s7, s5, 0
	v_pk_mul_f32 v[40:41], v[40:41], v[148:149] op_sel_hi:[1,0]
	v_pk_mul_f32 v[42:43], v[42:43], v[148:149] op_sel_hi:[1,0]
	v_pk_mul_f32 v[36:37], v[36:37], v[148:149] op_sel_hi:[1,0]
	v_pk_mul_f32 v[38:39], v[38:39], v[148:149] op_sel_hi:[1,0]
	v_pk_mul_f32 v[8:9], v[8:9], v[148:149] op_sel_hi:[1,0]
	v_pk_mul_f32 v[10:11], v[10:11], v[148:149] op_sel_hi:[1,0]
	v_pk_mul_f32 v[4:5], v[4:5], v[148:149] op_sel_hi:[1,0]
	v_pk_mul_f32 v[6:7], v[6:7], v[148:149] op_sel_hi:[1,0]
	v_pk_mul_f32 v[40:41], v[40:41], s[78:79] op_sel_hi:[1,0]
	v_pk_mul_f32 v[42:43], v[42:43], s[78:79] op_sel_hi:[1,0]
	v_pk_mul_f32 v[36:37], v[36:37], s[78:79] op_sel_hi:[1,0]
	v_pk_mul_f32 v[38:39], v[38:39], s[78:79] op_sel_hi:[1,0]
	v_pk_mul_f32 v[8:9], v[8:9], s[78:79] op_sel_hi:[1,0]
	v_pk_mul_f32 v[10:11], v[10:11], s[78:79] op_sel_hi:[1,0]
	v_pk_mul_f32 v[4:5], v[4:5], s[78:79] op_sel_hi:[1,0]
	v_pk_mul_f32 v[6:7], v[6:7], s[78:79] op_sel_hi:[1,0]
	v_cvt_pk_f16_f32 v160, v40, v41
	v_cvt_pk_f16_f32 v161, v42, v43
	v_cvt_pk_f16_f32 v162, v36, v37
	v_cvt_pk_f16_f32 v163, v38, v39
	global_store_dwordx4 v133, v[160:163], s[6:7]
	v_cvt_pk_f16_f32 v164, v8, v9
	v_cvt_pk_f16_f32 v165, v10, v11
	v_cvt_pk_f16_f32 v166, v4, v5
	v_cvt_pk_f16_f32 v167, v6, v7
	global_store_dwordx4 v133, v[164:167], s[6:7] offset:2048
	s_branch .Lepi_done_g1
.Lepi_silu:
	s_and_b32 s0, s70, 1
	s_lshl_b32 s0, s0, 10
	v_add_u32_e32 v132, s0, v219
	ds_read_b32 v134, v132
	ds_read_b32 v136, v132 offset:64
	ds_read_b32 v138, v132 offset:128
	ds_read_b32 v140, v132 offset:192
	ds_read_b32 v142, v132 offset:512
	ds_read_b32 v144, v132 offset:576
	ds_read_b32 v146, v132 offset:640
	ds_read_b32 v148, v132 offset:704
	s_lshr_b32 s0, s69, 2
	s_and_b32 s1, s69, 1
	v_lshrrev_b32_e32 v2, 6, v187
	v_lshrrev_b32_e32 v133, 3, v220
	v_lshl_add_u32 v133, v2, 7, v133
	v_and_b32_e32 v2, 15, v187
	v_lshlrev_b32_e32 v133, 8, v133
	v_lshl_add_u32 v133, v2, 3, v133
	v_lshlrev_b32_e32 v133, 1, v133
	s_lshl_b32 s0, s0, 25
	s_lshl_b32 s1, s1, 14
	s_add_u32 s0, s0, s1
	s_lshl_b32 s1, s68, 18
	s_add_u32 s0, s0, s1
	s_add_u32 s4, s82, s0
	s_addc_u32 s5, s83, 0
	s_waitcnt lgkmcnt(0)
	s_mov_b32 s6, s4
	s_mov_b32 s7, s5
	v_pk_mul_f32 v[128:129], v[128:129], v[134:135] op_sel_hi:[1,0]
	v_pk_mul_f32 v[130:131], v[130:131], v[134:135] op_sel_hi:[1,0]
	v_pk_mul_f32 v[124:125], v[124:125], v[134:135] op_sel_hi:[1,0]
	v_pk_mul_f32 v[126:127], v[126:127], v[134:135] op_sel_hi:[1,0]
	v_pk_mul_f32 v[96:97], v[96:97], v[134:135] op_sel_hi:[1,0]
	v_pk_mul_f32 v[98:99], v[98:99], v[134:135] op_sel_hi:[1,0]
	v_pk_mul_f32 v[92:93], v[92:93], v[134:135] op_sel_hi:[1,0]
	v_pk_mul_f32 v[94:95], v[94:95], v[134:135] op_sel_hi:[1,0]
	v_mul_f32_e32 v168, 0xbfb8aa3b, v128
	v_mul_f32_e32 v169, 0xbfb8aa3b, v129
	v_mul_f32_e32 v170, 0xbfb8aa3b, v130
	v_mul_f32_e32 v171, 0xbfb8aa3b, v131
	v_exp_f32_e32 v168, v168
	v_exp_f32_e32 v169, v169
	v_exp_f32_e32 v170, v170
	v_exp_f32_e32 v171, v171
	v_add_f32_e32 v168, 1.0, v168
	v_add_f32_e32 v169, 1.0, v169
	v_add_f32_e32 v170, 1.0, v170
	v_add_f32_e32 v171, 1.0, v171
	v_rcp_f32_e32 v168, v168
	v_rcp_f32_e32 v169, v169
	v_rcp_f32_e32 v170, v170
	v_rcp_f32_e32 v171, v171
	v_pk_mul_f32 v[128:129], v[128:129], v[168:169]
	v_pk_mul_f32 v[130:131], v[130:131], v[170:171]
	v_mul_f32_e32 v168, 0xbfb8aa3b, v124
	v_mul_f32_e32 v169, 0xbfb8aa3b, v125
	v_mul_f32_e32 v170, 0xbfb8aa3b, v126
	v_mul_f32_e32 v171, 0xbfb8aa3b, v127
	v_exp_f32_e32 v168, v168
	v_exp_f32_e32 v169, v169
	v_exp_f32_e32 v170, v170
	v_exp_f32_e32 v171, v171
	v_add_f32_e32 v168, 1.0, v168
	v_add_f32_e32 v169, 1.0, v169
	v_add_f32_e32 v170, 1.0, v170
	v_add_f32_e32 v171, 1.0, v171
	v_rcp_f32_e32 v168, v168
	v_rcp_f32_e32 v169, v169
	v_rcp_f32_e32 v170, v170
	v_rcp_f32_e32 v171, v171
	v_pk_mul_f32 v[124:125], v[124:125], v[168:169]
	v_pk_mul_f32 v[126:127], v[126:127], v[170:171]
; #define GAS __attribute__((address_space(1)))
; __host__ __device__ __forceinline__ size_t bl512(size_t row, int col) { return ((row >> 5) * 64 + (size_t)(col >> 3)) * 256 + (row & 31) * 8 + (col & 7); }
; __device__ __forceinline__ float silu_f(float v) { return v * __builtin_amdgcn_rcpf(1.0f + __builtin_amdgcn_exp2f(-v * LOG2E)); }
;     __device__ __forceinline__ void operator()(const f32x4 (&acc)[2][2][4][2], const Unit& u, int wr, int wc, int fr, int fq) const {
;     ...
;                 } else if (sec == 3 || sec == 7) {
; #pragma unroll
;                     for (int bj = 0; bj < 2; ++bj)
; #pragma unroll
;                         for (int n = 0; n < 2; ++n)
; #pragma unroll
;                             for (int e = 0; e < 4; ++e) v[bj][n][e] = silu_f(v[bj][n][e]);
;                 }
;                 GAS f16* rowp = isqg ? QG + (size_t)dsec * QG_SEC + bl512((size_t)row, cs) : KV + (size_t)row * KVW + dsec * 512 + cs;
; #pragma unroll
;                 for (int bj = 0; bj < 2; ++bj) {
;                     u32x4 w; w.x = pkh(v[bj][0][0], v[bj][0][1]); w.y = pkh(v[bj][0][2], v[bj][0][3]); w.z = pkh(v[bj][1][0], v[bj][1][1]); w.w = pkh(v[bj][1][2], v[bj][1][3]);
;                     *(GAS u32x4*)(rowp + bjstep * bj) = w;
;                 }
	v_mul_f32_e32 v168, 0xbfb8aa3b, v96
	v_mul_f32_e32 v169, 0xbfb8aa3b, v97
	v_mul_f32_e32 v170, 0xbfb8aa3b, v98
	v_mul_f32_e32 v171, 0xbfb8aa3b, v99
	v_exp_f32_e32 v168, v168
	v_exp_f32_e32 v169, v169
	v_exp_f32_e32 v170, v170
	v_exp_f32_e32 v171, v171
	v_add_f32_e32 v168, 1.0, v168
	v_add_f32_e32 v169, 1.0, v169
	v_add_f32_e32 v170, 1.0, v170
	v_add_f32_e32 v171, 1.0, v171
	v_rcp_f32_e32 v168, v168
	v_rcp_f32_e32 v169, v169
	v_rcp_f32_e32 v170, v170
	v_rcp_f32_e32 v171, v171
	v_pk_mul_f32 v[96:97], v[96:97], v[168:169]
	v_pk_mul_f32 v[98:99], v[98:99], v[170:171]
	v_mul_f32_e32 v168, 0xbfb8aa3b, v92
	v_mul_f32_e32 v169, 0xbfb8aa3b, v93
	v_mul_f32_e32 v170, 0xbfb8aa3b, v94
	v_mul_f32_e32 v171, 0xbfb8aa3b, v95
	v_exp_f32_e32 v168, v168
	v_exp_f32_e32 v169, v169
	v_exp_f32_e32 v170, v170
	v_exp_f32_e32 v171, v171
	v_add_f32_e32 v168, 1.0, v168
	v_add_f32_e32 v169, 1.0, v169
	v_add_f32_e32 v170, 1.0, v170
	v_add_f32_e32 v171, 1.0, v171
	v_rcp_f32_e32 v168, v168
	v_rcp_f32_e32 v169, v169
	v_rcp_f32_e32 v170, v170
	v_rcp_f32_e32 v171, v171
	v_pk_mul_f32 v[92:93], v[92:93], v[168:169]
	v_pk_mul_f32 v[94:95], v[94:95], v[170:171]
	v_cvt_pk_f16_f32 v152, v128, v129
	v_cvt_pk_f16_f32 v153, v130, v131
	v_cvt_pk_f16_f32 v154, v124, v125
	v_cvt_pk_f16_f32 v155, v126, v127
	global_store_dwordx4 v133, v[152:155], s[6:7]
	v_cvt_pk_f16_f32 v156, v96, v97
	v_cvt_pk_f16_f32 v157, v98, v99
	v_cvt_pk_f16_f32 v158, v92, v93
	v_cvt_pk_f16_f32 v159, v94, v95
	global_store_dwordx4 v133, v[156:159], s[6:7] offset:2048
	s_add_u32 s6, s4, 0x100
	s_addc_u32 s7, s5, 0
	v_pk_mul_f32 v[120:121], v[120:121], v[136:137] op_sel_hi:[1,0]
	v_pk_mul_f32 v[122:123], v[122:123], v[136:137] op_sel_hi:[1,0]
	v_pk_mul_f32 v[116:117], v[116:117], v[136:137] op_sel_hi:[1,0]
	v_pk_mul_f32 v[118:119], v[118:119], v[136:137] op_sel_hi:[1,0]
	v_pk_mul_f32 v[88:89], v[88:89], v[136:137] op_sel_hi:[1,0]
	v_pk_mul_f32 v[90:91], v[90:91], v[136:137] op_sel_hi:[1,0]
	v_pk_mul_f32 v[84:85], v[84:85], v[136:137] op_sel_hi:[1,0]
	v_pk_mul_f32 v[86:87], v[86:87], v[136:137] op_sel_hi:[1,0]
	v_mul_f32_e32 v168, 0xbfb8aa3b, v120
	v_mul_f32_e32 v169, 0xbfb8aa3b, v121
	v_mul_f32_e32 v170, 0xbfb8aa3b, v122
	v_mul_f32_e32 v171, 0xbfb8aa3b, v123
	v_exp_f32_e32 v168, v168
	v_exp_f32_e32 v169, v169
	v_exp_f32_e32 v170, v170
	v_exp_f32_e32 v171, v171
	v_add_f32_e32 v168, 1.0, v168
	v_add_f32_e32 v169, 1.0, v169
	v_add_f32_e32 v170, 1.0, v170
	v_add_f32_e32 v171, 1.0, v171
	v_rcp_f32_e32 v168, v168
	v_rcp_f32_e32 v169, v169
	v_rcp_f32_e32 v170, v170
	v_rcp_f32_e32 v171, v171
	v_pk_mul_f32 v[120:121], v[120:121], v[168:169]
	v_pk_mul_f32 v[122:123], v[122:123], v[170:171]
	v_mul_f32_e32 v168, 0xbfb8aa3b, v116
	v_mul_f32_e32 v169, 0xbfb8aa3b, v117
	v_mul_f32_e32 v170, 0xbfb8aa3b, v118
	v_mul_f32_e32 v171, 0xbfb8aa3b, v119
	v_exp_f32_e32 v168, v168
	v_exp_f32_e32 v169, v169
	v_exp_f32_e32 v170, v170
	v_exp_f32_e32 v171, v171
	v_add_f32_e32 v168, 1.0, v168
	v_add_f32_e32 v169, 1.0, v169
	v_add_f32_e32 v170, 1.0, v170
	v_add_f32_e32 v171, 1.0, v171
	v_rcp_f32_e32 v168, v168
	v_rcp_f32_e32 v169, v169
	v_rcp_f32_e32 v170, v170
	v_rcp_f32_e32 v171, v171
	v_pk_mul_f32 v[116:117], v[116:117], v[168:169]
	v_pk_mul_f32 v[118:119], v[118:119], v[170:171]
	v_mul_f32_e32 v168, 0xbfb8aa3b, v88
	v_mul_f32_e32 v169, 0xbfb8aa3b, v89
	v_mul_f32_e32 v170, 0xbfb8aa3b, v90
	v_mul_f32_e32 v171, 0xbfb8aa3b, v91
	v_exp_f32_e32 v168, v168
	v_exp_f32_e32 v169, v169
	v_exp_f32_e32 v170, v170
	v_exp_f32_e32 v171, v171
	v_add_f32_e32 v168, 1.0, v168
	v_add_f32_e32 v169, 1.0, v169
	v_add_f32_e32 v170, 1.0, v170
	v_add_f32_e32 v171, 1.0, v171
	v_rcp_f32_e32 v168, v168
	v_rcp_f32_e32 v169, v169
	v_rcp_f32_e32 v170, v170
	v_rcp_f32_e32 v171, v171
	v_pk_mul_f32 v[88:89], v[88:89], v[168:169]
	v_pk_mul_f32 v[90:91], v[90:91], v[170:171]
	v_mul_f32_e32 v168, 0xbfb8aa3b, v84
	v_mul_f32_e32 v169, 0xbfb8aa3b, v85
	v_mul_f32_e32 v170, 0xbfb8aa3b, v86
	v_mul_f32_e32 v171, 0xbfb8aa3b, v87
	v_exp_f32_e32 v168, v168
	v_exp_f32_e32 v169, v169
	v_exp_f32_e32 v170, v170
	v_exp_f32_e32 v171, v171
	v_add_f32_e32 v168, 1.0, v168
	v_add_f32_e32 v169, 1.0, v169
	v_add_f32_e32 v170, 1.0, v170
	v_add_f32_e32 v171, 1.0, v171
	v_rcp_f32_e32 v168, v168
	v_rcp_f32_e32 v169, v169
	v_rcp_f32_e32 v170, v170
	v_rcp_f32_e32 v171, v171
	v_pk_mul_f32 v[84:85], v[84:85], v[168:169]
	v_pk_mul_f32 v[86:87], v[86:87], v[170:171]
	v_cvt_pk_f16_f32 v160, v120, v121
	v_cvt_pk_f16_f32 v161, v122, v123
	v_cvt_pk_f16_f32 v162, v116, v117
	v_cvt_pk_f16_f32 v163, v118, v119
	global_store_dwordx4 v133, v[160:163], s[6:7]
	v_cvt_pk_f16_f32 v164, v88, v89
	v_cvt_pk_f16_f32 v165, v90, v91
	v_cvt_pk_f16_f32 v166, v84, v85
	v_cvt_pk_f16_f32 v167, v86, v87
	global_store_dwordx4 v133, v[164:167], s[6:7] offset:2048
	s_add_u32 s6, s4, 0x8000
	s_addc_u32 s7, s5, 0
	v_pk_mul_f32 v[112:113], v[112:113], v[138:139] op_sel_hi:[1,0]
	v_pk_mul_f32 v[114:115], v[114:115], v[138:139] op_sel_hi:[1,0]
	v_pk_mul_f32 v[108:109], v[108:109], v[138:139] op_sel_hi:[1,0]
	v_pk_mul_f32 v[110:111], v[110:111], v[138:139] op_sel_hi:[1,0]
	v_pk_mul_f32 v[80:81], v[80:81], v[138:139] op_sel_hi:[1,0]
	v_pk_mul_f32 v[82:83], v[82:83], v[138:139] op_sel_hi:[1,0]
	v_pk_mul_f32 v[76:77], v[76:77], v[138:139] op_sel_hi:[1,0]
	v_pk_mul_f32 v[78:79], v[78:79], v[138:139] op_sel_hi:[1,0]
	v_mul_f32_e32 v168, 0xbfb8aa3b, v112
	v_mul_f32_e32 v169, 0xbfb8aa3b, v113
	v_mul_f32_e32 v170, 0xbfb8aa3b, v114
	v_mul_f32_e32 v171, 0xbfb8aa3b, v115
	v_exp_f32_e32 v168, v168
	v_exp_f32_e32 v169, v169
	v_exp_f32_e32 v170, v170
	v_exp_f32_e32 v171, v171
	v_add_f32_e32 v168, 1.0, v168
	v_add_f32_e32 v169, 1.0, v169
	v_add_f32_e32 v170, 1.0, v170
; #define GAS __attribute__((address_space(1)))
; __host__ __device__ __forceinline__ size_t bl512(size_t row, int col) { return ((row >> 5) * 64 + (size_t)(col >> 3)) * 256 + (row & 31) * 8 + (col & 7); }
; __device__ __forceinline__ float silu_f(float v) { return v * __builtin_amdgcn_rcpf(1.0f + __builtin_amdgcn_exp2f(-v * LOG2E)); }
;     __device__ __forceinline__ void operator()(const f32x4 (&acc)[2][2][4][2], const Unit& u, int wr, int wc, int fr, int fq) const {
;     ...
;                 } else if (sec == 3 || sec == 7) {
; #pragma unroll
;                     for (int bj = 0; bj < 2; ++bj)
; #pragma unroll
;                         for (int n = 0; n < 2; ++n)
; #pragma unroll
;                             for (int e = 0; e < 4; ++e) v[bj][n][e] = silu_f(v[bj][n][e]);
;                 }
;                 GAS f16* rowp = isqg ? QG + (size_t)dsec * QG_SEC + bl512((size_t)row, cs) : KV + (size_t)row * KVW + dsec * 512 + cs;
; #pragma unroll
;                 for (int bj = 0; bj < 2; ++bj) {
;                     u32x4 w; w.x = pkh(v[bj][0][0], v[bj][0][1]); w.y = pkh(v[bj][0][2], v[bj][0][3]); w.z = pkh(v[bj][1][0], v[bj][1][1]); w.w = pkh(v[bj][1][2], v[bj][1][3]);
;                     *(GAS u32x4*)(rowp + bjstep * bj) = w;
;                 }
	v_add_f32_e32 v171, 1.0, v171
	v_rcp_f32_e32 v168, v168
	v_rcp_f32_e32 v169, v169
	v_rcp_f32_e32 v170, v170
	v_rcp_f32_e32 v171, v171
	v_pk_mul_f32 v[112:113], v[112:113], v[168:169]
	v_pk_mul_f32 v[114:115], v[114:115], v[170:171]
	v_mul_f32_e32 v168, 0xbfb8aa3b, v108
	v_mul_f32_e32 v169, 0xbfb8aa3b, v109
	v_mul_f32_e32 v170, 0xbfb8aa3b, v110
	v_mul_f32_e32 v171, 0xbfb8aa3b, v111
	v_exp_f32_e32 v168, v168
	v_exp_f32_e32 v169, v169
	v_exp_f32_e32 v170, v170
	v_exp_f32_e32 v171, v171
	v_add_f32_e32 v168, 1.0, v168
	v_add_f32_e32 v169, 1.0, v169
	v_add_f32_e32 v170, 1.0, v170
	v_add_f32_e32 v171, 1.0, v171
	v_rcp_f32_e32 v168, v168
	v_rcp_f32_e32 v169, v169
	v_rcp_f32_e32 v170, v170
	v_rcp_f32_e32 v171, v171
	v_pk_mul_f32 v[108:109], v[108:109], v[168:169]
	v_pk_mul_f32 v[110:111], v[110:111], v[170:171]
	v_mul_f32_e32 v168, 0xbfb8aa3b, v80
	v_mul_f32_e32 v169, 0xbfb8aa3b, v81
	v_mul_f32_e32 v170, 0xbfb8aa3b, v82
	v_mul_f32_e32 v171, 0xbfb8aa3b, v83
	v_exp_f32_e32 v168, v168
	v_exp_f32_e32 v169, v169
	v_exp_f32_e32 v170, v170
	v_exp_f32_e32 v171, v171
	v_add_f32_e32 v168, 1.0, v168
	v_add_f32_e32 v169, 1.0, v169
	v_add_f32_e32 v170, 1.0, v170
	v_add_f32_e32 v171, 1.0, v171
	v_rcp_f32_e32 v168, v168
	v_rcp_f32_e32 v169, v169
	v_rcp_f32_e32 v170, v170
	v_rcp_f32_e32 v171, v171
	v_pk_mul_f32 v[80:81], v[80:81], v[168:169]
	v_pk_mul_f32 v[82:83], v[82:83], v[170:171]
	v_mul_f32_e32 v168, 0xbfb8aa3b, v76
	v_mul_f32_e32 v169, 0xbfb8aa3b, v77
	v_mul_f32_e32 v170, 0xbfb8aa3b, v78
	v_mul_f32_e32 v171, 0xbfb8aa3b, v79
	v_exp_f32_e32 v168, v168
	v_exp_f32_e32 v169, v169
	v_exp_f32_e32 v170, v170
	v_exp_f32_e32 v171, v171
	v_add_f32_e32 v168, 1.0, v168
	v_add_f32_e32 v169, 1.0, v169
	v_add_f32_e32 v170, 1.0, v170
	v_add_f32_e32 v171, 1.0, v171
	v_rcp_f32_e32 v168, v168
	v_rcp_f32_e32 v169, v169
	v_rcp_f32_e32 v170, v170
	v_rcp_f32_e32 v171, v171
	v_pk_mul_f32 v[76:77], v[76:77], v[168:169]
	v_pk_mul_f32 v[78:79], v[78:79], v[170:171]
	v_cvt_pk_f16_f32 v152, v112, v113
	v_cvt_pk_f16_f32 v153, v114, v115
	v_cvt_pk_f16_f32 v154, v108, v109
	v_cvt_pk_f16_f32 v155, v110, v111
	global_store_dwordx4 v133, v[152:155], s[6:7]
	v_cvt_pk_f16_f32 v156, v80, v81
	v_cvt_pk_f16_f32 v157, v82, v83
	v_cvt_pk_f16_f32 v158, v76, v77
	v_cvt_pk_f16_f32 v159, v78, v79
	global_store_dwordx4 v133, v[156:159], s[6:7] offset:2048
	s_add_u32 s6, s4, 0x8100
	s_addc_u32 s7, s5, 0
	v_pk_mul_f32 v[104:105], v[104:105], v[140:141] op_sel_hi:[1,0]
	v_pk_mul_f32 v[106:107], v[106:107], v[140:141] op_sel_hi:[1,0]
	v_pk_mul_f32 v[100:101], v[100:101], v[140:141] op_sel_hi:[1,0]
	v_pk_mul_f32 v[102:103], v[102:103], v[140:141] op_sel_hi:[1,0]
	v_pk_mul_f32 v[72:73], v[72:73], v[140:141] op_sel_hi:[1,0]
	v_pk_mul_f32 v[74:75], v[74:75], v[140:141] op_sel_hi:[1,0]
	v_pk_mul_f32 v[68:69], v[68:69], v[140:141] op_sel_hi:[1,0]
	v_pk_mul_f32 v[70:71], v[70:71], v[140:141] op_sel_hi:[1,0]
	v_mul_f32_e32 v168, 0xbfb8aa3b, v104
	v_mul_f32_e32 v169, 0xbfb8aa3b, v105
	v_mul_f32_e32 v170, 0xbfb8aa3b, v106
	v_mul_f32_e32 v171, 0xbfb8aa3b, v107
	v_exp_f32_e32 v168, v168
	v_exp_f32_e32 v169, v169
	v_exp_f32_e32 v170, v170
	v_exp_f32_e32 v171, v171
	v_add_f32_e32 v168, 1.0, v168
	v_add_f32_e32 v169, 1.0, v169
	v_add_f32_e32 v170, 1.0, v170
	v_add_f32_e32 v171, 1.0, v171
	v_rcp_f32_e32 v168, v168
	v_rcp_f32_e32 v169, v169
	v_rcp_f32_e32 v170, v170
	v_rcp_f32_e32 v171, v171
	v_pk_mul_f32 v[104:105], v[104:105], v[168:169]
	v_pk_mul_f32 v[106:107], v[106:107], v[170:171]
	v_mul_f32_e32 v168, 0xbfb8aa3b, v100
	v_mul_f32_e32 v169, 0xbfb8aa3b, v101
	v_mul_f32_e32 v170, 0xbfb8aa3b, v102
	v_mul_f32_e32 v171, 0xbfb8aa3b, v103
	v_exp_f32_e32 v168, v168
	v_exp_f32_e32 v169, v169
	v_exp_f32_e32 v170, v170
	v_exp_f32_e32 v171, v171
	v_add_f32_e32 v168, 1.0, v168
	v_add_f32_e32 v169, 1.0, v169
	v_add_f32_e32 v170, 1.0, v170
	v_add_f32_e32 v171, 1.0, v171
	v_rcp_f32_e32 v168, v168
	v_rcp_f32_e32 v169, v169
	v_rcp_f32_e32 v170, v170
	v_rcp_f32_e32 v171, v171
	v_pk_mul_f32 v[100:101], v[100:101], v[168:169]
	v_pk_mul_f32 v[102:103], v[102:103], v[170:171]
	v_mul_f32_e32 v168, 0xbfb8aa3b, v72
	v_mul_f32_e32 v169, 0xbfb8aa3b, v73
	v_mul_f32_e32 v170, 0xbfb8aa3b, v74
	v_mul_f32_e32 v171, 0xbfb8aa3b, v75
	v_exp_f32_e32 v168, v168
	v_exp_f32_e32 v169, v169
	v_exp_f32_e32 v170, v170
	v_exp_f32_e32 v171, v171
	v_add_f32_e32 v168, 1.0, v168
	v_add_f32_e32 v169, 1.0, v169
	v_add_f32_e32 v170, 1.0, v170
	v_add_f32_e32 v171, 1.0, v171
	v_rcp_f32_e32 v168, v168
	v_rcp_f32_e32 v169, v169
	v_rcp_f32_e32 v170, v170
	v_rcp_f32_e32 v171, v171
	v_pk_mul_f32 v[72:73], v[72:73], v[168:169]
	v_pk_mul_f32 v[74:75], v[74:75], v[170:171]
	v_mul_f32_e32 v168, 0xbfb8aa3b, v68
	v_mul_f32_e32 v169, 0xbfb8aa3b, v69
	v_mul_f32_e32 v170, 0xbfb8aa3b, v70
	v_mul_f32_e32 v171, 0xbfb8aa3b, v71
	v_exp_f32_e32 v168, v168
	v_exp_f32_e32 v169, v169
	v_exp_f32_e32 v170, v170
	v_exp_f32_e32 v171, v171
	v_add_f32_e32 v168, 1.0, v168
	v_add_f32_e32 v169, 1.0, v169
	v_add_f32_e32 v170, 1.0, v170
	v_add_f32_e32 v171, 1.0, v171
	v_rcp_f32_e32 v168, v168
	v_rcp_f32_e32 v169, v169
	v_rcp_f32_e32 v170, v170
	v_rcp_f32_e32 v171, v171
	v_pk_mul_f32 v[68:69], v[68:69], v[168:169]
	v_pk_mul_f32 v[70:71], v[70:71], v[170:171]
	v_cvt_pk_f16_f32 v160, v104, v105
	v_cvt_pk_f16_f32 v161, v106, v107
	v_cvt_pk_f16_f32 v162, v100, v101
	v_cvt_pk_f16_f32 v163, v102, v103
	global_store_dwordx4 v133, v[160:163], s[6:7]
	v_cvt_pk_f16_f32 v164, v72, v73
	v_cvt_pk_f16_f32 v165, v74, v75
	v_cvt_pk_f16_f32 v166, v68, v69
	v_cvt_pk_f16_f32 v167, v70, v71
	global_store_dwordx4 v133, v[164:167], s[6:7] offset:2048
	s_add_u32 s6, s4, 0x20000
	s_addc_u32 s7, s5, 0
; #define GAS __attribute__((address_space(1)))
; __host__ __device__ __forceinline__ size_t bl512(size_t row, int col) { return ((row >> 5) * 64 + (size_t)(col >> 3)) * 256 + (row & 31) * 8 + (col & 7); }
; __device__ __forceinline__ float silu_f(float v) { return v * __builtin_amdgcn_rcpf(1.0f + __builtin_amdgcn_exp2f(-v * LOG2E)); }
;     __device__ __forceinline__ void operator()(const f32x4 (&acc)[2][2][4][2], const Unit& u, int wr, int wc, int fr, int fq) const {
;     ...
;                 } else if (sec == 3 || sec == 7) {
; #pragma unroll
;                     for (int bj = 0; bj < 2; ++bj)
; #pragma unroll
;                         for (int n = 0; n < 2; ++n)
; #pragma unroll
;                             for (int e = 0; e < 4; ++e) v[bj][n][e] = silu_f(v[bj][n][e]);
;                 }
;                 GAS f16* rowp = isqg ? QG + (size_t)dsec * QG_SEC + bl512((size_t)row, cs) : KV + (size_t)row * KVW + dsec * 512 + cs;
; #pragma unroll
;                 for (int bj = 0; bj < 2; ++bj) {
;                     u32x4 w; w.x = pkh(v[bj][0][0], v[bj][0][1]); w.y = pkh(v[bj][0][2], v[bj][0][3]); w.z = pkh(v[bj][1][0], v[bj][1][1]); w.w = pkh(v[bj][1][2], v[bj][1][3]);
;                     *(GAS u32x4*)(rowp + bjstep * bj) = w;
;                 }
	v_pk_mul_f32 v[64:65], v[64:65], v[142:143] op_sel_hi:[1,0]
	v_pk_mul_f32 v[66:67], v[66:67], v[142:143] op_sel_hi:[1,0]
	v_pk_mul_f32 v[60:61], v[60:61], v[142:143] op_sel_hi:[1,0]
	v_pk_mul_f32 v[62:63], v[62:63], v[142:143] op_sel_hi:[1,0]
	v_pk_mul_f32 v[32:33], v[32:33], v[142:143] op_sel_hi:[1,0]
	v_pk_mul_f32 v[34:35], v[34:35], v[142:143] op_sel_hi:[1,0]
	v_pk_mul_f32 v[28:29], v[28:29], v[142:143] op_sel_hi:[1,0]
	v_pk_mul_f32 v[30:31], v[30:31], v[142:143] op_sel_hi:[1,0]
	v_mul_f32_e32 v168, 0xbfb8aa3b, v64
	v_mul_f32_e32 v169, 0xbfb8aa3b, v65
	v_mul_f32_e32 v170, 0xbfb8aa3b, v66
	v_mul_f32_e32 v171, 0xbfb8aa3b, v67
	v_exp_f32_e32 v168, v168
	v_exp_f32_e32 v169, v169
	v_exp_f32_e32 v170, v170
	v_exp_f32_e32 v171, v171
	v_add_f32_e32 v168, 1.0, v168
	v_add_f32_e32 v169, 1.0, v169
	v_add_f32_e32 v170, 1.0, v170
	v_add_f32_e32 v171, 1.0, v171
	v_rcp_f32_e32 v168, v168
	v_rcp_f32_e32 v169, v169
	v_rcp_f32_e32 v170, v170
	v_rcp_f32_e32 v171, v171
	v_pk_mul_f32 v[64:65], v[64:65], v[168:169]
	v_pk_mul_f32 v[66:67], v[66:67], v[170:171]
	v_mul_f32_e32 v168, 0xbfb8aa3b, v60
	v_mul_f32_e32 v169, 0xbfb8aa3b, v61
	v_mul_f32_e32 v170, 0xbfb8aa3b, v62
	v_mul_f32_e32 v171, 0xbfb8aa3b, v63
	v_exp_f32_e32 v168, v168
	v_exp_f32_e32 v169, v169
	v_exp_f32_e32 v170, v170
	v_exp_f32_e32 v171, v171
	v_add_f32_e32 v168, 1.0, v168
	v_add_f32_e32 v169, 1.0, v169
	v_add_f32_e32 v170, 1.0, v170
	v_add_f32_e32 v171, 1.0, v171
	v_rcp_f32_e32 v168, v168
	v_rcp_f32_e32 v169, v169
	v_rcp_f32_e32 v170, v170
	v_rcp_f32_e32 v171, v171
	v_pk_mul_f32 v[60:61], v[60:61], v[168:169]
	v_pk_mul_f32 v[62:63], v[62:63], v[170:171]
	v_mul_f32_e32 v168, 0xbfb8aa3b, v32
	v_mul_f32_e32 v169, 0xbfb8aa3b, v33
	v_mul_f32_e32 v170, 0xbfb8aa3b, v34
	v_mul_f32_e32 v171, 0xbfb8aa3b, v35
	v_exp_f32_e32 v168, v168
	v_exp_f32_e32 v169, v169
	v_exp_f32_e32 v170, v170
	v_exp_f32_e32 v171, v171
	v_add_f32_e32 v168, 1.0, v168
	v_add_f32_e32 v169, 1.0, v169
	v_add_f32_e32 v170, 1.0, v170
	v_add_f32_e32 v171, 1.0, v171
	v_rcp_f32_e32 v168, v168
	v_rcp_f32_e32 v169, v169
	v_rcp_f32_e32 v170, v170
	v_rcp_f32_e32 v171, v171
	v_pk_mul_f32 v[32:33], v[32:33], v[168:169]
	v_pk_mul_f32 v[34:35], v[34:35], v[170:171]
	v_mul_f32_e32 v168, 0xbfb8aa3b, v28
	v_mul_f32_e32 v169, 0xbfb8aa3b, v29
	v_mul_f32_e32 v170, 0xbfb8aa3b, v30
	v_mul_f32_e32 v171, 0xbfb8aa3b, v31
	v_exp_f32_e32 v168, v168
	v_exp_f32_e32 v169, v169
	v_exp_f32_e32 v170, v170
	v_exp_f32_e32 v171, v171
	v_add_f32_e32 v168, 1.0, v168
	v_add_f32_e32 v169, 1.0, v169
	v_add_f32_e32 v170, 1.0, v170
	v_add_f32_e32 v171, 1.0, v171
	v_rcp_f32_e32 v168, v168
	v_rcp_f32_e32 v169, v169
	v_rcp_f32_e32 v170, v170
	v_rcp_f32_e32 v171, v171
	v_pk_mul_f32 v[28:29], v[28:29], v[168:169]
	v_pk_mul_f32 v[30:31], v[30:31], v[170:171]
	v_cvt_pk_f16_f32 v152, v64, v65
	v_cvt_pk_f16_f32 v153, v66, v67
	v_cvt_pk_f16_f32 v154, v60, v61
	v_cvt_pk_f16_f32 v155, v62, v63
	global_store_dwordx4 v133, v[152:155], s[6:7]
	v_cvt_pk_f16_f32 v156, v32, v33
	v_cvt_pk_f16_f32 v157, v34, v35
	v_cvt_pk_f16_f32 v158, v28, v29
	v_cvt_pk_f16_f32 v159, v30, v31
	global_store_dwordx4 v133, v[156:159], s[6:7] offset:2048
	s_add_u32 s6, s4, 0x20100
	s_addc_u32 s7, s5, 0
	v_pk_mul_f32 v[56:57], v[56:57], v[144:145] op_sel_hi:[1,0]
	v_pk_mul_f32 v[58:59], v[58:59], v[144:145] op_sel_hi:[1,0]
	v_pk_mul_f32 v[52:53], v[52:53], v[144:145] op_sel_hi:[1,0]
	v_pk_mul_f32 v[54:55], v[54:55], v[144:145] op_sel_hi:[1,0]
	v_pk_mul_f32 v[24:25], v[24:25], v[144:145] op_sel_hi:[1,0]
	v_pk_mul_f32 v[26:27], v[26:27], v[144:145] op_sel_hi:[1,0]
	v_pk_mul_f32 v[20:21], v[20:21], v[144:145] op_sel_hi:[1,0]
	v_pk_mul_f32 v[22:23], v[22:23], v[144:145] op_sel_hi:[1,0]
	v_mul_f32_e32 v168, 0xbfb8aa3b, v56
	v_mul_f32_e32 v169, 0xbfb8aa3b, v57
	v_mul_f32_e32 v170, 0xbfb8aa3b, v58
	v_mul_f32_e32 v171, 0xbfb8aa3b, v59
	v_exp_f32_e32 v168, v168
	v_exp_f32_e32 v169, v169
	v_exp_f32_e32 v170, v170
	v_exp_f32_e32 v171, v171
	v_add_f32_e32 v168, 1.0, v168
	v_add_f32_e32 v169, 1.0, v169
	v_add_f32_e32 v170, 1.0, v170
	v_add_f32_e32 v171, 1.0, v171
	v_rcp_f32_e32 v168, v168
	v_rcp_f32_e32 v169, v169
	v_rcp_f32_e32 v170, v170
	v_rcp_f32_e32 v171, v171
	v_pk_mul_f32 v[56:57], v[56:57], v[168:169]
	v_pk_mul_f32 v[58:59], v[58:59], v[170:171]
	v_mul_f32_e32 v168, 0xbfb8aa3b, v52
	v_mul_f32_e32 v169, 0xbfb8aa3b, v53
	v_mul_f32_e32 v170, 0xbfb8aa3b, v54
	v_mul_f32_e32 v171, 0xbfb8aa3b, v55
	v_exp_f32_e32 v168, v168
	v_exp_f32_e32 v169, v169
	v_exp_f32_e32 v170, v170
	v_exp_f32_e32 v171, v171
	v_add_f32_e32 v168, 1.0, v168
	v_add_f32_e32 v169, 1.0, v169
	v_add_f32_e32 v170, 1.0, v170
	v_add_f32_e32 v171, 1.0, v171
	v_rcp_f32_e32 v168, v168
	v_rcp_f32_e32 v169, v169
	v_rcp_f32_e32 v170, v170
	v_rcp_f32_e32 v171, v171
	v_pk_mul_f32 v[52:53], v[52:53], v[168:169]
	v_pk_mul_f32 v[54:55], v[54:55], v[170:171]
	v_mul_f32_e32 v168, 0xbfb8aa3b, v24
	v_mul_f32_e32 v169, 0xbfb8aa3b, v25
	v_mul_f32_e32 v170, 0xbfb8aa3b, v26
	v_mul_f32_e32 v171, 0xbfb8aa3b, v27
	v_exp_f32_e32 v168, v168
	v_exp_f32_e32 v169, v169
	v_exp_f32_e32 v170, v170
	v_exp_f32_e32 v171, v171
	v_add_f32_e32 v168, 1.0, v168
	v_add_f32_e32 v169, 1.0, v169
	v_add_f32_e32 v170, 1.0, v170
	v_add_f32_e32 v171, 1.0, v171
	v_rcp_f32_e32 v168, v168
	v_rcp_f32_e32 v169, v169
	v_rcp_f32_e32 v170, v170
	v_rcp_f32_e32 v171, v171
	v_pk_mul_f32 v[24:25], v[24:25], v[168:169]
	v_pk_mul_f32 v[26:27], v[26:27], v[170:171]
	v_mul_f32_e32 v168, 0xbfb8aa3b, v20
	v_mul_f32_e32 v169, 0xbfb8aa3b, v21
	v_mul_f32_e32 v170, 0xbfb8aa3b, v22
	v_mul_f32_e32 v171, 0xbfb8aa3b, v23
	v_exp_f32_e32 v168, v168
	v_exp_f32_e32 v169, v169
	v_exp_f32_e32 v170, v170
	v_exp_f32_e32 v171, v171
; #define GAS __attribute__((address_space(1)))
; __host__ __device__ __forceinline__ size_t bl512(size_t row, int col) { return ((row >> 5) * 64 + (size_t)(col >> 3)) * 256 + (row & 31) * 8 + (col & 7); }
; __device__ __forceinline__ float silu_f(float v) { return v * __builtin_amdgcn_rcpf(1.0f + __builtin_amdgcn_exp2f(-v * LOG2E)); }
;     __device__ __forceinline__ void operator()(const f32x4 (&acc)[2][2][4][2], const Unit& u, int wr, int wc, int fr, int fq) const {
;     ...
;                 } else if (sec == 3 || sec == 7) {
; #pragma unroll
;                     for (int bj = 0; bj < 2; ++bj)
; #pragma unroll
;                         for (int n = 0; n < 2; ++n)
; #pragma unroll
;                             for (int e = 0; e < 4; ++e) v[bj][n][e] = silu_f(v[bj][n][e]);
;                 }
;                 GAS f16* rowp = isqg ? QG + (size_t)dsec * QG_SEC + bl512((size_t)row, cs) : KV + (size_t)row * KVW + dsec * 512 + cs;
; #pragma unroll
;                 for (int bj = 0; bj < 2; ++bj) {
;                     u32x4 w; w.x = pkh(v[bj][0][0], v[bj][0][1]); w.y = pkh(v[bj][0][2], v[bj][0][3]); w.z = pkh(v[bj][1][0], v[bj][1][1]); w.w = pkh(v[bj][1][2], v[bj][1][3]);
;                     *(GAS u32x4*)(rowp + bjstep * bj) = w;
;                 }
	v_add_f32_e32 v168, 1.0, v168
	v_add_f32_e32 v169, 1.0, v169
	v_add_f32_e32 v170, 1.0, v170
	v_add_f32_e32 v171, 1.0, v171
	v_rcp_f32_e32 v168, v168
	v_rcp_f32_e32 v169, v169
	v_rcp_f32_e32 v170, v170
	v_rcp_f32_e32 v171, v171
	v_pk_mul_f32 v[20:21], v[20:21], v[168:169]
	v_pk_mul_f32 v[22:23], v[22:23], v[170:171]
	v_cvt_pk_f16_f32 v160, v56, v57
	v_cvt_pk_f16_f32 v161, v58, v59
	v_cvt_pk_f16_f32 v162, v52, v53
	v_cvt_pk_f16_f32 v163, v54, v55
	global_store_dwordx4 v133, v[160:163], s[6:7]
	v_cvt_pk_f16_f32 v164, v24, v25
	v_cvt_pk_f16_f32 v165, v26, v27
	v_cvt_pk_f16_f32 v166, v20, v21
	v_cvt_pk_f16_f32 v167, v22, v23
	global_store_dwordx4 v133, v[164:167], s[6:7] offset:2048
	s_add_u32 s6, s4, 0x28000
	s_addc_u32 s7, s5, 0
	v_pk_mul_f32 v[48:49], v[48:49], v[146:147] op_sel_hi:[1,0]
	v_pk_mul_f32 v[50:51], v[50:51], v[146:147] op_sel_hi:[1,0]
	v_pk_mul_f32 v[44:45], v[44:45], v[146:147] op_sel_hi:[1,0]
	v_pk_mul_f32 v[46:47], v[46:47], v[146:147] op_sel_hi:[1,0]
	v_pk_mul_f32 v[16:17], v[16:17], v[146:147] op_sel_hi:[1,0]
	v_pk_mul_f32 v[18:19], v[18:19], v[146:147] op_sel_hi:[1,0]
	v_pk_mul_f32 v[12:13], v[12:13], v[146:147] op_sel_hi:[1,0]
	v_pk_mul_f32 v[14:15], v[14:15], v[146:147] op_sel_hi:[1,0]
	v_mul_f32_e32 v168, 0xbfb8aa3b, v48
	v_mul_f32_e32 v169, 0xbfb8aa3b, v49
	v_mul_f32_e32 v170, 0xbfb8aa3b, v50
	v_mul_f32_e32 v171, 0xbfb8aa3b, v51
	v_exp_f32_e32 v168, v168
	v_exp_f32_e32 v169, v169
	v_exp_f32_e32 v170, v170
	v_exp_f32_e32 v171, v171
	v_add_f32_e32 v168, 1.0, v168
	v_add_f32_e32 v169, 1.0, v169
	v_add_f32_e32 v170, 1.0, v170
	v_add_f32_e32 v171, 1.0, v171
	v_rcp_f32_e32 v168, v168
	v_rcp_f32_e32 v169, v169
	v_rcp_f32_e32 v170, v170
	v_rcp_f32_e32 v171, v171
	v_pk_mul_f32 v[48:49], v[48:49], v[168:169]
	v_pk_mul_f32 v[50:51], v[50:51], v[170:171]
	v_mul_f32_e32 v168, 0xbfb8aa3b, v44
	v_mul_f32_e32 v169, 0xbfb8aa3b, v45
	v_mul_f32_e32 v170, 0xbfb8aa3b, v46
	v_mul_f32_e32 v171, 0xbfb8aa3b, v47
	v_exp_f32_e32 v168, v168
	v_exp_f32_e32 v169, v169
	v_exp_f32_e32 v170, v170
	v_exp_f32_e32 v171, v171
	v_add_f32_e32 v168, 1.0, v168
	v_add_f32_e32 v169, 1.0, v169
	v_add_f32_e32 v170, 1.0, v170
	v_add_f32_e32 v171, 1.0, v171
	v_rcp_f32_e32 v168, v168
	v_rcp_f32_e32 v169, v169
	v_rcp_f32_e32 v170, v170
	v_rcp_f32_e32 v171, v171
	v_pk_mul_f32 v[44:45], v[44:45], v[168:169]
	v_pk_mul_f32 v[46:47], v[46:47], v[170:171]
	v_mul_f32_e32 v168, 0xbfb8aa3b, v16
	v_mul_f32_e32 v169, 0xbfb8aa3b, v17
	v_mul_f32_e32 v170, 0xbfb8aa3b, v18
	v_mul_f32_e32 v171, 0xbfb8aa3b, v19
	v_exp_f32_e32 v168, v168
	v_exp_f32_e32 v169, v169
	v_exp_f32_e32 v170, v170
	v_exp_f32_e32 v171, v171
	v_add_f32_e32 v168, 1.0, v168
	v_add_f32_e32 v169, 1.0, v169
	v_add_f32_e32 v170, 1.0, v170
	v_add_f32_e32 v171, 1.0, v171
	v_rcp_f32_e32 v168, v168
	v_rcp_f32_e32 v169, v169
	v_rcp_f32_e32 v170, v170
	v_rcp_f32_e32 v171, v171
	v_pk_mul_f32 v[16:17], v[16:17], v[168:169]
	v_pk_mul_f32 v[18:19], v[18:19], v[170:171]
	v_mul_f32_e32 v168, 0xbfb8aa3b, v12
	v_mul_f32_e32 v169, 0xbfb8aa3b, v13
	v_mul_f32_e32 v170, 0xbfb8aa3b, v14
	v_mul_f32_e32 v171, 0xbfb8aa3b, v15
	v_exp_f32_e32 v168, v168
	v_exp_f32_e32 v169, v169
	v_exp_f32_e32 v170, v170
	v_exp_f32_e32 v171, v171
	v_add_f32_e32 v168, 1.0, v168
	v_add_f32_e32 v169, 1.0, v169
	v_add_f32_e32 v170, 1.0, v170
	v_add_f32_e32 v171, 1.0, v171
	v_rcp_f32_e32 v168, v168
	v_rcp_f32_e32 v169, v169
	v_rcp_f32_e32 v170, v170
	v_rcp_f32_e32 v171, v171
	v_pk_mul_f32 v[12:13], v[12:13], v[168:169]
	v_pk_mul_f32 v[14:15], v[14:15], v[170:171]
	v_cvt_pk_f16_f32 v152, v48, v49
	v_cvt_pk_f16_f32 v153, v50, v51
	v_cvt_pk_f16_f32 v154, v44, v45
	v_cvt_pk_f16_f32 v155, v46, v47
	global_store_dwordx4 v133, v[152:155], s[6:7]
	v_cvt_pk_f16_f32 v156, v16, v17
	v_cvt_pk_f16_f32 v157, v18, v19
	v_cvt_pk_f16_f32 v158, v12, v13
	v_cvt_pk_f16_f32 v159, v14, v15
	global_store_dwordx4 v133, v[156:159], s[6:7] offset:2048
	s_add_u32 s6, s4, 0x28100
	s_addc_u32 s7, s5, 0
	v_pk_mul_f32 v[40:41], v[40:41], v[148:149] op_sel_hi:[1,0]
	v_pk_mul_f32 v[42:43], v[42:43], v[148:149] op_sel_hi:[1,0]
	v_pk_mul_f32 v[36:37], v[36:37], v[148:149] op_sel_hi:[1,0]
	v_pk_mul_f32 v[38:39], v[38:39], v[148:149] op_sel_hi:[1,0]
	v_pk_mul_f32 v[8:9], v[8:9], v[148:149] op_sel_hi:[1,0]
	v_pk_mul_f32 v[10:11], v[10:11], v[148:149] op_sel_hi:[1,0]
	v_pk_mul_f32 v[4:5], v[4:5], v[148:149] op_sel_hi:[1,0]
	v_pk_mul_f32 v[6:7], v[6:7], v[148:149] op_sel_hi:[1,0]
	v_mul_f32_e32 v168, 0xbfb8aa3b, v40
	v_mul_f32_e32 v169, 0xbfb8aa3b, v41
	v_mul_f32_e32 v170, 0xbfb8aa3b, v42
	v_mul_f32_e32 v171, 0xbfb8aa3b, v43
	v_exp_f32_e32 v168, v168
	v_exp_f32_e32 v169, v169
	v_exp_f32_e32 v170, v170
	v_exp_f32_e32 v171, v171
	v_add_f32_e32 v168, 1.0, v168
	v_add_f32_e32 v169, 1.0, v169
	v_add_f32_e32 v170, 1.0, v170
	v_add_f32_e32 v171, 1.0, v171
	v_rcp_f32_e32 v168, v168
	v_rcp_f32_e32 v169, v169
	v_rcp_f32_e32 v170, v170
	v_rcp_f32_e32 v171, v171
	v_pk_mul_f32 v[40:41], v[40:41], v[168:169]
	v_pk_mul_f32 v[42:43], v[42:43], v[170:171]
	v_mul_f32_e32 v168, 0xbfb8aa3b, v36
	v_mul_f32_e32 v169, 0xbfb8aa3b, v37
	v_mul_f32_e32 v170, 0xbfb8aa3b, v38
	v_mul_f32_e32 v171, 0xbfb8aa3b, v39
	v_exp_f32_e32 v168, v168
	v_exp_f32_e32 v169, v169
	v_exp_f32_e32 v170, v170
	v_exp_f32_e32 v171, v171
	v_add_f32_e32 v168, 1.0, v168
	v_add_f32_e32 v169, 1.0, v169
	v_add_f32_e32 v170, 1.0, v170
	v_add_f32_e32 v171, 1.0, v171
	v_rcp_f32_e32 v168, v168
	v_rcp_f32_e32 v169, v169
	v_rcp_f32_e32 v170, v170
	v_rcp_f32_e32 v171, v171
	v_pk_mul_f32 v[36:37], v[36:37], v[168:169]
	v_pk_mul_f32 v[38:39], v[38:39], v[170:171]
	v_mul_f32_e32 v168, 0xbfb8aa3b, v8
	v_mul_f32_e32 v169, 0xbfb8aa3b, v9
	v_mul_f32_e32 v170, 0xbfb8aa3b, v10
	v_mul_f32_e32 v171, 0xbfb8aa3b, v11
	v_exp_f32_e32 v168, v168
	v_exp_f32_e32 v169, v169
	v_exp_f32_e32 v170, v170
	v_exp_f32_e32 v171, v171
	v_add_f32_e32 v168, 1.0, v168
	v_add_f32_e32 v169, 1.0, v169
	v_add_f32_e32 v170, 1.0, v170
	v_add_f32_e32 v171, 1.0, v171
	v_rcp_f32_e32 v168, v168
	v_rcp_f32_e32 v169, v169
	v_rcp_f32_e32 v170, v170
	v_rcp_f32_e32 v171, v171
	v_pk_mul_f32 v[8:9], v[8:9], v[168:169]
	v_pk_mul_f32 v[10:11], v[10:11], v[170:171]
	v_mul_f32_e32 v168, 0xbfb8aa3b, v4
	v_mul_f32_e32 v169, 0xbfb8aa3b, v5
	v_mul_f32_e32 v170, 0xbfb8aa3b, v6
	v_mul_f32_e32 v171, 0xbfb8aa3b, v7
	v_exp_f32_e32 v168, v168
	v_exp_f32_e32 v169, v169
	v_exp_f32_e32 v170, v170
	v_exp_f32_e32 v171, v171
	v_add_f32_e32 v168, 1.0, v168
	v_add_f32_e32 v169, 1.0, v169
	v_add_f32_e32 v170, 1.0, v170
	v_add_f32_e32 v171, 1.0, v171
	v_rcp_f32_e32 v168, v168
	v_rcp_f32_e32 v169, v169
	v_rcp_f32_e32 v170, v170
	v_rcp_f32_e32 v171, v171
	v_pk_mul_f32 v[4:5], v[4:5], v[168:169]
	v_pk_mul_f32 v[6:7], v[6:7], v[170:171]
	v_cvt_pk_f16_f32 v160, v40, v41
	v_cvt_pk_f16_f32 v161, v42, v43
	v_cvt_pk_f16_f32 v162, v36, v37
	v_cvt_pk_f16_f32 v163, v38, v39
	global_store_dwordx4 v133, v[160:163], s[6:7]
	v_cvt_pk_f16_f32 v164, v8, v9
	v_cvt_pk_f16_f32 v165, v10, v11
	v_cvt_pk_f16_f32 v166, v4, v5
	v_cvt_pk_f16_f32 v167, v6, v7
	global_store_dwordx4 v133, v[164:167], s[6:7] offset:2048
	s_branch .Lepi_done_g1
; #define LAS __attribute__((address_space(3)))
; #define GAS __attribute__((address_space(1)))
;     __device__ __forceinline__ void operator()(const f32x4 (&acc)[2][2][4][2], const Unit& u, int wr, int wc, int fr, int fq) const {
;     ...
;         if (sec == 4 || sec == 5) {
;             const GAS float* g = (sec == 4) ? gq : gk;
; #pragma unroll
;             for (int bj = 0; bj < 2; ++bj)
; #pragma unroll
;                 for (int n = 0; n < 2; ++n) gain[bj][n] = *(const GAS f32x4*)(g + 32 * bj + 8 * fq + 4 * n);
;         }
;         const LAS int* tags = (const LAS int*)(rsc + 2048);
;         const int slot = (tags[0] == u.pm) ? 0 : (tags[1] == u.pm) ? 1 : -1;
;         const LAS float* rtab = (const LAS float*)rsc + (slot > 0 ? 256 : 0) + wr * 64 + fr;
; #pragma unroll
;         for (int ai = 0; ai < 2; ++ai)
; #pragma unroll
;             for (int m = 0; m < 4; ++m) {
;                 const int row = row0 + ai * HALF + m * 16;
;                 float rs;
;                 if (slot >= 0) rs = rtab[ai * HALF + m * 16];
;                 else {
;                     const f32x4 pv = *(const GAS f32x4*)(part + (size_t)row * 16 + fq * 4);
;                     float s = (pv[0] + pv[1]) + (pv[2] + pv[3]);
;                     s = row4_sum(s);
;                     rs = __builtin_amdgcn_rsqf(s * (1.0f / DM) + RMS_EPS);
;                 }
;                 f32x4 v[2][2];
; #pragma unroll
;                 for (int bj = 0; bj < 2; ++bj)
; #pragma unroll
;                     for (int n = 0; n < 2; ++n) v[bj][n] = acc[ai][bj][m][n] * rs;
;                 if (sec == 4 || sec == 5) {
;                     float ss = 0.f;
; #pragma unroll
;                     for (int bj = 0; bj < 2; ++bj)
; #pragma unroll
;                         for (int n = 0; n < 2; ++n) { const f32x4 x = v[bj][n]; ss += (x[0] * x[0] + x[1] * x[1]) + (x[2] * x[2] + x[3] * x[3]); }
;                     ss = row4_sum(ss);
;                     float rn = __builtin_amdgcn_rsqf(ss * (1.0f / 64.0f) + RMS_EPS);
;                     if (sec == 4) rn *= QS;
; #pragma unroll
;                     for (int bj = 0; bj < 2; ++bj)
; #pragma unroll
;                         for (int n = 0; n < 2; ++n) v[bj][n] = v[bj][n] * rn * gain[bj][n];
.Lepi_qn:
	s_and_b32 s0, s70, 1
	s_lshl_b32 s0, s0, 10
	v_add_u32_e32 v132, s0, v219
	ds_read_b32 v134, v132
	ds_read_b32 v136, v132 offset:64
	ds_read_b32 v138, v132 offset:128
	ds_read_b32 v140, v132 offset:192
	ds_read_b32 v142, v132 offset:512
	ds_read_b32 v144, v132 offset:576
	ds_read_b32 v146, v132 offset:640
	ds_read_b32 v148, v132 offset:704
	s_lshr_b32 s0, s69, 2
	s_and_b32 s1, s69, 1
	v_lshrrev_b32_e32 v2, 6, v187
	v_lshrrev_b32_e32 v133, 3, v220
	v_lshl_add_u32 v133, v2, 7, v133
	v_and_b32_e32 v2, 15, v187
	v_lshlrev_b32_e32 v133, 8, v133
	v_lshl_add_u32 v133, v2, 3, v133
	v_lshlrev_b32_e32 v133, 1, v133
	s_lshl_b32 s0, s0, 25
	s_lshl_b32 s1, s1, 14
	s_add_u32 s0, s0, s1
	s_lshl_b32 s1, s68, 18
	s_add_u32 s0, s0, s1
	s_add_u32 s4, s82, s0
	s_addc_u32 s5, s83, 0
	v_readlane_b32 s10, v252, 17
	v_readlane_b32 s11, v252, 18
	s_lshl_b32 s0, s22, 2
	s_nop 0
	s_add_u32 s10, s10, s0
	s_addc_u32 s11, s11, 0
	s_nop 3
	global_load_dwordx4 v[176:179], v222, s[10:11]
	global_load_dwordx4 v[206:209], v222, s[10:11] offset:16
	global_load_dwordx4 v[224:227], v222, s[10:11] offset:128
	global_load_dwordx4 v[228:231], v222, s[10:11] offset:144
	s_waitcnt vmcnt(0)
	s_waitcnt lgkmcnt(0)
	s_mov_b32 s6, s4
	s_mov_b32 s7, s5
	v_pk_mul_f32 v[128:129], v[128:129], v[134:135] op_sel_hi:[1,0]
	v_pk_mul_f32 v[130:131], v[130:131], v[134:135] op_sel_hi:[1,0]
	v_pk_mul_f32 v[124:125], v[124:125], v[134:135] op_sel_hi:[1,0]
	v_pk_mul_f32 v[126:127], v[126:127], v[134:135] op_sel_hi:[1,0]
	v_pk_mul_f32 v[96:97], v[96:97], v[134:135] op_sel_hi:[1,0]
	v_pk_mul_f32 v[98:99], v[98:99], v[134:135] op_sel_hi:[1,0]
	v_pk_mul_f32 v[92:93], v[92:93], v[134:135] op_sel_hi:[1,0]
	v_pk_mul_f32 v[94:95], v[94:95], v[134:135] op_sel_hi:[1,0]
	v_mul_f32_e32 v2, v128, v128
	v_mul_f32_e32 v150, v129, v129
	v_fmac_f32_e32 v2, v130, v130
	v_fmac_f32_e32 v150, v131, v131
	v_fmac_f32_e32 v2, v124, v124
	v_fmac_f32_e32 v150, v125, v125
	v_fmac_f32_e32 v2, v126, v126
	v_fmac_f32_e32 v150, v127, v127
	v_fmac_f32_e32 v2, v96, v96
	v_fmac_f32_e32 v150, v97, v97
	v_fmac_f32_e32 v2, v98, v98
	v_fmac_f32_e32 v150, v99, v99
	v_fmac_f32_e32 v2, v92, v92
	v_fmac_f32_e32 v150, v93, v93
	v_fmac_f32_e32 v2, v94, v94
	v_fmac_f32_e32 v150, v95, v95
	v_add_f32_e32 v2, v2, v150
	v_mov_b32_e32 v150, v2
	s_nop 1
	v_permlane16_swap_b32_e32 v2, v150
	v_add_f32_e32 v2, v2, v150
	v_mov_b32_e32 v150, v2
	s_nop 1
	v_permlane32_swap_b32_e32 v2, v150
	v_add_f32_e32 v2, v2, v150
	v_fmamk_f32 v2, v2, 0x3c800000, v211
	v_rsq_f32_e32 v2, v2
	s_nop 0
	v_mul_f32_e32 v2, s78, v2
	v_pk_mul_f32 v[128:129], v[128:129], v[2:3] op_sel_hi:[1,0]
	v_pk_mul_f32 v[130:131], v[130:131], v[2:3] op_sel_hi:[1,0]
	v_pk_mul_f32 v[124:125], v[124:125], v[2:3] op_sel_hi:[1,0]
	v_pk_mul_f32 v[126:127], v[126:127], v[2:3] op_sel_hi:[1,0]
	v_pk_mul_f32 v[96:97], v[96:97], v[2:3] op_sel_hi:[1,0]
	v_pk_mul_f32 v[98:99], v[98:99], v[2:3] op_sel_hi:[1,0]
	v_pk_mul_f32 v[92:93], v[92:93], v[2:3] op_sel_hi:[1,0]
	v_pk_mul_f32 v[94:95], v[94:95], v[2:3] op_sel_hi:[1,0]
	v_pk_mul_f32 v[128:129], v[128:129], v[176:177]
	v_pk_mul_f32 v[130:131], v[130:131], v[178:179]
	v_pk_mul_f32 v[124:125], v[124:125], v[206:207]
	v_pk_mul_f32 v[126:127], v[126:127], v[208:209]
	v_pk_mul_f32 v[96:97], v[96:97], v[224:225]
	v_pk_mul_f32 v[98:99], v[98:99], v[226:227]
	v_pk_mul_f32 v[92:93], v[92:93], v[228:229]
	v_pk_mul_f32 v[94:95], v[94:95], v[230:231]
	v_cvt_pk_f16_f32 v152, v128, v129
	v_cvt_pk_f16_f32 v153, v130, v131
	v_cvt_pk_f16_f32 v154, v124, v125
	v_cvt_pk_f16_f32 v155, v126, v127
	global_store_dwordx4 v133, v[152:155], s[6:7]
	v_cvt_pk_f16_f32 v156, v96, v97
	v_cvt_pk_f16_f32 v157, v98, v99
	v_cvt_pk_f16_f32 v158, v92, v93
	v_cvt_pk_f16_f32 v159, v94, v95
	global_store_dwordx4 v133, v[156:159], s[6:7] offset:2048
	s_add_u32 s6, s4, 0x100
	s_addc_u32 s7, s5, 0
	v_pk_mul_f32 v[120:121], v[120:121], v[136:137] op_sel_hi:[1,0]
	v_pk_mul_f32 v[122:123], v[122:123], v[136:137] op_sel_hi:[1,0]
	v_pk_mul_f32 v[116:117], v[116:117], v[136:137] op_sel_hi:[1,0]
	v_pk_mul_f32 v[118:119], v[118:119], v[136:137] op_sel_hi:[1,0]
	v_pk_mul_f32 v[88:89], v[88:89], v[136:137] op_sel_hi:[1,0]
	v_pk_mul_f32 v[90:91], v[90:91], v[136:137] op_sel_hi:[1,0]
	v_pk_mul_f32 v[84:85], v[84:85], v[136:137] op_sel_hi:[1,0]
	v_pk_mul_f32 v[86:87], v[86:87], v[136:137] op_sel_hi:[1,0]
	v_mul_f32_e32 v2, v120, v120
	v_mul_f32_e32 v150, v121, v121
	v_fmac_f32_e32 v2, v122, v122
	v_fmac_f32_e32 v150, v123, v123
	v_fmac_f32_e32 v2, v116, v116
	v_fmac_f32_e32 v150, v117, v117
	v_fmac_f32_e32 v2, v118, v118
	v_fmac_f32_e32 v150, v119, v119
	v_fmac_f32_e32 v2, v88, v88
	v_fmac_f32_e32 v150, v89, v89
	v_fmac_f32_e32 v2, v90, v90
	v_fmac_f32_e32 v150, v91, v91
	v_fmac_f32_e32 v2, v84, v84
	v_fmac_f32_e32 v150, v85, v85
	v_fmac_f32_e32 v2, v86, v86
	v_fmac_f32_e32 v150, v87, v87
	v_add_f32_e32 v2, v2, v150
	v_mov_b32_e32 v150, v2
	s_nop 1
	v_permlane16_swap_b32_e32 v2, v150
	v_add_f32_e32 v2, v2, v150
	v_mov_b32_e32 v150, v2
	s_nop 1
	v_permlane32_swap_b32_e32 v2, v150
	v_add_f32_e32 v2, v2, v150
	v_fmamk_f32 v2, v2, 0x3c800000, v211
	v_rsq_f32_e32 v2, v2
	s_nop 0
	v_mul_f32_e32 v2, s78, v2
	v_pk_mul_f32 v[120:121], v[120:121], v[2:3] op_sel_hi:[1,0]
	v_pk_mul_f32 v[122:123], v[122:123], v[2:3] op_sel_hi:[1,0]
	v_pk_mul_f32 v[116:117], v[116:117], v[2:3] op_sel_hi:[1,0]
	v_pk_mul_f32 v[118:119], v[118:119], v[2:3] op_sel_hi:[1,0]
	v_pk_mul_f32 v[88:89], v[88:89], v[2:3] op_sel_hi:[1,0]
	v_pk_mul_f32 v[90:91], v[90:91], v[2:3] op_sel_hi:[1,0]
	v_pk_mul_f32 v[84:85], v[84:85], v[2:3] op_sel_hi:[1,0]
	v_pk_mul_f32 v[86:87], v[86:87], v[2:3] op_sel_hi:[1,0]
	v_pk_mul_f32 v[120:121], v[120:121], v[176:177]
; #define GAS __attribute__((address_space(1)))
; __host__ __device__ __forceinline__ size_t bl512(size_t row, int col) { return ((row >> 5) * 64 + (size_t)(col >> 3)) * 256 + (row & 31) * 8 + (col & 7); }
; __device__ __forceinline__ float silu_f(float v) { return v * __builtin_amdgcn_rcpf(1.0f + __builtin_amdgcn_exp2f(-v * LOG2E)); }
;     __device__ __forceinline__ void operator()(const f32x4 (&acc)[2][2][4][2], const Unit& u, int wr, int wc, int fr, int fq) const {
;     ...
;                 if (sec == 4 || sec == 5) {
;                     float ss = 0.f;
; #pragma unroll
;                     for (int bj = 0; bj < 2; ++bj)
; #pragma unroll
;                         for (int n = 0; n < 2; ++n) { const f32x4 x = v[bj][n]; ss += (x[0] * x[0] + x[1] * x[1]) + (x[2] * x[2] + x[3] * x[3]); }
;                     ss = row4_sum(ss);
;                     float rn = __builtin_amdgcn_rsqf(ss * (1.0f / 64.0f) + RMS_EPS);
;                     if (sec == 4) rn *= QS;
; #pragma unroll
;                     for (int bj = 0; bj < 2; ++bj)
; #pragma unroll
;                         for (int n = 0; n < 2; ++n) v[bj][n] = v[bj][n] * rn * gain[bj][n];
;                 } else if (sec == 0) {
; #pragma unroll
;                     for (int bj = 0; bj < 2; ++bj)
; #pragma unroll
;                         for (int n = 0; n < 2; ++n) v[bj][n] = v[bj][n] * QS;
;                 } else if (sec == 3 || sec == 7) {
; #pragma unroll
;                     for (int bj = 0; bj < 2; ++bj)
; #pragma unroll
;                         for (int n = 0; n < 2; ++n)
; #pragma unroll
;                             for (int e = 0; e < 4; ++e) v[bj][n][e] = silu_f(v[bj][n][e]);
;                 }
;                 GAS f16* rowp = isqg ? QG + (size_t)dsec * QG_SEC + bl512((size_t)row, cs) : KV + (size_t)row * KVW + dsec * 512 + cs;
; #pragma unroll
;                 for (int bj = 0; bj < 2; ++bj) {
;                     u32x4 w; w.x = pkh(v[bj][0][0], v[bj][0][1]); w.y = pkh(v[bj][0][2], v[bj][0][3]); w.z = pkh(v[bj][1][0], v[bj][1][1]); w.w = pkh(v[bj][1][2], v[bj][1][3]);
;                     *(GAS u32x4*)(rowp + bjstep * bj) = w;
;                 }
	v_pk_mul_f32 v[122:123], v[122:123], v[178:179]
	v_pk_mul_f32 v[116:117], v[116:117], v[206:207]
	v_pk_mul_f32 v[118:119], v[118:119], v[208:209]
	v_pk_mul_f32 v[88:89], v[88:89], v[224:225]
	v_pk_mul_f32 v[90:91], v[90:91], v[226:227]
	v_pk_mul_f32 v[84:85], v[84:85], v[228:229]
	v_pk_mul_f32 v[86:87], v[86:87], v[230:231]
	v_cvt_pk_f16_f32 v160, v120, v121
	v_cvt_pk_f16_f32 v161, v122, v123
	v_cvt_pk_f16_f32 v162, v116, v117
	v_cvt_pk_f16_f32 v163, v118, v119
	global_store_dwordx4 v133, v[160:163], s[6:7]
	v_cvt_pk_f16_f32 v164, v88, v89
	v_cvt_pk_f16_f32 v165, v90, v91
	v_cvt_pk_f16_f32 v166, v84, v85
	v_cvt_pk_f16_f32 v167, v86, v87
	global_store_dwordx4 v133, v[164:167], s[6:7] offset:2048
	s_add_u32 s6, s4, 0x8000
	s_addc_u32 s7, s5, 0
	v_pk_mul_f32 v[112:113], v[112:113], v[138:139] op_sel_hi:[1,0]
	v_pk_mul_f32 v[114:115], v[114:115], v[138:139] op_sel_hi:[1,0]
	v_pk_mul_f32 v[108:109], v[108:109], v[138:139] op_sel_hi:[1,0]
	v_pk_mul_f32 v[110:111], v[110:111], v[138:139] op_sel_hi:[1,0]
	v_pk_mul_f32 v[80:81], v[80:81], v[138:139] op_sel_hi:[1,0]
	v_pk_mul_f32 v[82:83], v[82:83], v[138:139] op_sel_hi:[1,0]
	v_pk_mul_f32 v[76:77], v[76:77], v[138:139] op_sel_hi:[1,0]
	v_pk_mul_f32 v[78:79], v[78:79], v[138:139] op_sel_hi:[1,0]
	v_mul_f32_e32 v2, v112, v112
	v_mul_f32_e32 v150, v113, v113
	v_fmac_f32_e32 v2, v114, v114
	v_fmac_f32_e32 v150, v115, v115
	v_fmac_f32_e32 v2, v108, v108
	v_fmac_f32_e32 v150, v109, v109
	v_fmac_f32_e32 v2, v110, v110
	v_fmac_f32_e32 v150, v111, v111
	v_fmac_f32_e32 v2, v80, v80
	v_fmac_f32_e32 v150, v81, v81
	v_fmac_f32_e32 v2, v82, v82
	v_fmac_f32_e32 v150, v83, v83
	v_fmac_f32_e32 v2, v76, v76
	v_fmac_f32_e32 v150, v77, v77
	v_fmac_f32_e32 v2, v78, v78
	v_fmac_f32_e32 v150, v79, v79
	v_add_f32_e32 v2, v2, v150
	v_mov_b32_e32 v150, v2
	s_nop 1
	v_permlane16_swap_b32_e32 v2, v150
	v_add_f32_e32 v2, v2, v150
	v_mov_b32_e32 v150, v2
	s_nop 1
	v_permlane32_swap_b32_e32 v2, v150
	v_add_f32_e32 v2, v2, v150
	v_fmamk_f32 v2, v2, 0x3c800000, v211
	v_rsq_f32_e32 v2, v2
	s_nop 0
	v_mul_f32_e32 v2, s78, v2
	v_pk_mul_f32 v[112:113], v[112:113], v[2:3] op_sel_hi:[1,0]
	v_pk_mul_f32 v[114:115], v[114:115], v[2:3] op_sel_hi:[1,0]
	v_pk_mul_f32 v[108:109], v[108:109], v[2:3] op_sel_hi:[1,0]
	v_pk_mul_f32 v[110:111], v[110:111], v[2:3] op_sel_hi:[1,0]
	v_pk_mul_f32 v[80:81], v[80:81], v[2:3] op_sel_hi:[1,0]
	v_pk_mul_f32 v[82:83], v[82:83], v[2:3] op_sel_hi:[1,0]
	v_pk_mul_f32 v[76:77], v[76:77], v[2:3] op_sel_hi:[1,0]
	v_pk_mul_f32 v[78:79], v[78:79], v[2:3] op_sel_hi:[1,0]
	v_pk_mul_f32 v[112:113], v[112:113], v[176:177]
	v_pk_mul_f32 v[114:115], v[114:115], v[178:179]
	v_pk_mul_f32 v[108:109], v[108:109], v[206:207]
	v_pk_mul_f32 v[110:111], v[110:111], v[208:209]
	v_pk_mul_f32 v[80:81], v[80:81], v[224:225]
	v_pk_mul_f32 v[82:83], v[82:83], v[226:227]
	v_pk_mul_f32 v[76:77], v[76:77], v[228:229]
	v_pk_mul_f32 v[78:79], v[78:79], v[230:231]
	v_cvt_pk_f16_f32 v152, v112, v113
	v_cvt_pk_f16_f32 v153, v114, v115
	v_cvt_pk_f16_f32 v154, v108, v109
	v_cvt_pk_f16_f32 v155, v110, v111
	global_store_dwordx4 v133, v[152:155], s[6:7]
	v_cvt_pk_f16_f32 v156, v80, v81
	v_cvt_pk_f16_f32 v157, v82, v83
	v_cvt_pk_f16_f32 v158, v76, v77
	v_cvt_pk_f16_f32 v159, v78, v79
	global_store_dwordx4 v133, v[156:159], s[6:7] offset:2048
	s_add_u32 s6, s4, 0x8100
	s_addc_u32 s7, s5, 0
	v_pk_mul_f32 v[104:105], v[104:105], v[140:141] op_sel_hi:[1,0]
	v_pk_mul_f32 v[106:107], v[106:107], v[140:141] op_sel_hi:[1,0]
	v_pk_mul_f32 v[100:101], v[100:101], v[140:141] op_sel_hi:[1,0]
	v_pk_mul_f32 v[102:103], v[102:103], v[140:141] op_sel_hi:[1,0]
	v_pk_mul_f32 v[72:73], v[72:73], v[140:141] op_sel_hi:[1,0]
	v_pk_mul_f32 v[74:75], v[74:75], v[140:141] op_sel_hi:[1,0]
	v_pk_mul_f32 v[68:69], v[68:69], v[140:141] op_sel_hi:[1,0]
	v_pk_mul_f32 v[70:71], v[70:71], v[140:141] op_sel_hi:[1,0]
	v_mul_f32_e32 v2, v104, v104
	v_mul_f32_e32 v150, v105, v105
	v_fmac_f32_e32 v2, v106, v106
	v_fmac_f32_e32 v150, v107, v107
	v_fmac_f32_e32 v2, v100, v100
	v_fmac_f32_e32 v150, v101, v101
	v_fmac_f32_e32 v2, v102, v102
	v_fmac_f32_e32 v150, v103, v103
	v_fmac_f32_e32 v2, v72, v72
	v_fmac_f32_e32 v150, v73, v73
	v_fmac_f32_e32 v2, v74, v74
	v_fmac_f32_e32 v150, v75, v75
	v_fmac_f32_e32 v2, v68, v68
	v_fmac_f32_e32 v150, v69, v69
	v_fmac_f32_e32 v2, v70, v70
	v_fmac_f32_e32 v150, v71, v71
	v_add_f32_e32 v2, v2, v150
	v_mov_b32_e32 v150, v2
	s_nop 1
	v_permlane16_swap_b32_e32 v2, v150
	v_add_f32_e32 v2, v2, v150
	v_mov_b32_e32 v150, v2
	s_nop 1
	v_permlane32_swap_b32_e32 v2, v150
	v_add_f32_e32 v2, v2, v150
	v_fmamk_f32 v2, v2, 0x3c800000, v211
	v_rsq_f32_e32 v2, v2
	s_nop 0
	v_mul_f32_e32 v2, s78, v2
	v_pk_mul_f32 v[104:105], v[104:105], v[2:3] op_sel_hi:[1,0]
	v_pk_mul_f32 v[106:107], v[106:107], v[2:3] op_sel_hi:[1,0]
	v_pk_mul_f32 v[100:101], v[100:101], v[2:3] op_sel_hi:[1,0]
	v_pk_mul_f32 v[102:103], v[102:103], v[2:3] op_sel_hi:[1,0]
	v_pk_mul_f32 v[72:73], v[72:73], v[2:3] op_sel_hi:[1,0]
	v_pk_mul_f32 v[74:75], v[74:75], v[2:3] op_sel_hi:[1,0]
	v_pk_mul_f32 v[68:69], v[68:69], v[2:3] op_sel_hi:[1,0]
	v_pk_mul_f32 v[70:71], v[70:71], v[2:3] op_sel_hi:[1,0]
	v_pk_mul_f32 v[104:105], v[104:105], v[176:177]
	v_pk_mul_f32 v[106:107], v[106:107], v[178:179]
	v_pk_mul_f32 v[100:101], v[100:101], v[206:207]
	v_pk_mul_f32 v[102:103], v[102:103], v[208:209]
	v_pk_mul_f32 v[72:73], v[72:73], v[224:225]
	v_pk_mul_f32 v[74:75], v[74:75], v[226:227]
	v_pk_mul_f32 v[68:69], v[68:69], v[228:229]
	v_pk_mul_f32 v[70:71], v[70:71], v[230:231]
	v_cvt_pk_f16_f32 v160, v104, v105
	v_cvt_pk_f16_f32 v161, v106, v107
	v_cvt_pk_f16_f32 v162, v100, v101
	v_cvt_pk_f16_f32 v163, v102, v103
; #define GAS __attribute__((address_space(1)))
; __host__ __device__ __forceinline__ size_t bl512(size_t row, int col) { return ((row >> 5) * 64 + (size_t)(col >> 3)) * 256 + (row & 31) * 8 + (col & 7); }
; __device__ __forceinline__ float silu_f(float v) { return v * __builtin_amdgcn_rcpf(1.0f + __builtin_amdgcn_exp2f(-v * LOG2E)); }
;     __device__ __forceinline__ void operator()(const f32x4 (&acc)[2][2][4][2], const Unit& u, int wr, int wc, int fr, int fq) const {
;     ...
;                 if (sec == 4 || sec == 5) {
;                     float ss = 0.f;
; #pragma unroll
;                     for (int bj = 0; bj < 2; ++bj)
; #pragma unroll
;                         for (int n = 0; n < 2; ++n) { const f32x4 x = v[bj][n]; ss += (x[0] * x[0] + x[1] * x[1]) + (x[2] * x[2] + x[3] * x[3]); }
;                     ss = row4_sum(ss);
;                     float rn = __builtin_amdgcn_rsqf(ss * (1.0f / 64.0f) + RMS_EPS);
;                     if (sec == 4) rn *= QS;
; #pragma unroll
;                     for (int bj = 0; bj < 2; ++bj)
; #pragma unroll
;                         for (int n = 0; n < 2; ++n) v[bj][n] = v[bj][n] * rn * gain[bj][n];
;                 } else if (sec == 0) {
; #pragma unroll
;                     for (int bj = 0; bj < 2; ++bj)
; #pragma unroll
;                         for (int n = 0; n < 2; ++n) v[bj][n] = v[bj][n] * QS;
;                 } else if (sec == 3 || sec == 7) {
; #pragma unroll
;                     for (int bj = 0; bj < 2; ++bj)
; #pragma unroll
;                         for (int n = 0; n < 2; ++n)
; #pragma unroll
;                             for (int e = 0; e < 4; ++e) v[bj][n][e] = silu_f(v[bj][n][e]);
;                 }
;                 GAS f16* rowp = isqg ? QG + (size_t)dsec * QG_SEC + bl512((size_t)row, cs) : KV + (size_t)row * KVW + dsec * 512 + cs;
; #pragma unroll
;                 for (int bj = 0; bj < 2; ++bj) {
;                     u32x4 w; w.x = pkh(v[bj][0][0], v[bj][0][1]); w.y = pkh(v[bj][0][2], v[bj][0][3]); w.z = pkh(v[bj][1][0], v[bj][1][1]); w.w = pkh(v[bj][1][2], v[bj][1][3]);
;                     *(GAS u32x4*)(rowp + bjstep * bj) = w;
;                 }
	global_store_dwordx4 v133, v[160:163], s[6:7]
	v_cvt_pk_f16_f32 v164, v72, v73
	v_cvt_pk_f16_f32 v165, v74, v75
	v_cvt_pk_f16_f32 v166, v68, v69
	v_cvt_pk_f16_f32 v167, v70, v71
	global_store_dwordx4 v133, v[164:167], s[6:7] offset:2048
	s_add_u32 s6, s4, 0x20000
	s_addc_u32 s7, s5, 0
	v_pk_mul_f32 v[64:65], v[64:65], v[142:143] op_sel_hi:[1,0]
	v_pk_mul_f32 v[66:67], v[66:67], v[142:143] op_sel_hi:[1,0]
	v_pk_mul_f32 v[60:61], v[60:61], v[142:143] op_sel_hi:[1,0]
	v_pk_mul_f32 v[62:63], v[62:63], v[142:143] op_sel_hi:[1,0]
	v_pk_mul_f32 v[32:33], v[32:33], v[142:143] op_sel_hi:[1,0]
	v_pk_mul_f32 v[34:35], v[34:35], v[142:143] op_sel_hi:[1,0]
	v_pk_mul_f32 v[28:29], v[28:29], v[142:143] op_sel_hi:[1,0]
	v_pk_mul_f32 v[30:31], v[30:31], v[142:143] op_sel_hi:[1,0]
	v_mul_f32_e32 v2, v64, v64
	v_mul_f32_e32 v150, v65, v65
	v_fmac_f32_e32 v2, v66, v66
	v_fmac_f32_e32 v150, v67, v67
	v_fmac_f32_e32 v2, v60, v60
	v_fmac_f32_e32 v150, v61, v61
	v_fmac_f32_e32 v2, v62, v62
	v_fmac_f32_e32 v150, v63, v63
	v_fmac_f32_e32 v2, v32, v32
	v_fmac_f32_e32 v150, v33, v33
	v_fmac_f32_e32 v2, v34, v34
	v_fmac_f32_e32 v150, v35, v35
	v_fmac_f32_e32 v2, v28, v28
	v_fmac_f32_e32 v150, v29, v29
	v_fmac_f32_e32 v2, v30, v30
	v_fmac_f32_e32 v150, v31, v31
	v_add_f32_e32 v2, v2, v150
	v_mov_b32_e32 v150, v2
	s_nop 1
	v_permlane16_swap_b32_e32 v2, v150
	v_add_f32_e32 v2, v2, v150
	v_mov_b32_e32 v150, v2
	s_nop 1
	v_permlane32_swap_b32_e32 v2, v150
	v_add_f32_e32 v2, v2, v150
	v_fmamk_f32 v2, v2, 0x3c800000, v211
	v_rsq_f32_e32 v2, v2
	s_nop 0
	v_mul_f32_e32 v2, s78, v2
	v_pk_mul_f32 v[64:65], v[64:65], v[2:3] op_sel_hi:[1,0]
	v_pk_mul_f32 v[66:67], v[66:67], v[2:3] op_sel_hi:[1,0]
	v_pk_mul_f32 v[60:61], v[60:61], v[2:3] op_sel_hi:[1,0]
	v_pk_mul_f32 v[62:63], v[62:63], v[2:3] op_sel_hi:[1,0]
	v_pk_mul_f32 v[32:33], v[32:33], v[2:3] op_sel_hi:[1,0]
	v_pk_mul_f32 v[34:35], v[34:35], v[2:3] op_sel_hi:[1,0]
	v_pk_mul_f32 v[28:29], v[28:29], v[2:3] op_sel_hi:[1,0]
	v_pk_mul_f32 v[30:31], v[30:31], v[2:3] op_sel_hi:[1,0]
	v_pk_mul_f32 v[64:65], v[64:65], v[176:177]
	v_pk_mul_f32 v[66:67], v[66:67], v[178:179]
	v_pk_mul_f32 v[60:61], v[60:61], v[206:207]
	v_pk_mul_f32 v[62:63], v[62:63], v[208:209]
	v_pk_mul_f32 v[32:33], v[32:33], v[224:225]
	v_pk_mul_f32 v[34:35], v[34:35], v[226:227]
	v_pk_mul_f32 v[28:29], v[28:29], v[228:229]
	v_pk_mul_f32 v[30:31], v[30:31], v[230:231]
	v_cvt_pk_f16_f32 v152, v64, v65
	v_cvt_pk_f16_f32 v153, v66, v67
	v_cvt_pk_f16_f32 v154, v60, v61
	v_cvt_pk_f16_f32 v155, v62, v63
	global_store_dwordx4 v133, v[152:155], s[6:7]
	v_cvt_pk_f16_f32 v156, v32, v33
	v_cvt_pk_f16_f32 v157, v34, v35
	v_cvt_pk_f16_f32 v158, v28, v29
	v_cvt_pk_f16_f32 v159, v30, v31
	global_store_dwordx4 v133, v[156:159], s[6:7] offset:2048
	s_add_u32 s6, s4, 0x20100
	s_addc_u32 s7, s5, 0
	v_pk_mul_f32 v[56:57], v[56:57], v[144:145] op_sel_hi:[1,0]
	v_pk_mul_f32 v[58:59], v[58:59], v[144:145] op_sel_hi:[1,0]
	v_pk_mul_f32 v[52:53], v[52:53], v[144:145] op_sel_hi:[1,0]
	v_pk_mul_f32 v[54:55], v[54:55], v[144:145] op_sel_hi:[1,0]
	v_pk_mul_f32 v[24:25], v[24:25], v[144:145] op_sel_hi:[1,0]
	v_pk_mul_f32 v[26:27], v[26:27], v[144:145] op_sel_hi:[1,0]
	v_pk_mul_f32 v[20:21], v[20:21], v[144:145] op_sel_hi:[1,0]
	v_pk_mul_f32 v[22:23], v[22:23], v[144:145] op_sel_hi:[1,0]
	v_mul_f32_e32 v2, v56, v56
	v_mul_f32_e32 v150, v57, v57
	v_fmac_f32_e32 v2, v58, v58
	v_fmac_f32_e32 v150, v59, v59
	v_fmac_f32_e32 v2, v52, v52
	v_fmac_f32_e32 v150, v53, v53
	v_fmac_f32_e32 v2, v54, v54
	v_fmac_f32_e32 v150, v55, v55
	v_fmac_f32_e32 v2, v24, v24
	v_fmac_f32_e32 v150, v25, v25
	v_fmac_f32_e32 v2, v26, v26
	v_fmac_f32_e32 v150, v27, v27
	v_fmac_f32_e32 v2, v20, v20
	v_fmac_f32_e32 v150, v21, v21
	v_fmac_f32_e32 v2, v22, v22
	v_fmac_f32_e32 v150, v23, v23
	v_add_f32_e32 v2, v2, v150
	v_mov_b32_e32 v150, v2
	s_nop 1
	v_permlane16_swap_b32_e32 v2, v150
	v_add_f32_e32 v2, v2, v150
	v_mov_b32_e32 v150, v2
	s_nop 1
	v_permlane32_swap_b32_e32 v2, v150
	v_add_f32_e32 v2, v2, v150
	v_fmamk_f32 v2, v2, 0x3c800000, v211
	v_rsq_f32_e32 v2, v2
	s_nop 0
	v_mul_f32_e32 v2, s78, v2
	v_pk_mul_f32 v[56:57], v[56:57], v[2:3] op_sel_hi:[1,0]
	v_pk_mul_f32 v[58:59], v[58:59], v[2:3] op_sel_hi:[1,0]
	v_pk_mul_f32 v[52:53], v[52:53], v[2:3] op_sel_hi:[1,0]
	v_pk_mul_f32 v[54:55], v[54:55], v[2:3] op_sel_hi:[1,0]
	v_pk_mul_f32 v[24:25], v[24:25], v[2:3] op_sel_hi:[1,0]
	v_pk_mul_f32 v[26:27], v[26:27], v[2:3] op_sel_hi:[1,0]
	v_pk_mul_f32 v[20:21], v[20:21], v[2:3] op_sel_hi:[1,0]
	v_pk_mul_f32 v[22:23], v[22:23], v[2:3] op_sel_hi:[1,0]
	v_pk_mul_f32 v[56:57], v[56:57], v[176:177]
	v_pk_mul_f32 v[58:59], v[58:59], v[178:179]
	v_pk_mul_f32 v[52:53], v[52:53], v[206:207]
	v_pk_mul_f32 v[54:55], v[54:55], v[208:209]
	v_pk_mul_f32 v[24:25], v[24:25], v[224:225]
	v_pk_mul_f32 v[26:27], v[26:27], v[226:227]
	v_pk_mul_f32 v[20:21], v[20:21], v[228:229]
	v_pk_mul_f32 v[22:23], v[22:23], v[230:231]
	v_cvt_pk_f16_f32 v160, v56, v57
	v_cvt_pk_f16_f32 v161, v58, v59
	v_cvt_pk_f16_f32 v162, v52, v53
	v_cvt_pk_f16_f32 v163, v54, v55
	global_store_dwordx4 v133, v[160:163], s[6:7]
	v_cvt_pk_f16_f32 v164, v24, v25
	v_cvt_pk_f16_f32 v165, v26, v27
	v_cvt_pk_f16_f32 v166, v20, v21
	v_cvt_pk_f16_f32 v167, v22, v23
	global_store_dwordx4 v133, v[164:167], s[6:7] offset:2048
	s_add_u32 s6, s4, 0x28000
	s_addc_u32 s7, s5, 0
	v_pk_mul_f32 v[48:49], v[48:49], v[146:147] op_sel_hi:[1,0]
	v_pk_mul_f32 v[50:51], v[50:51], v[146:147] op_sel_hi:[1,0]
	v_pk_mul_f32 v[44:45], v[44:45], v[146:147] op_sel_hi:[1,0]
	v_pk_mul_f32 v[46:47], v[46:47], v[146:147] op_sel_hi:[1,0]
	v_pk_mul_f32 v[16:17], v[16:17], v[146:147] op_sel_hi:[1,0]
; #define GAS __attribute__((address_space(1)))
; __host__ __device__ __forceinline__ size_t bl512(size_t row, int col) { return ((row >> 5) * 64 + (size_t)(col >> 3)) * 256 + (row & 31) * 8 + (col & 7); }
; __device__ __forceinline__ float silu_f(float v) { return v * __builtin_amdgcn_rcpf(1.0f + __builtin_amdgcn_exp2f(-v * LOG2E)); }
;     __device__ __forceinline__ void operator()(const f32x4 (&acc)[2][2][4][2], const Unit& u, int wr, int wc, int fr, int fq) const {
;     ...
;                 if (sec == 4 || sec == 5) {
;                     float ss = 0.f;
; #pragma unroll
;                     for (int bj = 0; bj < 2; ++bj)
; #pragma unroll
;                         for (int n = 0; n < 2; ++n) { const f32x4 x = v[bj][n]; ss += (x[0] * x[0] + x[1] * x[1]) + (x[2] * x[2] + x[3] * x[3]); }
;                     ss = row4_sum(ss);
;                     float rn = __builtin_amdgcn_rsqf(ss * (1.0f / 64.0f) + RMS_EPS);
;                     if (sec == 4) rn *= QS;
; #pragma unroll
;                     for (int bj = 0; bj < 2; ++bj)
; #pragma unroll
;                         for (int n = 0; n < 2; ++n) v[bj][n] = v[bj][n] * rn * gain[bj][n];
;                 } else if (sec == 0) {
; #pragma unroll
;                     for (int bj = 0; bj < 2; ++bj)
; #pragma unroll
;                         for (int n = 0; n < 2; ++n) v[bj][n] = v[bj][n] * QS;
;                 } else if (sec == 3 || sec == 7) {
; #pragma unroll
;                     for (int bj = 0; bj < 2; ++bj)
; #pragma unroll
;                         for (int n = 0; n < 2; ++n)
; #pragma unroll
;                             for (int e = 0; e < 4; ++e) v[bj][n][e] = silu_f(v[bj][n][e]);
;                 }
;                 GAS f16* rowp = isqg ? QG + (size_t)dsec * QG_SEC + bl512((size_t)row, cs) : KV + (size_t)row * KVW + dsec * 512 + cs;
; #pragma unroll
;                 for (int bj = 0; bj < 2; ++bj) {
;                     u32x4 w; w.x = pkh(v[bj][0][0], v[bj][0][1]); w.y = pkh(v[bj][0][2], v[bj][0][3]); w.z = pkh(v[bj][1][0], v[bj][1][1]); w.w = pkh(v[bj][1][2], v[bj][1][3]);
;                     *(GAS u32x4*)(rowp + bjstep * bj) = w;
;                 }
	v_pk_mul_f32 v[18:19], v[18:19], v[146:147] op_sel_hi:[1,0]
	v_pk_mul_f32 v[12:13], v[12:13], v[146:147] op_sel_hi:[1,0]
	v_pk_mul_f32 v[14:15], v[14:15], v[146:147] op_sel_hi:[1,0]
	v_mul_f32_e32 v2, v48, v48
	v_mul_f32_e32 v150, v49, v49
	v_fmac_f32_e32 v2, v50, v50
	v_fmac_f32_e32 v150, v51, v51
	v_fmac_f32_e32 v2, v44, v44
	v_fmac_f32_e32 v150, v45, v45
	v_fmac_f32_e32 v2, v46, v46
	v_fmac_f32_e32 v150, v47, v47
	v_fmac_f32_e32 v2, v16, v16
	v_fmac_f32_e32 v150, v17, v17
	v_fmac_f32_e32 v2, v18, v18
	v_fmac_f32_e32 v150, v19, v19
	v_fmac_f32_e32 v2, v12, v12
	v_fmac_f32_e32 v150, v13, v13
	v_fmac_f32_e32 v2, v14, v14
	v_fmac_f32_e32 v150, v15, v15
	v_add_f32_e32 v2, v2, v150
	v_mov_b32_e32 v150, v2
	s_nop 1
	v_permlane16_swap_b32_e32 v2, v150
	v_add_f32_e32 v2, v2, v150
	v_mov_b32_e32 v150, v2
	s_nop 1
	v_permlane32_swap_b32_e32 v2, v150
	v_add_f32_e32 v2, v2, v150
	v_fmamk_f32 v2, v2, 0x3c800000, v211
	v_rsq_f32_e32 v2, v2
	s_nop 0
	v_mul_f32_e32 v2, s78, v2
	v_pk_mul_f32 v[48:49], v[48:49], v[2:3] op_sel_hi:[1,0]
	v_pk_mul_f32 v[50:51], v[50:51], v[2:3] op_sel_hi:[1,0]
	v_pk_mul_f32 v[44:45], v[44:45], v[2:3] op_sel_hi:[1,0]
	v_pk_mul_f32 v[46:47], v[46:47], v[2:3] op_sel_hi:[1,0]
	v_pk_mul_f32 v[16:17], v[16:17], v[2:3] op_sel_hi:[1,0]
	v_pk_mul_f32 v[18:19], v[18:19], v[2:3] op_sel_hi:[1,0]
	v_pk_mul_f32 v[12:13], v[12:13], v[2:3] op_sel_hi:[1,0]
	v_pk_mul_f32 v[14:15], v[14:15], v[2:3] op_sel_hi:[1,0]
	v_pk_mul_f32 v[48:49], v[48:49], v[176:177]
	v_pk_mul_f32 v[50:51], v[50:51], v[178:179]
	v_pk_mul_f32 v[44:45], v[44:45], v[206:207]
	v_pk_mul_f32 v[46:47], v[46:47], v[208:209]
	v_pk_mul_f32 v[16:17], v[16:17], v[224:225]
	v_pk_mul_f32 v[18:19], v[18:19], v[226:227]
	v_pk_mul_f32 v[12:13], v[12:13], v[228:229]
	v_pk_mul_f32 v[14:15], v[14:15], v[230:231]
	v_cvt_pk_f16_f32 v152, v48, v49
	v_cvt_pk_f16_f32 v153, v50, v51
	v_cvt_pk_f16_f32 v154, v44, v45
	v_cvt_pk_f16_f32 v155, v46, v47
	global_store_dwordx4 v133, v[152:155], s[6:7]
	v_cvt_pk_f16_f32 v156, v16, v17
	v_cvt_pk_f16_f32 v157, v18, v19
	v_cvt_pk_f16_f32 v158, v12, v13
	v_cvt_pk_f16_f32 v159, v14, v15
	global_store_dwordx4 v133, v[156:159], s[6:7] offset:2048
	s_add_u32 s6, s4, 0x28100
	s_addc_u32 s7, s5, 0
	v_pk_mul_f32 v[40:41], v[40:41], v[148:149] op_sel_hi:[1,0]
	v_pk_mul_f32 v[42:43], v[42:43], v[148:149] op_sel_hi:[1,0]
	v_pk_mul_f32 v[36:37], v[36:37], v[148:149] op_sel_hi:[1,0]
	v_pk_mul_f32 v[38:39], v[38:39], v[148:149] op_sel_hi:[1,0]
	v_pk_mul_f32 v[8:9], v[8:9], v[148:149] op_sel_hi:[1,0]
	v_pk_mul_f32 v[10:11], v[10:11], v[148:149] op_sel_hi:[1,0]
	v_pk_mul_f32 v[4:5], v[4:5], v[148:149] op_sel_hi:[1,0]
	v_pk_mul_f32 v[6:7], v[6:7], v[148:149] op_sel_hi:[1,0]
	v_mul_f32_e32 v2, v40, v40
	v_mul_f32_e32 v150, v41, v41
	v_fmac_f32_e32 v2, v42, v42
	v_fmac_f32_e32 v150, v43, v43
	v_fmac_f32_e32 v2, v36, v36
	v_fmac_f32_e32 v150, v37, v37
	v_fmac_f32_e32 v2, v38, v38
	v_fmac_f32_e32 v150, v39, v39
	v_fmac_f32_e32 v2, v8, v8
	v_fmac_f32_e32 v150, v9, v9
	v_fmac_f32_e32 v2, v10, v10
	v_fmac_f32_e32 v150, v11, v11
	v_fmac_f32_e32 v2, v4, v4
	v_fmac_f32_e32 v150, v5, v5
	v_fmac_f32_e32 v2, v6, v6
	v_fmac_f32_e32 v150, v7, v7
	v_add_f32_e32 v2, v2, v150
	v_mov_b32_e32 v150, v2
	s_nop 1
	v_permlane16_swap_b32_e32 v2, v150
	v_add_f32_e32 v2, v2, v150
	v_mov_b32_e32 v150, v2
	s_nop 1
	v_permlane32_swap_b32_e32 v2, v150
	v_add_f32_e32 v2, v2, v150
	v_fmamk_f32 v2, v2, 0x3c800000, v211
	v_rsq_f32_e32 v2, v2
	s_nop 0
	v_mul_f32_e32 v2, s78, v2
	v_pk_mul_f32 v[40:41], v[40:41], v[2:3] op_sel_hi:[1,0]
	v_pk_mul_f32 v[42:43], v[42:43], v[2:3] op_sel_hi:[1,0]
	v_pk_mul_f32 v[36:37], v[36:37], v[2:3] op_sel_hi:[1,0]
	v_pk_mul_f32 v[38:39], v[38:39], v[2:3] op_sel_hi:[1,0]
	v_pk_mul_f32 v[8:9], v[8:9], v[2:3] op_sel_hi:[1,0]
	v_pk_mul_f32 v[10:11], v[10:11], v[2:3] op_sel_hi:[1,0]
	v_pk_mul_f32 v[4:5], v[4:5], v[2:3] op_sel_hi:[1,0]
	v_pk_mul_f32 v[6:7], v[6:7], v[2:3] op_sel_hi:[1,0]
	v_pk_mul_f32 v[40:41], v[40:41], v[176:177]
	v_pk_mul_f32 v[42:43], v[42:43], v[178:179]
	v_pk_mul_f32 v[36:37], v[36:37], v[206:207]
	v_pk_mul_f32 v[38:39], v[38:39], v[208:209]
	v_pk_mul_f32 v[8:9], v[8:9], v[224:225]
	v_pk_mul_f32 v[10:11], v[10:11], v[226:227]
	v_pk_mul_f32 v[4:5], v[4:5], v[228:229]
	v_pk_mul_f32 v[6:7], v[6:7], v[230:231]
	v_cvt_pk_f16_f32 v160, v40, v41
	v_cvt_pk_f16_f32 v161, v42, v43
	v_cvt_pk_f16_f32 v162, v36, v37
	v_cvt_pk_f16_f32 v163, v38, v39
	global_store_dwordx4 v133, v[160:163], s[6:7]
	v_cvt_pk_f16_f32 v164, v8, v9
	v_cvt_pk_f16_f32 v165, v10, v11
	v_cvt_pk_f16_f32 v166, v4, v5
	v_cvt_pk_f16_f32 v167, v6, v7
	global_store_dwordx4 v133, v[164:167], s[6:7] offset:2048
	s_branch .Lepi_done_g1
; #define LAS __attribute__((address_space(3)))
; #define GAS __attribute__((address_space(1)))
;     __device__ __forceinline__ void operator()(const f32x4 (&acc)[2][2][4][2], const Unit& u, int wr, int wc, int fr, int fq) const {
;     ...
;         if (sec == 4 || sec == 5) {
;             const GAS float* g = (sec == 4) ? gq : gk;
; #pragma unroll
;             for (int bj = 0; bj < 2; ++bj)
; #pragma unroll
;                 for (int n = 0; n < 2; ++n) gain[bj][n] = *(const GAS f32x4*)(g + 32 * bj + 8 * fq + 4 * n);
;         }
;         const LAS int* tags = (const LAS int*)(rsc + 2048);
;         const int slot = (tags[0] == u.pm) ? 0 : (tags[1] == u.pm) ? 1 : -1;
;         const LAS float* rtab = (const LAS float*)rsc + (slot > 0 ? 256 : 0) + wr * 64 + fr;
; #pragma unroll
;         for (int ai = 0; ai < 2; ++ai)
; #pragma unroll
;             for (int m = 0; m < 4; ++m) {
;                 const int row = row0 + ai * HALF + m * 16;
;                 float rs;
;                 if (slot >= 0) rs = rtab[ai * HALF + m * 16];
;                 else {
;                     const f32x4 pv = *(const GAS f32x4*)(part + (size_t)row * 16 + fq * 4);
;                     float s = (pv[0] + pv[1]) + (pv[2] + pv[3]);
;                     s = row4_sum(s);
;                     rs = __builtin_amdgcn_rsqf(s * (1.0f / DM) + RMS_EPS);
;                 }
;                 f32x4 v[2][2];
; #pragma unroll
;                 for (int bj = 0; bj < 2; ++bj)
; #pragma unroll
;                     for (int n = 0; n < 2; ++n) v[bj][n] = acc[ai][bj][m][n] * rs;
;                 if (sec == 4 || sec == 5) {
;                     float ss = 0.f;
; #pragma unroll
;                     for (int bj = 0; bj < 2; ++bj)
; #pragma unroll
;                         for (int n = 0; n < 2; ++n) { const f32x4 x = v[bj][n]; ss += (x[0] * x[0] + x[1] * x[1]) + (x[2] * x[2] + x[3] * x[3]); }
;                     ss = row4_sum(ss);
;                     float rn = __builtin_amdgcn_rsqf(ss * (1.0f / 64.0f) + RMS_EPS);
;                     if (sec == 4) rn *= QS;
; #pragma unroll
;                     for (int bj = 0; bj < 2; ++bj)
; #pragma unroll
;                         for (int n = 0; n < 2; ++n) v[bj][n] = v[bj][n] * rn * gain[bj][n];
.Lepi_kn:
	s_and_b32 s0, s70, 1
	s_lshl_b32 s0, s0, 10
	v_add_u32_e32 v132, s0, v219
	ds_read_b32 v134, v132
	ds_read_b32 v136, v132 offset:64
	ds_read_b32 v138, v132 offset:128
	ds_read_b32 v140, v132 offset:192
	ds_read_b32 v142, v132 offset:512
	ds_read_b32 v144, v132 offset:576
	ds_read_b32 v146, v132 offset:640
	ds_read_b32 v148, v132 offset:704
	s_lshr_b32 s0, s69, 2
	s_and_b32 s1, s69, 1
	v_lshl_add_u32 v133, s68, 8, v187
	v_lshlrev_b32_e32 v133, 12, v133
	v_lshl_add_u32 v133, v220, 1, v133
	s_lshl_b32 s0, s0, 10
	s_lshl_b32 s1, s1, 9
	s_add_u32 s0, s0, s1
	s_add_u32 s4, s8, s0
	s_addc_u32 s5, s9, 0
	v_readlane_b32 s10, v252, 19
	v_readlane_b32 s11, v252, 20
	s_lshl_b32 s0, s22, 2
	s_nop 0
	s_add_u32 s10, s10, s0
	s_addc_u32 s11, s11, 0
	s_nop 3
	global_load_dwordx4 v[176:179], v222, s[10:11]
	global_load_dwordx4 v[206:209], v222, s[10:11] offset:16
	global_load_dwordx4 v[224:227], v222, s[10:11] offset:128
	global_load_dwordx4 v[228:231], v222, s[10:11] offset:144
	s_waitcnt vmcnt(0)
	s_waitcnt lgkmcnt(0)
	s_mov_b32 s6, s4
	s_mov_b32 s7, s5
	v_pk_mul_f32 v[128:129], v[128:129], v[134:135] op_sel_hi:[1,0]
	v_pk_mul_f32 v[130:131], v[130:131], v[134:135] op_sel_hi:[1,0]
	v_pk_mul_f32 v[124:125], v[124:125], v[134:135] op_sel_hi:[1,0]
	v_pk_mul_f32 v[126:127], v[126:127], v[134:135] op_sel_hi:[1,0]
	v_pk_mul_f32 v[96:97], v[96:97], v[134:135] op_sel_hi:[1,0]
	v_pk_mul_f32 v[98:99], v[98:99], v[134:135] op_sel_hi:[1,0]
	v_pk_mul_f32 v[92:93], v[92:93], v[134:135] op_sel_hi:[1,0]
	v_pk_mul_f32 v[94:95], v[94:95], v[134:135] op_sel_hi:[1,0]
	v_mul_f32_e32 v2, v128, v128
	v_mul_f32_e32 v150, v129, v129
	v_fmac_f32_e32 v2, v130, v130
	v_fmac_f32_e32 v150, v131, v131
	v_fmac_f32_e32 v2, v124, v124
	v_fmac_f32_e32 v150, v125, v125
	v_fmac_f32_e32 v2, v126, v126
	v_fmac_f32_e32 v150, v127, v127
	v_fmac_f32_e32 v2, v96, v96
	v_fmac_f32_e32 v150, v97, v97
	v_fmac_f32_e32 v2, v98, v98
	v_fmac_f32_e32 v150, v99, v99
	v_fmac_f32_e32 v2, v92, v92
	v_fmac_f32_e32 v150, v93, v93
	v_fmac_f32_e32 v2, v94, v94
	v_fmac_f32_e32 v150, v95, v95
	v_add_f32_e32 v2, v2, v150
	v_mov_b32_e32 v150, v2
	s_nop 1
	v_permlane16_swap_b32_e32 v2, v150
	v_add_f32_e32 v2, v2, v150
	v_mov_b32_e32 v150, v2
	s_nop 1
	v_permlane32_swap_b32_e32 v2, v150
	v_add_f32_e32 v2, v2, v150
	v_fmamk_f32 v2, v2, 0x3c800000, v211
	v_rsq_f32_e32 v2, v2
	s_nop 0
	v_pk_mul_f32 v[128:129], v[128:129], v[2:3] op_sel_hi:[1,0]
	v_pk_mul_f32 v[130:131], v[130:131], v[2:3] op_sel_hi:[1,0]
	v_pk_mul_f32 v[124:125], v[124:125], v[2:3] op_sel_hi:[1,0]
	v_pk_mul_f32 v[126:127], v[126:127], v[2:3] op_sel_hi:[1,0]
	v_pk_mul_f32 v[96:97], v[96:97], v[2:3] op_sel_hi:[1,0]
	v_pk_mul_f32 v[98:99], v[98:99], v[2:3] op_sel_hi:[1,0]
	v_pk_mul_f32 v[92:93], v[92:93], v[2:3] op_sel_hi:[1,0]
	v_pk_mul_f32 v[94:95], v[94:95], v[2:3] op_sel_hi:[1,0]
	v_pk_mul_f32 v[128:129], v[128:129], v[176:177]
	v_pk_mul_f32 v[130:131], v[130:131], v[178:179]
	v_pk_mul_f32 v[124:125], v[124:125], v[206:207]
	v_pk_mul_f32 v[126:127], v[126:127], v[208:209]
	v_pk_mul_f32 v[96:97], v[96:97], v[224:225]
	v_pk_mul_f32 v[98:99], v[98:99], v[226:227]
	v_pk_mul_f32 v[92:93], v[92:93], v[228:229]
	v_pk_mul_f32 v[94:95], v[94:95], v[230:231]
	v_cvt_pk_f16_f32 v152, v128, v129
	v_cvt_pk_f16_f32 v153, v130, v131
	v_cvt_pk_f16_f32 v154, v124, v125
	v_cvt_pk_f16_f32 v155, v126, v127
	global_store_dwordx4 v133, v[152:155], s[6:7]
	v_cvt_pk_f16_f32 v156, v96, v97
	v_cvt_pk_f16_f32 v157, v98, v99
	v_cvt_pk_f16_f32 v158, v92, v93
	v_cvt_pk_f16_f32 v159, v94, v95
	global_store_dwordx4 v133, v[156:159], s[6:7] offset:64
	s_add_u32 s6, s4, 0x10000
	s_addc_u32 s7, s5, 0
	v_pk_mul_f32 v[120:121], v[120:121], v[136:137] op_sel_hi:[1,0]
	v_pk_mul_f32 v[122:123], v[122:123], v[136:137] op_sel_hi:[1,0]
	v_pk_mul_f32 v[116:117], v[116:117], v[136:137] op_sel_hi:[1,0]
	v_pk_mul_f32 v[118:119], v[118:119], v[136:137] op_sel_hi:[1,0]
	v_pk_mul_f32 v[88:89], v[88:89], v[136:137] op_sel_hi:[1,0]
	v_pk_mul_f32 v[90:91], v[90:91], v[136:137] op_sel_hi:[1,0]
	v_pk_mul_f32 v[84:85], v[84:85], v[136:137] op_sel_hi:[1,0]
	v_pk_mul_f32 v[86:87], v[86:87], v[136:137] op_sel_hi:[1,0]
	v_mul_f32_e32 v2, v120, v120
	v_mul_f32_e32 v150, v121, v121
	v_fmac_f32_e32 v2, v122, v122
	v_fmac_f32_e32 v150, v123, v123
	v_fmac_f32_e32 v2, v116, v116
	v_fmac_f32_e32 v150, v117, v117
	v_fmac_f32_e32 v2, v118, v118
	v_fmac_f32_e32 v150, v119, v119
	v_fmac_f32_e32 v2, v88, v88
	v_fmac_f32_e32 v150, v89, v89
	v_fmac_f32_e32 v2, v90, v90
	v_fmac_f32_e32 v150, v91, v91
	v_fmac_f32_e32 v2, v84, v84
	v_fmac_f32_e32 v150, v85, v85
	v_fmac_f32_e32 v2, v86, v86
	v_fmac_f32_e32 v150, v87, v87
	v_add_f32_e32 v2, v2, v150
	v_mov_b32_e32 v150, v2
	s_nop 1
	v_permlane16_swap_b32_e32 v2, v150
	v_add_f32_e32 v2, v2, v150
	v_mov_b32_e32 v150, v2
	s_nop 1
	v_permlane32_swap_b32_e32 v2, v150
	v_add_f32_e32 v2, v2, v150
	v_fmamk_f32 v2, v2, 0x3c800000, v211
	v_rsq_f32_e32 v2, v2
	s_nop 0
	v_pk_mul_f32 v[120:121], v[120:121], v[2:3] op_sel_hi:[1,0]
	v_pk_mul_f32 v[122:123], v[122:123], v[2:3] op_sel_hi:[1,0]
	v_pk_mul_f32 v[116:117], v[116:117], v[2:3] op_sel_hi:[1,0]
	v_pk_mul_f32 v[118:119], v[118:119], v[2:3] op_sel_hi:[1,0]
	v_pk_mul_f32 v[88:89], v[88:89], v[2:3] op_sel_hi:[1,0]
	v_pk_mul_f32 v[90:91], v[90:91], v[2:3] op_sel_hi:[1,0]
	v_pk_mul_f32 v[84:85], v[84:85], v[2:3] op_sel_hi:[1,0]
	v_pk_mul_f32 v[86:87], v[86:87], v[2:3] op_sel_hi:[1,0]
	v_pk_mul_f32 v[120:121], v[120:121], v[176:177]
	v_pk_mul_f32 v[122:123], v[122:123], v[178:179]
	v_pk_mul_f32 v[116:117], v[116:117], v[206:207]
	v_pk_mul_f32 v[118:119], v[118:119], v[208:209]
	v_pk_mul_f32 v[88:89], v[88:89], v[224:225]
; #define GAS __attribute__((address_space(1)))
; __host__ __device__ __forceinline__ size_t bl512(size_t row, int col) { return ((row >> 5) * 64 + (size_t)(col >> 3)) * 256 + (row & 31) * 8 + (col & 7); }
; __device__ __forceinline__ float silu_f(float v) { return v * __builtin_amdgcn_rcpf(1.0f + __builtin_amdgcn_exp2f(-v * LOG2E)); }
;     __device__ __forceinline__ void operator()(const f32x4 (&acc)[2][2][4][2], const Unit& u, int wr, int wc, int fr, int fq) const {
;     ...
;                 if (sec == 4 || sec == 5) {
;                     float ss = 0.f;
; #pragma unroll
;                     for (int bj = 0; bj < 2; ++bj)
; #pragma unroll
;                         for (int n = 0; n < 2; ++n) { const f32x4 x = v[bj][n]; ss += (x[0] * x[0] + x[1] * x[1]) + (x[2] * x[2] + x[3] * x[3]); }
;                     ss = row4_sum(ss);
;                     float rn = __builtin_amdgcn_rsqf(ss * (1.0f / 64.0f) + RMS_EPS);
;                     if (sec == 4) rn *= QS;
; #pragma unroll
;                     for (int bj = 0; bj < 2; ++bj)
; #pragma unroll
;                         for (int n = 0; n < 2; ++n) v[bj][n] = v[bj][n] * rn * gain[bj][n];
;                 } else if (sec == 0) {
; #pragma unroll
;                     for (int bj = 0; bj < 2; ++bj)
; #pragma unroll
;                         for (int n = 0; n < 2; ++n) v[bj][n] = v[bj][n] * QS;
;                 } else if (sec == 3 || sec == 7) {
; #pragma unroll
;                     for (int bj = 0; bj < 2; ++bj)
; #pragma unroll
;                         for (int n = 0; n < 2; ++n)
; #pragma unroll
;                             for (int e = 0; e < 4; ++e) v[bj][n][e] = silu_f(v[bj][n][e]);
;                 }
;                 GAS f16* rowp = isqg ? QG + (size_t)dsec * QG_SEC + bl512((size_t)row, cs) : KV + (size_t)row * KVW + dsec * 512 + cs;
; #pragma unroll
;                 for (int bj = 0; bj < 2; ++bj) {
;                     u32x4 w; w.x = pkh(v[bj][0][0], v[bj][0][1]); w.y = pkh(v[bj][0][2], v[bj][0][3]); w.z = pkh(v[bj][1][0], v[bj][1][1]); w.w = pkh(v[bj][1][2], v[bj][1][3]);
;                     *(GAS u32x4*)(rowp + bjstep * bj) = w;
;                 }
	v_pk_mul_f32 v[90:91], v[90:91], v[226:227]
	v_pk_mul_f32 v[84:85], v[84:85], v[228:229]
	v_pk_mul_f32 v[86:87], v[86:87], v[230:231]
	v_cvt_pk_f16_f32 v160, v120, v121
	v_cvt_pk_f16_f32 v161, v122, v123
	v_cvt_pk_f16_f32 v162, v116, v117
	v_cvt_pk_f16_f32 v163, v118, v119
	global_store_dwordx4 v133, v[160:163], s[6:7]
	v_cvt_pk_f16_f32 v164, v88, v89
	v_cvt_pk_f16_f32 v165, v90, v91
	v_cvt_pk_f16_f32 v166, v84, v85
	v_cvt_pk_f16_f32 v167, v86, v87
	global_store_dwordx4 v133, v[164:167], s[6:7] offset:64
	s_add_u32 s6, s4, 0x20000
	s_addc_u32 s7, s5, 0
	v_pk_mul_f32 v[112:113], v[112:113], v[138:139] op_sel_hi:[1,0]
	v_pk_mul_f32 v[114:115], v[114:115], v[138:139] op_sel_hi:[1,0]
	v_pk_mul_f32 v[108:109], v[108:109], v[138:139] op_sel_hi:[1,0]
	v_pk_mul_f32 v[110:111], v[110:111], v[138:139] op_sel_hi:[1,0]
	v_pk_mul_f32 v[80:81], v[80:81], v[138:139] op_sel_hi:[1,0]
	v_pk_mul_f32 v[82:83], v[82:83], v[138:139] op_sel_hi:[1,0]
	v_pk_mul_f32 v[76:77], v[76:77], v[138:139] op_sel_hi:[1,0]
	v_pk_mul_f32 v[78:79], v[78:79], v[138:139] op_sel_hi:[1,0]
	v_mul_f32_e32 v2, v112, v112
	v_mul_f32_e32 v150, v113, v113
	v_fmac_f32_e32 v2, v114, v114
	v_fmac_f32_e32 v150, v115, v115
	v_fmac_f32_e32 v2, v108, v108
	v_fmac_f32_e32 v150, v109, v109
	v_fmac_f32_e32 v2, v110, v110
	v_fmac_f32_e32 v150, v111, v111
	v_fmac_f32_e32 v2, v80, v80
	v_fmac_f32_e32 v150, v81, v81
	v_fmac_f32_e32 v2, v82, v82
	v_fmac_f32_e32 v150, v83, v83
	v_fmac_f32_e32 v2, v76, v76
	v_fmac_f32_e32 v150, v77, v77
	v_fmac_f32_e32 v2, v78, v78
	v_fmac_f32_e32 v150, v79, v79
	v_add_f32_e32 v2, v2, v150
	v_mov_b32_e32 v150, v2
	s_nop 1
	v_permlane16_swap_b32_e32 v2, v150
	v_add_f32_e32 v2, v2, v150
	v_mov_b32_e32 v150, v2
	s_nop 1
	v_permlane32_swap_b32_e32 v2, v150
	v_add_f32_e32 v2, v2, v150
	v_fmamk_f32 v2, v2, 0x3c800000, v211
	v_rsq_f32_e32 v2, v2
	s_nop 0
	v_pk_mul_f32 v[112:113], v[112:113], v[2:3] op_sel_hi:[1,0]
	v_pk_mul_f32 v[114:115], v[114:115], v[2:3] op_sel_hi:[1,0]
	v_pk_mul_f32 v[108:109], v[108:109], v[2:3] op_sel_hi:[1,0]
	v_pk_mul_f32 v[110:111], v[110:111], v[2:3] op_sel_hi:[1,0]
	v_pk_mul_f32 v[80:81], v[80:81], v[2:3] op_sel_hi:[1,0]
	v_pk_mul_f32 v[82:83], v[82:83], v[2:3] op_sel_hi:[1,0]
	v_pk_mul_f32 v[76:77], v[76:77], v[2:3] op_sel_hi:[1,0]
	v_pk_mul_f32 v[78:79], v[78:79], v[2:3] op_sel_hi:[1,0]
	v_pk_mul_f32 v[112:113], v[112:113], v[176:177]
	v_pk_mul_f32 v[114:115], v[114:115], v[178:179]
	v_pk_mul_f32 v[108:109], v[108:109], v[206:207]
	v_pk_mul_f32 v[110:111], v[110:111], v[208:209]
	v_pk_mul_f32 v[80:81], v[80:81], v[224:225]
	v_pk_mul_f32 v[82:83], v[82:83], v[226:227]
	v_pk_mul_f32 v[76:77], v[76:77], v[228:229]
	v_pk_mul_f32 v[78:79], v[78:79], v[230:231]
	v_cvt_pk_f16_f32 v152, v112, v113
	v_cvt_pk_f16_f32 v153, v114, v115
	v_cvt_pk_f16_f32 v154, v108, v109
	v_cvt_pk_f16_f32 v155, v110, v111
	global_store_dwordx4 v133, v[152:155], s[6:7]
	v_cvt_pk_f16_f32 v156, v80, v81
	v_cvt_pk_f16_f32 v157, v82, v83
	v_cvt_pk_f16_f32 v158, v76, v77
	v_cvt_pk_f16_f32 v159, v78, v79
	global_store_dwordx4 v133, v[156:159], s[6:7] offset:64
	s_add_u32 s6, s4, 0x30000
	s_addc_u32 s7, s5, 0
	v_pk_mul_f32 v[104:105], v[104:105], v[140:141] op_sel_hi:[1,0]
	v_pk_mul_f32 v[106:107], v[106:107], v[140:141] op_sel_hi:[1,0]
	v_pk_mul_f32 v[100:101], v[100:101], v[140:141] op_sel_hi:[1,0]
	v_pk_mul_f32 v[102:103], v[102:103], v[140:141] op_sel_hi:[1,0]
	v_pk_mul_f32 v[72:73], v[72:73], v[140:141] op_sel_hi:[1,0]
	v_pk_mul_f32 v[74:75], v[74:75], v[140:141] op_sel_hi:[1,0]
	v_pk_mul_f32 v[68:69], v[68:69], v[140:141] op_sel_hi:[1,0]
	v_pk_mul_f32 v[70:71], v[70:71], v[140:141] op_sel_hi:[1,0]
	v_mul_f32_e32 v2, v104, v104
	v_mul_f32_e32 v150, v105, v105
	v_fmac_f32_e32 v2, v106, v106
	v_fmac_f32_e32 v150, v107, v107
	v_fmac_f32_e32 v2, v100, v100
	v_fmac_f32_e32 v150, v101, v101
	v_fmac_f32_e32 v2, v102, v102
	v_fmac_f32_e32 v150, v103, v103
	v_fmac_f32_e32 v2, v72, v72
	v_fmac_f32_e32 v150, v73, v73
	v_fmac_f32_e32 v2, v74, v74
	v_fmac_f32_e32 v150, v75, v75
	v_fmac_f32_e32 v2, v68, v68
	v_fmac_f32_e32 v150, v69, v69
	v_fmac_f32_e32 v2, v70, v70
	v_fmac_f32_e32 v150, v71, v71
	v_add_f32_e32 v2, v2, v150
	v_mov_b32_e32 v150, v2
	s_nop 1
	v_permlane16_swap_b32_e32 v2, v150
	v_add_f32_e32 v2, v2, v150
	v_mov_b32_e32 v150, v2
	s_nop 1
	v_permlane32_swap_b32_e32 v2, v150
	v_add_f32_e32 v2, v2, v150
	v_fmamk_f32 v2, v2, 0x3c800000, v211
	v_rsq_f32_e32 v2, v2
	s_nop 0
	v_pk_mul_f32 v[104:105], v[104:105], v[2:3] op_sel_hi:[1,0]
	v_pk_mul_f32 v[106:107], v[106:107], v[2:3] op_sel_hi:[1,0]
	v_pk_mul_f32 v[100:101], v[100:101], v[2:3] op_sel_hi:[1,0]
	v_pk_mul_f32 v[102:103], v[102:103], v[2:3] op_sel_hi:[1,0]
	v_pk_mul_f32 v[72:73], v[72:73], v[2:3] op_sel_hi:[1,0]
	v_pk_mul_f32 v[74:75], v[74:75], v[2:3] op_sel_hi:[1,0]
	v_pk_mul_f32 v[68:69], v[68:69], v[2:3] op_sel_hi:[1,0]
	v_pk_mul_f32 v[70:71], v[70:71], v[2:3] op_sel_hi:[1,0]
	v_pk_mul_f32 v[104:105], v[104:105], v[176:177]
	v_pk_mul_f32 v[106:107], v[106:107], v[178:179]
	v_pk_mul_f32 v[100:101], v[100:101], v[206:207]
	v_pk_mul_f32 v[102:103], v[102:103], v[208:209]
	v_pk_mul_f32 v[72:73], v[72:73], v[224:225]
	v_pk_mul_f32 v[74:75], v[74:75], v[226:227]
	v_pk_mul_f32 v[68:69], v[68:69], v[228:229]
	v_pk_mul_f32 v[70:71], v[70:71], v[230:231]
	v_cvt_pk_f16_f32 v160, v104, v105
	v_cvt_pk_f16_f32 v161, v106, v107
	v_cvt_pk_f16_f32 v162, v100, v101
	v_cvt_pk_f16_f32 v163, v102, v103
	global_store_dwordx4 v133, v[160:163], s[6:7]
	v_cvt_pk_f16_f32 v164, v72, v73
	v_cvt_pk_f16_f32 v165, v74, v75
	v_cvt_pk_f16_f32 v166, v68, v69
	v_cvt_pk_f16_f32 v167, v70, v71
	global_store_dwordx4 v133, v[164:167], s[6:7] offset:64
; #define GAS __attribute__((address_space(1)))
; __host__ __device__ __forceinline__ size_t bl512(size_t row, int col) { return ((row >> 5) * 64 + (size_t)(col >> 3)) * 256 + (row & 31) * 8 + (col & 7); }
; __device__ __forceinline__ float silu_f(float v) { return v * __builtin_amdgcn_rcpf(1.0f + __builtin_amdgcn_exp2f(-v * LOG2E)); }
;     __device__ __forceinline__ void operator()(const f32x4 (&acc)[2][2][4][2], const Unit& u, int wr, int wc, int fr, int fq) const {
;     ...
;                 if (sec == 4 || sec == 5) {
;                     float ss = 0.f;
; #pragma unroll
;                     for (int bj = 0; bj < 2; ++bj)
; #pragma unroll
;                         for (int n = 0; n < 2; ++n) { const f32x4 x = v[bj][n]; ss += (x[0] * x[0] + x[1] * x[1]) + (x[2] * x[2] + x[3] * x[3]); }
;                     ss = row4_sum(ss);
;                     float rn = __builtin_amdgcn_rsqf(ss * (1.0f / 64.0f) + RMS_EPS);
;                     if (sec == 4) rn *= QS;
; #pragma unroll
;                     for (int bj = 0; bj < 2; ++bj)
; #pragma unroll
;                         for (int n = 0; n < 2; ++n) v[bj][n] = v[bj][n] * rn * gain[bj][n];
;                 } else if (sec == 0) {
; #pragma unroll
;                     for (int bj = 0; bj < 2; ++bj)
; #pragma unroll
;                         for (int n = 0; n < 2; ++n) v[bj][n] = v[bj][n] * QS;
;                 } else if (sec == 3 || sec == 7) {
; #pragma unroll
;                     for (int bj = 0; bj < 2; ++bj)
; #pragma unroll
;                         for (int n = 0; n < 2; ++n)
; #pragma unroll
;                             for (int e = 0; e < 4; ++e) v[bj][n][e] = silu_f(v[bj][n][e]);
;                 }
;                 GAS f16* rowp = isqg ? QG + (size_t)dsec * QG_SEC + bl512((size_t)row, cs) : KV + (size_t)row * KVW + dsec * 512 + cs;
; #pragma unroll
;                 for (int bj = 0; bj < 2; ++bj) {
;                     u32x4 w; w.x = pkh(v[bj][0][0], v[bj][0][1]); w.y = pkh(v[bj][0][2], v[bj][0][3]); w.z = pkh(v[bj][1][0], v[bj][1][1]); w.w = pkh(v[bj][1][2], v[bj][1][3]);
;                     *(GAS u32x4*)(rowp + bjstep * bj) = w;
;                 }
	s_add_u32 s6, s4, 0x80000
	s_addc_u32 s7, s5, 0
	v_pk_mul_f32 v[64:65], v[64:65], v[142:143] op_sel_hi:[1,0]
	v_pk_mul_f32 v[66:67], v[66:67], v[142:143] op_sel_hi:[1,0]
	v_pk_mul_f32 v[60:61], v[60:61], v[142:143] op_sel_hi:[1,0]
	v_pk_mul_f32 v[62:63], v[62:63], v[142:143] op_sel_hi:[1,0]
	v_pk_mul_f32 v[32:33], v[32:33], v[142:143] op_sel_hi:[1,0]
	v_pk_mul_f32 v[34:35], v[34:35], v[142:143] op_sel_hi:[1,0]
	v_pk_mul_f32 v[28:29], v[28:29], v[142:143] op_sel_hi:[1,0]
	v_pk_mul_f32 v[30:31], v[30:31], v[142:143] op_sel_hi:[1,0]
	v_mul_f32_e32 v2, v64, v64
	v_mul_f32_e32 v150, v65, v65
	v_fmac_f32_e32 v2, v66, v66
	v_fmac_f32_e32 v150, v67, v67
	v_fmac_f32_e32 v2, v60, v60
	v_fmac_f32_e32 v150, v61, v61
	v_fmac_f32_e32 v2, v62, v62
	v_fmac_f32_e32 v150, v63, v63
	v_fmac_f32_e32 v2, v32, v32
	v_fmac_f32_e32 v150, v33, v33
	v_fmac_f32_e32 v2, v34, v34
	v_fmac_f32_e32 v150, v35, v35
	v_fmac_f32_e32 v2, v28, v28
	v_fmac_f32_e32 v150, v29, v29
	v_fmac_f32_e32 v2, v30, v30
	v_fmac_f32_e32 v150, v31, v31
	v_add_f32_e32 v2, v2, v150
	v_mov_b32_e32 v150, v2
	s_nop 1
	v_permlane16_swap_b32_e32 v2, v150
	v_add_f32_e32 v2, v2, v150
	v_mov_b32_e32 v150, v2
	s_nop 1
	v_permlane32_swap_b32_e32 v2, v150
	v_add_f32_e32 v2, v2, v150
	v_fmamk_f32 v2, v2, 0x3c800000, v211
	v_rsq_f32_e32 v2, v2
	s_nop 0
	v_pk_mul_f32 v[64:65], v[64:65], v[2:3] op_sel_hi:[1,0]
	v_pk_mul_f32 v[66:67], v[66:67], v[2:3] op_sel_hi:[1,0]
	v_pk_mul_f32 v[60:61], v[60:61], v[2:3] op_sel_hi:[1,0]
	v_pk_mul_f32 v[62:63], v[62:63], v[2:3] op_sel_hi:[1,0]
	v_pk_mul_f32 v[32:33], v[32:33], v[2:3] op_sel_hi:[1,0]
	v_pk_mul_f32 v[34:35], v[34:35], v[2:3] op_sel_hi:[1,0]
	v_pk_mul_f32 v[28:29], v[28:29], v[2:3] op_sel_hi:[1,0]
	v_pk_mul_f32 v[30:31], v[30:31], v[2:3] op_sel_hi:[1,0]
	v_pk_mul_f32 v[64:65], v[64:65], v[176:177]
	v_pk_mul_f32 v[66:67], v[66:67], v[178:179]
	v_pk_mul_f32 v[60:61], v[60:61], v[206:207]
	v_pk_mul_f32 v[62:63], v[62:63], v[208:209]
	v_pk_mul_f32 v[32:33], v[32:33], v[224:225]
	v_pk_mul_f32 v[34:35], v[34:35], v[226:227]
	v_pk_mul_f32 v[28:29], v[28:29], v[228:229]
	v_pk_mul_f32 v[30:31], v[30:31], v[230:231]
	v_cvt_pk_f16_f32 v152, v64, v65
	v_cvt_pk_f16_f32 v153, v66, v67
	v_cvt_pk_f16_f32 v154, v60, v61
	v_cvt_pk_f16_f32 v155, v62, v63
	global_store_dwordx4 v133, v[152:155], s[6:7]
	v_cvt_pk_f16_f32 v156, v32, v33
	v_cvt_pk_f16_f32 v157, v34, v35
	v_cvt_pk_f16_f32 v158, v28, v29
	v_cvt_pk_f16_f32 v159, v30, v31
	global_store_dwordx4 v133, v[156:159], s[6:7] offset:64
	s_add_u32 s6, s4, 0x90000
	s_addc_u32 s7, s5, 0
	v_pk_mul_f32 v[56:57], v[56:57], v[144:145] op_sel_hi:[1,0]
	v_pk_mul_f32 v[58:59], v[58:59], v[144:145] op_sel_hi:[1,0]
	v_pk_mul_f32 v[52:53], v[52:53], v[144:145] op_sel_hi:[1,0]
	v_pk_mul_f32 v[54:55], v[54:55], v[144:145] op_sel_hi:[1,0]
	v_pk_mul_f32 v[24:25], v[24:25], v[144:145] op_sel_hi:[1,0]
	v_pk_mul_f32 v[26:27], v[26:27], v[144:145] op_sel_hi:[1,0]
	v_pk_mul_f32 v[20:21], v[20:21], v[144:145] op_sel_hi:[1,0]
	v_pk_mul_f32 v[22:23], v[22:23], v[144:145] op_sel_hi:[1,0]
	v_mul_f32_e32 v2, v56, v56
	v_mul_f32_e32 v150, v57, v57
	v_fmac_f32_e32 v2, v58, v58
	v_fmac_f32_e32 v150, v59, v59
	v_fmac_f32_e32 v2, v52, v52
	v_fmac_f32_e32 v150, v53, v53
	v_fmac_f32_e32 v2, v54, v54
	v_fmac_f32_e32 v150, v55, v55
	v_fmac_f32_e32 v2, v24, v24
	v_fmac_f32_e32 v150, v25, v25
	v_fmac_f32_e32 v2, v26, v26
	v_fmac_f32_e32 v150, v27, v27
	v_fmac_f32_e32 v2, v20, v20
	v_fmac_f32_e32 v150, v21, v21
	v_fmac_f32_e32 v2, v22, v22
	v_fmac_f32_e32 v150, v23, v23
	v_add_f32_e32 v2, v2, v150
	v_mov_b32_e32 v150, v2
	s_nop 1
	v_permlane16_swap_b32_e32 v2, v150
	v_add_f32_e32 v2, v2, v150
	v_mov_b32_e32 v150, v2
	s_nop 1
	v_permlane32_swap_b32_e32 v2, v150
	v_add_f32_e32 v2, v2, v150
	v_fmamk_f32 v2, v2, 0x3c800000, v211
	v_rsq_f32_e32 v2, v2
	s_nop 0
	v_pk_mul_f32 v[56:57], v[56:57], v[2:3] op_sel_hi:[1,0]
	v_pk_mul_f32 v[58:59], v[58:59], v[2:3] op_sel_hi:[1,0]
	v_pk_mul_f32 v[52:53], v[52:53], v[2:3] op_sel_hi:[1,0]
	v_pk_mul_f32 v[54:55], v[54:55], v[2:3] op_sel_hi:[1,0]
	v_pk_mul_f32 v[24:25], v[24:25], v[2:3] op_sel_hi:[1,0]
	v_pk_mul_f32 v[26:27], v[26:27], v[2:3] op_sel_hi:[1,0]
	v_pk_mul_f32 v[20:21], v[20:21], v[2:3] op_sel_hi:[1,0]
	v_pk_mul_f32 v[22:23], v[22:23], v[2:3] op_sel_hi:[1,0]
	v_pk_mul_f32 v[56:57], v[56:57], v[176:177]
	v_pk_mul_f32 v[58:59], v[58:59], v[178:179]
	v_pk_mul_f32 v[52:53], v[52:53], v[206:207]
	v_pk_mul_f32 v[54:55], v[54:55], v[208:209]
	v_pk_mul_f32 v[24:25], v[24:25], v[224:225]
	v_pk_mul_f32 v[26:27], v[26:27], v[226:227]
	v_pk_mul_f32 v[20:21], v[20:21], v[228:229]
	v_pk_mul_f32 v[22:23], v[22:23], v[230:231]
	v_cvt_pk_f16_f32 v160, v56, v57
	v_cvt_pk_f16_f32 v161, v58, v59
	v_cvt_pk_f16_f32 v162, v52, v53
	v_cvt_pk_f16_f32 v163, v54, v55
	global_store_dwordx4 v133, v[160:163], s[6:7]
	v_cvt_pk_f16_f32 v164, v24, v25
	v_cvt_pk_f16_f32 v165, v26, v27
	v_cvt_pk_f16_f32 v166, v20, v21
	v_cvt_pk_f16_f32 v167, v22, v23
	global_store_dwordx4 v133, v[164:167], s[6:7] offset:64
	s_add_u32 s6, s4, 0xa0000
	s_addc_u32 s7, s5, 0
; #define GAS __attribute__((address_space(1)))
; __host__ __device__ __forceinline__ size_t bl512(size_t row, int col) { return ((row >> 5) * 64 + (size_t)(col >> 3)) * 256 + (row & 31) * 8 + (col & 7); }
; __device__ __forceinline__ float silu_f(float v) { return v * __builtin_amdgcn_rcpf(1.0f + __builtin_amdgcn_exp2f(-v * LOG2E)); }
;     __device__ __forceinline__ void operator()(const f32x4 (&acc)[2][2][4][2], const Unit& u, int wr, int wc, int fr, int fq) const {
;     ...
;                     for (int n = 0; n < 2; ++n) v[bj][n] = acc[ai][bj][m][n] * rs;
;                 if (sec == 4 || sec == 5) {
;                     float ss = 0.f;
; #pragma unroll
;                     for (int bj = 0; bj < 2; ++bj)
; #pragma unroll
;                         for (int n = 0; n < 2; ++n) { const f32x4 x = v[bj][n]; ss += (x[0] * x[0] + x[1] * x[1]) + (x[2] * x[2] + x[3] * x[3]); }
;                     ss = row4_sum(ss);
;                     float rn = __builtin_amdgcn_rsqf(ss * (1.0f / 64.0f) + RMS_EPS);
;                     if (sec == 4) rn *= QS;
; #pragma unroll
;                     for (int bj = 0; bj < 2; ++bj)
; #pragma unroll
;                         for (int n = 0; n < 2; ++n) v[bj][n] = v[bj][n] * rn * gain[bj][n];
;                 } else if (sec == 0) {
; #pragma unroll
;                     for (int bj = 0; bj < 2; ++bj)
; #pragma unroll
;                         for (int n = 0; n < 2; ++n) v[bj][n] = v[bj][n] * QS;
;                 } else if (sec == 3 || sec == 7) {
; #pragma unroll
;                     for (int bj = 0; bj < 2; ++bj)
; #pragma unroll
;                         for (int n = 0; n < 2; ++n)
; #pragma unroll
;                             for (int e = 0; e < 4; ++e) v[bj][n][e] = silu_f(v[bj][n][e]);
;                 }
;                 GAS f16* rowp = isqg ? QG + (size_t)dsec * QG_SEC + bl512((size_t)row, cs) : KV + (size_t)row * KVW + dsec * 512 + cs;
; #pragma unroll
;                 for (int bj = 0; bj < 2; ++bj) {
;                     u32x4 w; w.x = pkh(v[bj][0][0], v[bj][0][1]); w.y = pkh(v[bj][0][2], v[bj][0][3]); w.z = pkh(v[bj][1][0], v[bj][1][1]); w.w = pkh(v[bj][1][2], v[bj][1][3]);
;                     *(GAS u32x4*)(rowp + bjstep * bj) = w;
;                 }
	v_pk_mul_f32 v[48:49], v[48:49], v[146:147] op_sel_hi:[1,0]
	v_pk_mul_f32 v[50:51], v[50:51], v[146:147] op_sel_hi:[1,0]
	v_pk_mul_f32 v[44:45], v[44:45], v[146:147] op_sel_hi:[1,0]
	v_pk_mul_f32 v[46:47], v[46:47], v[146:147] op_sel_hi:[1,0]
	v_pk_mul_f32 v[16:17], v[16:17], v[146:147] op_sel_hi:[1,0]
	v_pk_mul_f32 v[18:19], v[18:19], v[146:147] op_sel_hi:[1,0]
	v_pk_mul_f32 v[12:13], v[12:13], v[146:147] op_sel_hi:[1,0]
	v_pk_mul_f32 v[14:15], v[14:15], v[146:147] op_sel_hi:[1,0]
	v_mul_f32_e32 v2, v48, v48
	v_mul_f32_e32 v150, v49, v49
	v_fmac_f32_e32 v2, v50, v50
	v_fmac_f32_e32 v150, v51, v51
	v_fmac_f32_e32 v2, v44, v44
	v_fmac_f32_e32 v150, v45, v45
	v_fmac_f32_e32 v2, v46, v46
	v_fmac_f32_e32 v150, v47, v47
	v_fmac_f32_e32 v2, v16, v16
	v_fmac_f32_e32 v150, v17, v17
	v_fmac_f32_e32 v2, v18, v18
	v_fmac_f32_e32 v150, v19, v19
	v_fmac_f32_e32 v2, v12, v12
	v_fmac_f32_e32 v150, v13, v13
	v_fmac_f32_e32 v2, v14, v14
	v_fmac_f32_e32 v150, v15, v15
	v_add_f32_e32 v2, v2, v150
	v_mov_b32_e32 v150, v2
	s_nop 1
	v_permlane16_swap_b32_e32 v2, v150
	v_add_f32_e32 v2, v2, v150
	v_mov_b32_e32 v150, v2
	s_nop 1
	v_permlane32_swap_b32_e32 v2, v150
	v_add_f32_e32 v2, v2, v150
	v_fmamk_f32 v2, v2, 0x3c800000, v211
	v_rsq_f32_e32 v2, v2
	s_nop 0
	v_pk_mul_f32 v[48:49], v[48:49], v[2:3] op_sel_hi:[1,0]
	v_pk_mul_f32 v[50:51], v[50:51], v[2:3] op_sel_hi:[1,0]
	v_pk_mul_f32 v[44:45], v[44:45], v[2:3] op_sel_hi:[1,0]
	v_pk_mul_f32 v[46:47], v[46:47], v[2:3] op_sel_hi:[1,0]
	v_pk_mul_f32 v[16:17], v[16:17], v[2:3] op_sel_hi:[1,0]
	v_pk_mul_f32 v[18:19], v[18:19], v[2:3] op_sel_hi:[1,0]
	v_pk_mul_f32 v[12:13], v[12:13], v[2:3] op_sel_hi:[1,0]
	v_pk_mul_f32 v[14:15], v[14:15], v[2:3] op_sel_hi:[1,0]
	v_pk_mul_f32 v[48:49], v[48:49], v[176:177]
	v_pk_mul_f32 v[50:51], v[50:51], v[178:179]
	v_pk_mul_f32 v[44:45], v[44:45], v[206:207]
	v_pk_mul_f32 v[46:47], v[46:47], v[208:209]
	v_pk_mul_f32 v[16:17], v[16:17], v[224:225]
	v_pk_mul_f32 v[18:19], v[18:19], v[226:227]
	v_pk_mul_f32 v[12:13], v[12:13], v[228:229]
	v_pk_mul_f32 v[14:15], v[14:15], v[230:231]
	v_cvt_pk_f16_f32 v152, v48, v49
	v_cvt_pk_f16_f32 v153, v50, v51
	v_cvt_pk_f16_f32 v154, v44, v45
	v_cvt_pk_f16_f32 v155, v46, v47
	global_store_dwordx4 v133, v[152:155], s[6:7]
	v_cvt_pk_f16_f32 v156, v16, v17
	v_cvt_pk_f16_f32 v157, v18, v19
	v_cvt_pk_f16_f32 v158, v12, v13
	v_cvt_pk_f16_f32 v159, v14, v15
	global_store_dwordx4 v133, v[156:159], s[6:7] offset:64
	s_add_u32 s6, s4, 0xb0000
	s_addc_u32 s7, s5, 0
	v_pk_mul_f32 v[40:41], v[40:41], v[148:149] op_sel_hi:[1,0]
	v_pk_mul_f32 v[42:43], v[42:43], v[148:149] op_sel_hi:[1,0]
	v_pk_mul_f32 v[36:37], v[36:37], v[148:149] op_sel_hi:[1,0]
	v_pk_mul_f32 v[38:39], v[38:39], v[148:149] op_sel_hi:[1,0]
	v_pk_mul_f32 v[8:9], v[8:9], v[148:149] op_sel_hi:[1,0]
	v_pk_mul_f32 v[10:11], v[10:11], v[148:149] op_sel_hi:[1,0]
	v_pk_mul_f32 v[4:5], v[4:5], v[148:149] op_sel_hi:[1,0]
	v_pk_mul_f32 v[6:7], v[6:7], v[148:149] op_sel_hi:[1,0]
	v_mul_f32_e32 v2, v40, v40
	v_mul_f32_e32 v150, v41, v41
	v_fmac_f32_e32 v2, v42, v42
	v_fmac_f32_e32 v150, v43, v43
	v_fmac_f32_e32 v2, v36, v36
	v_fmac_f32_e32 v150, v37, v37
	v_fmac_f32_e32 v2, v38, v38
	v_fmac_f32_e32 v150, v39, v39
	v_fmac_f32_e32 v2, v8, v8
	v_fmac_f32_e32 v150, v9, v9
	v_fmac_f32_e32 v2, v10, v10
	v_fmac_f32_e32 v150, v11, v11
	v_fmac_f32_e32 v2, v4, v4
	v_fmac_f32_e32 v150, v5, v5
	v_fmac_f32_e32 v2, v6, v6
	v_fmac_f32_e32 v150, v7, v7
	v_add_f32_e32 v2, v2, v150
	v_mov_b32_e32 v150, v2
	s_nop 1
	v_permlane16_swap_b32_e32 v2, v150
	v_add_f32_e32 v2, v2, v150
	v_mov_b32_e32 v150, v2
	s_nop 1
	v_permlane32_swap_b32_e32 v2, v150
	v_add_f32_e32 v2, v2, v150
	v_fmamk_f32 v2, v2, 0x3c800000, v211
	v_rsq_f32_e32 v2, v2
	s_nop 0
	v_pk_mul_f32 v[40:41], v[40:41], v[2:3] op_sel_hi:[1,0]
	v_pk_mul_f32 v[42:43], v[42:43], v[2:3] op_sel_hi:[1,0]
	v_pk_mul_f32 v[36:37], v[36:37], v[2:3] op_sel_hi:[1,0]
	v_pk_mul_f32 v[38:39], v[38:39], v[2:3] op_sel_hi:[1,0]
	v_pk_mul_f32 v[8:9], v[8:9], v[2:3] op_sel_hi:[1,0]
	v_pk_mul_f32 v[10:11], v[10:11], v[2:3] op_sel_hi:[1,0]
	v_pk_mul_f32 v[4:5], v[4:5], v[2:3] op_sel_hi:[1,0]
	v_pk_mul_f32 v[6:7], v[6:7], v[2:3] op_sel_hi:[1,0]
	v_pk_mul_f32 v[40:41], v[40:41], v[176:177]
	v_pk_mul_f32 v[42:43], v[42:43], v[178:179]
	v_pk_mul_f32 v[36:37], v[36:37], v[206:207]
	v_pk_mul_f32 v[38:39], v[38:39], v[208:209]
	v_pk_mul_f32 v[8:9], v[8:9], v[224:225]
	v_pk_mul_f32 v[10:11], v[10:11], v[226:227]
	v_pk_mul_f32 v[4:5], v[4:5], v[228:229]
	v_pk_mul_f32 v[6:7], v[6:7], v[230:231]
	v_cvt_pk_f16_f32 v160, v40, v41
	v_cvt_pk_f16_f32 v161, v42, v43
	v_cvt_pk_f16_f32 v162, v36, v37
	v_cvt_pk_f16_f32 v163, v38, v39
	global_store_dwordx4 v133, v[160:163], s[6:7]
	v_cvt_pk_f16_f32 v164, v8, v9
	v_cvt_pk_f16_f32 v165, v10, v11
	v_cvt_pk_f16_f32 v166, v4, v5
	v_cvt_pk_f16_f32 v167, v6, v7
	global_store_dwordx4 v133, v[164:167], s[6:7] offset:64
	s_branch .Lepi_done_g1
.Lepi_done_g1:
	s_add_u32 s4, s72, 0xffffff00
	s_addc_u32 s5, s73, -1
	s_andn2_b64 vcc, exec, s[66:67]
	s_cbranch_vccnz .LBB0_377
	s_branch .Lepi_tail_g1

; #define PG8_STAGE(bufoff, gbase, voff) do { _Pragma("unroll") for (int _i = 0; _i < 2; ++_i) \
;         __builtin_amdgcn_global_load_lds((const unsigned*)((const char*)(gbase) + (voff)[_i]), (LAS unsigned*)(lds + (bufoff) + ldsw + _i * 8192), 16, 0, 0); } while (0)
; #define PG8_LDA(dst, b, h) do { _Pragma("unroll") for (int m = 0; m < 4; ++m) _Pragma("unroll") for (int k = 0; k < 2; ++k) dst[m][k] = *(const LAS h8*)(lds + PG8_SA(b, h) + aoff + m * 2048 + k * 1024); } while (0)
; #define PG8_LDB(dst, b, h) do { _Pragma("unroll") for (int n = 0; n < 2; ++n) _Pragma("unroll") for (int k = 0; k < 2; ++k) dst[n][k] = *(const LAS h8*)(lds + PG8_SB(b, h) + boff + n * 2048 + k * 1024); } while (0)
; #define PG8_MMA(ai, bj, At, Bt) do { __builtin_amdgcn_s_setprio(1); _Pragma("unroll") for (int m = 0; m < 4; ++m) _Pragma("unroll") for (int n = 0; n < 2; ++n) _Pragma("unroll") for (int k = 0; k < 2; ++k) \
;         acc[ai][bj][m][n] = __builtin_amdgcn_mfma_f32_16x16x32_f16(Bt[n][k], At[m][k], acc[ai][bj][m][n], 0, 0, 0); __builtin_amdgcn_s_setprio(0); } while (0)
; #define PG8_WAIT_V(n) asm volatile("s_waitcnt vmcnt(" #n ")" ::: "memory")
; #define PG8_WAIT_L(n) asm volatile("s_waitcnt lgkmcnt(" #n ")" ::: "memory")
; #define PG8_BAR __builtin_amdgcn_s_barrier()
; #define PG8_SCHED __builtin_amdgcn_sched_barrier(0)
; template <class Epi>
; __device__ __forceinline__ void gemm_phase(LAS unsigned char* lds, const Gemm g, const StaticOrder& S, const Epi& E, unsigned long long& sw_acc) {
;     ...
;             PG8_LDB(B0, 0, 0); PG8_LDB(B1, 0, 1); PG8_SCHED; PG8_LDA(At, 0, 0); PG8_STAGE(PG8_SA(1, 1), a1 + hstep, voffA);
;             PG8_WAIT_V(8); PG8_WAIT_L(0); PG8_BAR; PG8_MMA(0, 0, At, B0); PG8_MMA(0, 1, At, B1); PG8_BAR; PG8_SCHED;
;             PG8_LDA(At, 0, 1); PG8_STAGE(PG8_SB(0, 0), b2, voffB); PG8_STAGE(PG8_SB(0, 1), b2 + hstepB, voffB); PG8_STAGE(PG8_SA(0, 0), a2, voffA);
;             PG8_WAIT_V(8); PG8_WAIT_L(0); PG8_BAR; PG8_MMA(1, 0, At, B0); PG8_MMA(1, 1, At, B1); PG8_BAR; PG8_SCHED;
.LBB0_700:
	s_add_u32 s18, s6, 0xfffc1000
	s_addc_u32 s19, s7, -1
	s_cmp_eq_u32 s22, 12
	s_cselect_b32 s24, s5, s18
	s_cselect_b32 s25, s1, s19
	s_cselect_b32 s20, s11, s14
	s_cselect_b32 s21, s10, s15
	s_add_u32 s18, s24, 0x1000
	s_addc_u32 s19, s25, 0
	s_add_i32 s23, 0, 0x10000
	s_add_i32 s42, 0, 0x14000
	v_add_u32_e32 v144, s23, v200
	v_add_u32_e32 v170, s42, v200
	ds_read_b128 v[124:127], v144
	ds_read_b128 v[136:139], v144 offset:1024
	ds_read_b128 v[140:143], v144 offset:2048
	ds_read_b128 v[144:147], v144 offset:3072
	ds_read_b128 v[148:151], v170
	ds_read_b128 v[152:155], v170 offset:1024
	ds_read_b128 v[156:159], v170 offset:2048
	ds_read_b128 v[170:173], v170 offset:3072
	v_lshl_add_u64 v[178:179], s[6:7], 0, v[166:167]
	s_add_i32 m0, s30, 0xc000
	ds_read_b128 v[174:177], v202
	ds_read_b128 v[192:195], v202 offset:1024
	ds_read_b128 v[196:199], v202 offset:2048
	ds_read_b128 v[204:207], v202 offset:3072
	ds_read_b128 v[218:221], v202 offset:4096
	ds_read_b128 v[222:225], v202 offset:5120
	ds_read_b128 v[226:229], v202 offset:6144
	ds_read_b128 v[230:233], v202 offset:7168
	global_load_lds_dwordx4 v[178:179], off
	v_lshl_add_u64 v[178:179], s[6:7], 0, v[168:169]
	s_add_i32 m0, s30, 0xe000
	s_nop 0
	global_load_lds_dwordx4 v[178:179], off
	s_waitcnt vmcnt(8)
	s_waitcnt lgkmcnt(0)
	s_barrier
	s_waitcnt lgkmcnt(0)
	v_mfma_f32_16x16x32_f16 v[132:135], v[124:127], v[174:177], v[132:135]
	v_mfma_f32_16x16x32_f16 v[128:131], v[140:143], v[174:177], v[128:131]
	v_mfma_f32_16x16x32_f16 v[112:115], v[124:127], v[196:199], v[112:115]
	v_mfma_f32_16x16x32_f16 v[108:111], v[140:143], v[196:199], v[108:111]
	v_mfma_f32_16x16x32_f16 v[96:99], v[124:127], v[218:221], v[96:99]
	v_mfma_f32_16x16x32_f16 v[92:95], v[140:143], v[218:221], v[92:95]
	v_mfma_f32_16x16x32_f16 v[80:83], v[124:127], v[226:229], v[80:83]
	v_mfma_f32_16x16x32_f16 v[76:79], v[140:143], v[226:229], v[76:79]
	v_mfma_f32_16x16x32_f16 v[132:135], v[136:139], v[192:195], v[132:135]
	v_mfma_f32_16x16x32_f16 v[128:131], v[144:147], v[192:195], v[128:131]
	v_mfma_f32_16x16x32_f16 v[112:115], v[136:139], v[204:207], v[112:115]
	v_mfma_f32_16x16x32_f16 v[108:111], v[144:147], v[204:207], v[108:111]
	v_mfma_f32_16x16x32_f16 v[96:99], v[136:139], v[222:225], v[96:99]
	v_mfma_f32_16x16x32_f16 v[92:95], v[144:147], v[222:225], v[92:95]
	v_mfma_f32_16x16x32_f16 v[80:83], v[136:139], v[230:233], v[80:83]
	v_mfma_f32_16x16x32_f16 v[76:79], v[144:147], v[230:233], v[76:79]
	v_mfma_f32_16x16x32_f16 v[120:123], v[148:151], v[174:177], v[120:123]
	v_mfma_f32_16x16x32_f16 v[116:119], v[156:159], v[174:177], v[116:119]
	v_mfma_f32_16x16x32_f16 v[104:107], v[148:151], v[196:199], v[104:107]
	v_mfma_f32_16x16x32_f16 v[100:103], v[156:159], v[196:199], v[100:103]
	v_mfma_f32_16x16x32_f16 v[88:91], v[148:151], v[218:221], v[88:91]
	v_mfma_f32_16x16x32_f16 v[84:87], v[156:159], v[218:221], v[84:87]
	v_mfma_f32_16x16x32_f16 v[72:75], v[148:151], v[226:229], v[72:75]
	v_mfma_f32_16x16x32_f16 v[68:71], v[156:159], v[226:229], v[68:71]
	v_mfma_f32_16x16x32_f16 v[120:123], v[152:155], v[192:195], v[120:123]
	v_mfma_f32_16x16x32_f16 v[116:119], v[170:173], v[192:195], v[116:119]
	v_mfma_f32_16x16x32_f16 v[104:107], v[152:155], v[204:207], v[104:107]
	v_mfma_f32_16x16x32_f16 v[100:103], v[170:173], v[204:207], v[100:103]
	v_mfma_f32_16x16x32_f16 v[88:91], v[152:155], v[222:225], v[88:91]
	v_mfma_f32_16x16x32_f16 v[84:87], v[170:173], v[222:225], v[84:87]
	v_mfma_f32_16x16x32_f16 v[72:75], v[152:155], v[230:233], v[72:75]
	v_mfma_f32_16x16x32_f16 v[68:71], v[170:173], v[230:233], v[68:71]
	s_barrier
	s_add_i32 s23, s23, s29
	v_lshl_add_u64 v[178:179], s[20:21], 0, v[2:3]
	s_mov_b32 m0, s23
	ds_read_b128 v[174:177], v202 offset:16384
	ds_read_b128 v[192:195], v202 offset:17408
	ds_read_b128 v[196:199], v202 offset:18432
	ds_read_b128 v[204:207], v202 offset:19456
	ds_read_b128 v[218:221], v202 offset:20480
	ds_read_b128 v[222:225], v202 offset:21504
	ds_read_b128 v[226:229], v202 offset:22528
	ds_read_b128 v[230:233], v202 offset:23552
	global_load_lds_dwordx4 v[178:179], off
	s_add_i32 m0, s23, 0x2000
	s_add_u32 s40, s20, 0x10000
	v_lshl_add_u64 v[208:209], s[20:21], 0, v[160:161]
	s_addc_u32 s41, s21, 0
	s_add_i32 s23, s42, s29
	global_load_lds_dwordx4 v[208:209], off
	v_lshl_add_u64 v[234:235], s[40:41], 0, v[2:3]
	s_mov_b32 m0, s23
	s_nop 0
	global_load_lds_dwordx4 v[234:235], off
	v_lshl_add_u64 v[234:235], s[40:41], 0, v[160:161]
	s_add_i32 m0, s23, 0x2000
	s_nop 0
	global_load_lds_dwordx4 v[234:235], off
	v_lshl_add_u64 v[234:235], s[24:25], 0, v[164:165]
	s_mov_b32 m0, s30
	s_nop 0
	global_load_lds_dwordx4 v[234:235], off
	v_lshl_add_u64 v[234:235], s[24:25], 0, v[162:163]
	s_mov_b32 m0, s31
	s_nop 0
	global_load_lds_dwordx4 v[234:235], off
	s_waitcnt vmcnt(8)
	s_waitcnt lgkmcnt(0)
	s_barrier
; #define PG8_STAGE(bufoff, gbase, voff) do { _Pragma("unroll") for (int _i = 0; _i < 2; ++_i) \
;         __builtin_amdgcn_global_load_lds((const unsigned*)((const char*)(gbase) + (voff)[_i]), (LAS unsigned*)(lds + (bufoff) + ldsw + _i * 8192), 16, 0, 0); } while (0)
; #define PG8_LDA(dst, b, h) do { _Pragma("unroll") for (int m = 0; m < 4; ++m) _Pragma("unroll") for (int k = 0; k < 2; ++k) dst[m][k] = *(const LAS h8*)(lds + PG8_SA(b, h) + aoff + m * 2048 + k * 1024); } while (0)
; #define PG8_LDB(dst, b, h) do { _Pragma("unroll") for (int n = 0; n < 2; ++n) _Pragma("unroll") for (int k = 0; k < 2; ++k) dst[n][k] = *(const LAS h8*)(lds + PG8_SB(b, h) + boff + n * 2048 + k * 1024); } while (0)
; #define PG8_MMA(ai, bj, At, Bt) do { __builtin_amdgcn_s_setprio(1); _Pragma("unroll") for (int m = 0; m < 4; ++m) _Pragma("unroll") for (int n = 0; n < 2; ++n) _Pragma("unroll") for (int k = 0; k < 2; ++k) \
;         acc[ai][bj][m][n] = __builtin_amdgcn_mfma_f32_16x16x32_f16(Bt[n][k], At[m][k], acc[ai][bj][m][n], 0, 0, 0); __builtin_amdgcn_s_setprio(0); } while (0)
; #define PG8_WAIT_V(n) asm volatile("s_waitcnt vmcnt(" #n ")" ::: "memory")
; #define PG8_WAIT_L(n) asm volatile("s_waitcnt lgkmcnt(" #n ")" ::: "memory")
; #define PG8_BAR __builtin_amdgcn_s_barrier()
; #define PG8_SCHED __builtin_amdgcn_sched_barrier(0)
; template <class Epi>
; __device__ __forceinline__ void gemm_phase(LAS unsigned char* lds, const Gemm g, const StaticOrder& S, const Epi& E, unsigned long long& sw_acc) {
;     ...
;             PG8_LDA(At, 0, 1); PG8_STAGE(PG8_SB(0, 0), b2, voffB); PG8_STAGE(PG8_SB(0, 1), b2 + hstepB, voffB); PG8_STAGE(PG8_SA(0, 0), a2, voffA);
;             PG8_WAIT_V(8); PG8_WAIT_L(0); PG8_BAR; PG8_MMA(1, 0, At, B0); PG8_MMA(1, 1, At, B1); PG8_BAR; PG8_SCHED;
;             PG8_LDB(B0, 1, 0); PG8_LDB(B1, 1, 1); PG8_SCHED; PG8_LDA(At, 1, 0); PG8_STAGE(PG8_SA(0, 1), a2 + hstep, voffA);
;             PG8_WAIT_V(8); PG8_WAIT_L(0); PG8_BAR; PG8_MMA(0, 0, At, B0); PG8_MMA(0, 1, At, B1); PG8_BAR; PG8_SCHED;
	s_waitcnt lgkmcnt(0)
	v_mfma_f32_16x16x32_f16 v[64:67], v[124:127], v[174:177], v[64:67]
	v_mfma_f32_16x16x32_f16 v[60:63], v[140:143], v[174:177], v[60:63]
	v_mfma_f32_16x16x32_f16 v[48:51], v[124:127], v[196:199], v[48:51]
	v_mfma_f32_16x16x32_f16 v[44:47], v[140:143], v[196:199], v[44:47]
	v_mfma_f32_16x16x32_f16 v[32:35], v[124:127], v[218:221], v[32:35]
	v_mfma_f32_16x16x32_f16 v[28:31], v[140:143], v[218:221], v[28:31]
	v_mfma_f32_16x16x32_f16 v[16:19], v[124:127], v[226:229], v[16:19]
	v_mfma_f32_16x16x32_f16 v[12:15], v[140:143], v[226:229], v[12:15]
	v_mfma_f32_16x16x32_f16 v[64:67], v[136:139], v[192:195], v[64:67]
	v_mfma_f32_16x16x32_f16 v[60:63], v[144:147], v[192:195], v[60:63]
	v_mfma_f32_16x16x32_f16 v[48:51], v[136:139], v[204:207], v[48:51]
	v_mfma_f32_16x16x32_f16 v[44:47], v[144:147], v[204:207], v[44:47]
	v_mfma_f32_16x16x32_f16 v[32:35], v[136:139], v[222:225], v[32:35]
	v_mfma_f32_16x16x32_f16 v[28:31], v[144:147], v[222:225], v[28:31]
	v_mfma_f32_16x16x32_f16 v[16:19], v[136:139], v[230:233], v[16:19]
	v_mfma_f32_16x16x32_f16 v[12:15], v[144:147], v[230:233], v[12:15]
	v_mfma_f32_16x16x32_f16 v[56:59], v[148:151], v[174:177], v[56:59]
	v_mfma_f32_16x16x32_f16 v[52:55], v[156:159], v[174:177], v[52:55]
	v_mfma_f32_16x16x32_f16 v[40:43], v[148:151], v[196:199], v[40:43]
	v_mfma_f32_16x16x32_f16 v[36:39], v[156:159], v[196:199], v[36:39]
	v_mfma_f32_16x16x32_f16 v[24:27], v[148:151], v[218:221], v[24:27]
	v_mfma_f32_16x16x32_f16 v[20:23], v[156:159], v[218:221], v[20:23]
	v_mfma_f32_16x16x32_f16 v[8:11], v[148:151], v[226:229], v[8:11]
	v_mfma_f32_16x16x32_f16 v[4:7], v[156:159], v[226:229], v[4:7]
	v_mfma_f32_16x16x32_f16 v[56:59], v[152:155], v[192:195], v[56:59]
	v_mfma_f32_16x16x32_f16 v[52:55], v[170:173], v[192:195], v[52:55]
	v_mfma_f32_16x16x32_f16 v[40:43], v[152:155], v[204:207], v[40:43]
	v_mfma_f32_16x16x32_f16 v[36:39], v[170:173], v[204:207], v[36:39]
	v_mfma_f32_16x16x32_f16 v[24:27], v[152:155], v[222:225], v[24:27]
	v_mfma_f32_16x16x32_f16 v[20:23], v[170:173], v[222:225], v[20:23]
	v_mfma_f32_16x16x32_f16 v[8:11], v[152:155], v[230:233], v[8:11]
	v_mfma_f32_16x16x32_f16 v[4:7], v[170:173], v[230:233], v[4:7]
	s_barrier
	s_add_i32 s23, 0, 0x18000
	s_add_i32 s40, 0, 0x1c000
	v_add_u32_e32 v144, s23, v200
	v_add_u32_e32 v170, s40, v200
	ds_read_b128 v[124:127], v144
	ds_read_b128 v[136:139], v144 offset:1024
	ds_read_b128 v[140:143], v144 offset:2048
	ds_read_b128 v[144:147], v144 offset:3072
	ds_read_b128 v[148:151], v170
	ds_read_b128 v[152:155], v170 offset:1024
	ds_read_b128 v[156:159], v170 offset:2048
	ds_read_b128 v[170:173], v170 offset:3072
	s_add_u32 s24, s24, 0x40000
	s_addc_u32 s25, s25, 0
	s_mov_b32 m0, s34
	v_lshl_add_u64 v[234:235], s[24:25], 0, v[164:165]
	ds_read_b128 v[174:177], v202 offset:32768
	ds_read_b128 v[192:195], v202 offset:33792
	ds_read_b128 v[196:199], v202 offset:34816
	ds_read_b128 v[204:207], v202 offset:35840
	ds_read_b128 v[218:221], v202 offset:36864
	ds_read_b128 v[222:225], v202 offset:37888
	ds_read_b128 v[226:229], v202 offset:38912
	ds_read_b128 v[230:233], v202 offset:39936
	global_load_lds_dwordx4 v[234:235], off
	v_lshl_add_u64 v[234:235], s[24:25], 0, v[162:163]
	s_mov_b32 m0, s35
	s_nop 0
	global_load_lds_dwordx4 v[234:235], off
	s_waitcnt vmcnt(8)
	s_waitcnt lgkmcnt(0)
	s_barrier
	s_waitcnt lgkmcnt(0)
	v_mfma_f32_16x16x32_f16 v[132:135], v[124:127], v[174:177], v[132:135]
	v_mfma_f32_16x16x32_f16 v[128:131], v[140:143], v[174:177], v[128:131]
	v_mfma_f32_16x16x32_f16 v[112:115], v[124:127], v[196:199], v[112:115]
	v_mfma_f32_16x16x32_f16 v[108:111], v[140:143], v[196:199], v[108:111]
	v_mfma_f32_16x16x32_f16 v[96:99], v[124:127], v[218:221], v[96:99]
	v_mfma_f32_16x16x32_f16 v[92:95], v[140:143], v[218:221], v[92:95]
	v_mfma_f32_16x16x32_f16 v[80:83], v[124:127], v[226:229], v[80:83]
	v_mfma_f32_16x16x32_f16 v[76:79], v[140:143], v[226:229], v[76:79]
	v_mfma_f32_16x16x32_f16 v[132:135], v[136:139], v[192:195], v[132:135]
	v_mfma_f32_16x16x32_f16 v[128:131], v[144:147], v[192:195], v[128:131]
	v_mfma_f32_16x16x32_f16 v[112:115], v[136:139], v[204:207], v[112:115]
	v_mfma_f32_16x16x32_f16 v[108:111], v[144:147], v[204:207], v[108:111]
	v_mfma_f32_16x16x32_f16 v[96:99], v[136:139], v[222:225], v[96:99]
	v_mfma_f32_16x16x32_f16 v[92:95], v[144:147], v[222:225], v[92:95]
	v_mfma_f32_16x16x32_f16 v[80:83], v[136:139], v[230:233], v[80:83]
	v_mfma_f32_16x16x32_f16 v[76:79], v[144:147], v[230:233], v[76:79]
	v_mfma_f32_16x16x32_f16 v[120:123], v[148:151], v[174:177], v[120:123]
	v_mfma_f32_16x16x32_f16 v[116:119], v[156:159], v[174:177], v[116:119]
	v_mfma_f32_16x16x32_f16 v[104:107], v[148:151], v[196:199], v[104:107]
	v_mfma_f32_16x16x32_f16 v[100:103], v[156:159], v[196:199], v[100:103]
	v_mfma_f32_16x16x32_f16 v[88:91], v[148:151], v[218:221], v[88:91]
	v_mfma_f32_16x16x32_f16 v[84:87], v[156:159], v[218:221], v[84:87]
	v_mfma_f32_16x16x32_f16 v[72:75], v[148:151], v[226:229], v[72:75]
	v_mfma_f32_16x16x32_f16 v[68:71], v[156:159], v[226:229], v[68:71]
	v_mfma_f32_16x16x32_f16 v[120:123], v[152:155], v[192:195], v[120:123]
	v_mfma_f32_16x16x32_f16 v[116:119], v[170:173], v[192:195], v[116:119]
	v_mfma_f32_16x16x32_f16 v[104:107], v[152:155], v[204:207], v[104:107]
	v_mfma_f32_16x16x32_f16 v[100:103], v[170:173], v[204:207], v[100:103]
	v_mfma_f32_16x16x32_f16 v[88:91], v[152:155], v[222:225], v[88:91]
	v_mfma_f32_16x16x32_f16 v[84:87], v[170:173], v[222:225], v[84:87]
	v_mfma_f32_16x16x32_f16 v[72:75], v[152:155], v[230:233], v[72:75]
	v_mfma_f32_16x16x32_f16 v[68:71], v[170:173], v[230:233], v[68:71]
	s_barrier
; #define PG8_STAGE(bufoff, gbase, voff) do { _Pragma("unroll") for (int _i = 0; _i < 2; ++_i) \
;         __builtin_amdgcn_global_load_lds((const unsigned*)((const char*)(gbase) + (voff)[_i]), (LAS unsigned*)(lds + (bufoff) + ldsw + _i * 8192), 16, 0, 0); } while (0)
; #define PG8_LDA(dst, b, h) do { _Pragma("unroll") for (int m = 0; m < 4; ++m) _Pragma("unroll") for (int k = 0; k < 2; ++k) dst[m][k] = *(const LAS h8*)(lds + PG8_SA(b, h) + aoff + m * 2048 + k * 1024); } while (0)
; #define PG8_MMA(ai, bj, At, Bt) do { __builtin_amdgcn_s_setprio(1); _Pragma("unroll") for (int m = 0; m < 4; ++m) _Pragma("unroll") for (int n = 0; n < 2; ++n) _Pragma("unroll") for (int k = 0; k < 2; ++k) \
;         acc[ai][bj][m][n] = __builtin_amdgcn_mfma_f32_16x16x32_f16(Bt[n][k], At[m][k], acc[ai][bj][m][n], 0, 0, 0); __builtin_amdgcn_s_setprio(0); } while (0)
; #define PG8_WAIT_V(n) asm volatile("s_waitcnt vmcnt(" #n ")" ::: "memory")
; #define PG8_WAIT_L(n) asm volatile("s_waitcnt lgkmcnt(" #n ")" ::: "memory")
; #define PG8_BAR __builtin_amdgcn_s_barrier()
; #define PG8_SCHED __builtin_amdgcn_sched_barrier(0)
; template <class Epi>
; __device__ __forceinline__ void gemm_phase(LAS unsigned char* lds, const Gemm g, const StaticOrder& S, const Epi& E, unsigned long long& sw_acc) {
;     ...
;             PG8_LDA(At, 1, 1); PG8_STAGE(PG8_SB(1, 0), b3, voffB); PG8_STAGE(PG8_SB(1, 1), b3 + hstepB, voffB); PG8_STAGE(PG8_SA(1, 0), a3, voffA);
;             PG8_WAIT_V(8); PG8_WAIT_L(0); PG8_BAR; PG8_MMA(1, 0, At, B0); PG8_MMA(1, 1, At, B1); PG8_BAR; PG8_SCHED;
;         }
	s_add_i32 s23, s23, s29
	v_lshl_add_u64 v[178:179], v[178:179], 0, s[16:17]
	s_mov_b32 m0, s23
	ds_read_b128 v[174:177], v202 offset:49152
	ds_read_b128 v[192:195], v202 offset:50176
	ds_read_b128 v[196:199], v202 offset:51200
	ds_read_b128 v[204:207], v202 offset:52224
	ds_read_b128 v[218:221], v202 offset:53248
	ds_read_b128 v[222:225], v202 offset:54272
	ds_read_b128 v[226:229], v202 offset:55296
	ds_read_b128 v[230:233], v202 offset:56320
	global_load_lds_dwordx4 v[178:179], off
	s_add_i32 m0, s23, 0x2000
	s_add_u32 s20, s20, 0x10080
	v_lshl_add_u64 v[178:179], v[208:209], 0, s[16:17]
	s_addc_u32 s21, s21, 0
	s_add_i32 s23, s40, s29
	global_load_lds_dwordx4 v[178:179], off
	v_lshl_add_u64 v[178:179], s[20:21], 0, v[2:3]
	s_mov_b32 m0, s23
	s_nop 0
	global_load_lds_dwordx4 v[178:179], off
	v_lshl_add_u64 v[178:179], s[20:21], 0, v[160:161]
	s_add_i32 m0, s23, 0x2000
	s_nop 0
	global_load_lds_dwordx4 v[178:179], off
	v_lshl_add_u64 v[178:179], s[18:19], 0, v[164:165]
	s_mov_b32 m0, s37
	s_nop 0
	global_load_lds_dwordx4 v[178:179], off
	v_lshl_add_u64 v[178:179], s[18:19], 0, v[162:163]
	s_mov_b32 m0, s60
	s_nop 0
	global_load_lds_dwordx4 v[178:179], off
	s_waitcnt vmcnt(8)
	s_waitcnt lgkmcnt(0)
	s_barrier
	s_waitcnt lgkmcnt(0)
	v_mfma_f32_16x16x32_f16 v[64:67], v[124:127], v[174:177], v[64:67]
	v_mfma_f32_16x16x32_f16 v[60:63], v[140:143], v[174:177], v[60:63]
	v_mfma_f32_16x16x32_f16 v[48:51], v[124:127], v[196:199], v[48:51]
	v_mfma_f32_16x16x32_f16 v[44:47], v[140:143], v[196:199], v[44:47]
	v_mfma_f32_16x16x32_f16 v[32:35], v[124:127], v[218:221], v[32:35]
	v_mfma_f32_16x16x32_f16 v[28:31], v[140:143], v[218:221], v[28:31]
	v_mfma_f32_16x16x32_f16 v[16:19], v[124:127], v[226:229], v[16:19]
	v_mfma_f32_16x16x32_f16 v[12:15], v[140:143], v[226:229], v[12:15]
	v_mfma_f32_16x16x32_f16 v[64:67], v[136:139], v[192:195], v[64:67]
	v_mfma_f32_16x16x32_f16 v[60:63], v[144:147], v[192:195], v[60:63]
	v_mfma_f32_16x16x32_f16 v[48:51], v[136:139], v[204:207], v[48:51]
	v_mfma_f32_16x16x32_f16 v[44:47], v[144:147], v[204:207], v[44:47]
	v_mfma_f32_16x16x32_f16 v[32:35], v[136:139], v[222:225], v[32:35]
	v_mfma_f32_16x16x32_f16 v[28:31], v[144:147], v[222:225], v[28:31]
	v_mfma_f32_16x16x32_f16 v[16:19], v[136:139], v[230:233], v[16:19]
	v_mfma_f32_16x16x32_f16 v[12:15], v[144:147], v[230:233], v[12:15]
	v_mfma_f32_16x16x32_f16 v[56:59], v[148:151], v[174:177], v[56:59]
	v_mfma_f32_16x16x32_f16 v[52:55], v[156:159], v[174:177], v[52:55]
	v_mfma_f32_16x16x32_f16 v[40:43], v[148:151], v[196:199], v[40:43]
	v_mfma_f32_16x16x32_f16 v[36:39], v[156:159], v[196:199], v[36:39]
	v_mfma_f32_16x16x32_f16 v[24:27], v[148:151], v[218:221], v[24:27]
	v_mfma_f32_16x16x32_f16 v[20:23], v[156:159], v[218:221], v[20:23]
	v_mfma_f32_16x16x32_f16 v[8:11], v[148:151], v[226:229], v[8:11]
	v_mfma_f32_16x16x32_f16 v[4:7], v[156:159], v[226:229], v[4:7]
	v_mfma_f32_16x16x32_f16 v[56:59], v[152:155], v[192:195], v[56:59]
	v_mfma_f32_16x16x32_f16 v[52:55], v[170:173], v[192:195], v[52:55]
	v_mfma_f32_16x16x32_f16 v[40:43], v[152:155], v[204:207], v[40:43]
	v_mfma_f32_16x16x32_f16 v[36:39], v[170:173], v[204:207], v[36:39]
	v_mfma_f32_16x16x32_f16 v[24:27], v[152:155], v[222:225], v[24:27]
	v_mfma_f32_16x16x32_f16 v[20:23], v[170:173], v[222:225], v[20:23]
	v_mfma_f32_16x16x32_f16 v[8:11], v[152:155], v[230:233], v[8:11]
	v_mfma_f32_16x16x32_f16 v[4:7], v[170:173], v[230:233], v[4:7]
	s_barrier
	s_add_i32 s22, s22, 2
	s_add_u32 s14, s14, 0x100
	s_addc_u32 s15, s15, 0
	s_add_u32 s6, s6, 0x2000
	s_addc_u32 s7, s7, 0
	s_cmp_gt_u32 s22, 13
	s_cbranch_scc0 .LBB0_700
	s_and_b64 vcc, exec, s[46:47]
	s_cbranch_vccz .LBB0_703
	s_barrier

; __global__ void __launch_bounds__(NWAVES * 64, 2) hybrid_fwd(Args args) {
	.amdhsa_kernel _Z10hybrid_fwd4Args
		.amdhsa_group_segment_fixed_size 0
		.amdhsa_private_segment_fixed_size 0
		.amdhsa_kernarg_size 360
		.amdhsa_user_sgpr_count 2
		.amdhsa_user_sgpr_dispatch_ptr 0
		.amdhsa_user_sgpr_queue_ptr 0
		.amdhsa_user_sgpr_kernarg_segment_ptr 1
		.amdhsa_user_sgpr_dispatch_id 0
		.amdhsa_user_sgpr_kernarg_preload_length 0
		.amdhsa_user_sgpr_kernarg_preload_offset 0
		.amdhsa_user_sgpr_private_segment_size 0
		.amdhsa_uses_dynamic_stack 0
		.amdhsa_enable_private_segment 0
		.amdhsa_system_sgpr_workgroup_id_x 1
		.amdhsa_system_sgpr_workgroup_id_y 0
		.amdhsa_system_sgpr_workgroup_id_z 0
		.amdhsa_system_sgpr_workgroup_info 0
		.amdhsa_system_vgpr_workitem_id 0
		.amdhsa_next_free_vgpr 256
		.amdhsa_next_free_sgpr 100
		.amdhsa_accum_offset 256
		.amdhsa_reserve_vcc 1
		.amdhsa_float_round_mode_32 0
		.amdhsa_float_round_mode_16_64 0
		.amdhsa_float_denorm_mode_32 3
		.amdhsa_float_denorm_mode_16_64 3
		.amdhsa_dx10_clamp 1
		.amdhsa_ieee_mode 1
		.amdhsa_fp16_overflow 0
		.amdhsa_tg_split 0
		.amdhsa_exception_fp_ieee_invalid_op 0
		.amdhsa_exception_fp_denorm_src 0
		.amdhsa_exception_fp_ieee_div_zero 0
		.amdhsa_exception_fp_ieee_overflow 0
		.amdhsa_exception_fp_ieee_underflow 0
		.amdhsa_exception_fp_ieee_inexact 0
		.amdhsa_exception_int_div_zero 0
	.end_amdhsa_kernel

; __global__ void __launch_bounds__(NWAVES * 64, 2) hybrid_fwd(Args args) {
amdhsa.kernels:
  - .agpr_count:     0
    .args:
      - .offset:         0
        .size:           104
        .value_kind:     by_value
      - .offset:         104
        .size:           4
        .value_kind:     hidden_block_count_x
      - .offset:         108
        .size:           4
        .value_kind:     hidden_block_count_y
      - .offset:         112
        .size:           4
        .value_kind:     hidden_block_count_z
      - .offset:         116
        .size:           2
        .value_kind:     hidden_group_size_x
      - .offset:         118
        .size:           2
        .value_kind:     hidden_group_size_y
      - .offset:         120
        .size:           2
        .value_kind:     hidden_group_size_z
      - .offset:         122
        .size:           2
        .value_kind:     hidden_remainder_x
      - .offset:         124
        .size:           2
        .value_kind:     hidden_remainder_y
      - .offset:         126
        .size:           2
        .value_kind:     hidden_remainder_z
      - .offset:         144
        .size:           8
        .value_kind:     hidden_global_offset_x
      - .offset:         152
        .size:           8
        .value_kind:     hidden_global_offset_y
      - .offset:         160
        .size:           8
        .value_kind:     hidden_global_offset_z
      - .offset:         168
        .size:           2
        .value_kind:     hidden_grid_dims
      - .offset:         224
        .size:           4
        .value_kind:     hidden_dynamic_lds_size
    .group_segment_fixed_size: 0
    .kernarg_segment_align: 8
    .kernarg_segment_size: 360
    .language:       OpenCL C
    .language_version:
      - 2
      - 0
    .max_flat_workgroup_size: 512
    .name:           _Z10hybrid_fwd4Args
    .private_segment_fixed_size: 0
    .sgpr_count:     106
    .sgpr_spill_count: 153
    .symbol:         _Z10hybrid_fwd4Args.kd
    .uniform_work_group_size: 1
    .uses_dynamic_stack: false
    .vgpr_count:     256
    .vgpr_spill_count: 0
    .wavefront_size: 64
